# rowpass ctx slab loads de-serialized; conv DN loads batched; recurrence waits merged and 16-step unroll (branch trampolines)
# speedup vs baseline: 1.0140x; 1.0065x over previous
.Lrec_entry:
	s_and_b32 s100, s99, 1
	s_mul_i32 s101, s100, 0xc100
	s_lshl_b32 s100, s100, 13
	v_and_b32_e32 v92, 7, v119
	v_and_b32_e32 v93, -8, v119
	v_lshlrev_b32_e32 v92, 5, v92
	s_add_i32 s101, s101, 16
	s_add_i32 s100, s100, 0x18a10
	s_and_b64 vcc, exec, s[62:63]
	s_cbranch_vccz .Lrec_bwd
	s_mov_b32 s48, s101
	s_mov_b32 s49, s101
	v_add_u32_e32 v88, s48, v92
	v_add_u32_e32 v89, s48, v93
	v_mov_b32_e32 v90, s49
	v_add_u32_e32 v91, s100, v93
	ds_read_b128 v[18:21], v88 offset:18432
	ds_read_b128 v[22:25], v88 offset:18448
	ds_read_b128 v[26:29], v88 offset:34816
	ds_read_b128 v[30:33], v88 offset:34832
	ds_read_b128 v[34:37], v88 offset:2048
	ds_read_b128 v[38:41], v88 offset:2064
	ds_read_b128 v[42:45], v88 offset:10240
	ds_read_b128 v[46:49], v88 offset:10256
	ds_read_b128 v[50:53], v88 offset:26624
	ds_read_b128 v[54:57], v88 offset:26640
	ds_read_b64 v[58:59], v89 offset:43008
	ds_read_b64 v[60:61], v90 offset:51200
	s_movk_i32 s48, 4096
	s_movk_i32 s49, 128
	s_movk_i32 s100, 2
.Lrec_fwd_loop:
	s_waitcnt lgkmcnt(6)
	v_pk_mul_f32 v[62:63], v[2:3], v[18:19] op_sel_hi:[1,0]
	v_pk_mul_f32 v[64:65], v[4:5], v[18:19] op_sel:[0,1]
	v_pk_mul_f32 v[66:67], v[2:3], v[26:27] op_sel_hi:[1,0]
	v_pk_mul_f32 v[68:69], v[4:5], v[26:27] op_sel:[0,1]
	v_pk_fma_f32 v[62:63], v[6:7], v[20:21], v[62:63] op_sel_hi:[1,0,1]
	v_pk_fma_f32 v[66:67], v[6:7], v[28:29], v[66:67] op_sel_hi:[1,0,1]
	v_pk_fma_f32 v[64:65], v[8:9], v[20:21], v[64:65] op_sel:[0,1,0]
	v_pk_fma_f32 v[68:69], v[8:9], v[28:29], v[68:69] op_sel:[0,1,0]
	v_pk_fma_f32 v[62:63], v[10:11], v[22:23], v[62:63] op_sel_hi:[1,0,1]
	v_pk_fma_f32 v[66:67], v[10:11], v[30:31], v[66:67] op_sel_hi:[1,0,1]
	v_pk_fma_f32 v[64:65], v[12:13], v[22:23], v[64:65] op_sel:[0,1,0]
	v_pk_fma_f32 v[68:69], v[12:13], v[30:31], v[68:69] op_sel:[0,1,0]
	v_pk_fma_f32 v[62:63], v[14:15], v[24:25], v[62:63] op_sel_hi:[1,0,1]
	v_pk_fma_f32 v[66:67], v[14:15], v[32:33], v[66:67] op_sel_hi:[1,0,1]
	v_pk_fma_f32 v[64:65], v[16:17], v[24:25], v[64:65] op_sel:[0,1,0]
	v_pk_fma_f32 v[68:69], v[16:17], v[32:33], v[68:69] op_sel:[0,1,0]
	ds_read_b128 v[18:21], v88 offset:18688
	ds_read_b128 v[22:25], v88 offset:18704
	ds_read_b128 v[26:29], v88 offset:35072
	ds_read_b128 v[30:33], v88 offset:35088
	v_pk_add_f32 v[62:63], v[62:63], v[64:65]
	v_pk_add_f32 v[66:67], v[66:67], v[68:69]
	v_pk_mul_f32 v[70:71], v[2:3], v[34:35] op_sel_hi:[1,0]
	v_pk_mul_f32 v[72:73], v[4:5], v[34:35] op_sel:[0,1]
	v_pk_mul_f32 v[74:75], v[6:7], v[36:37] op_sel_hi:[1,0]
	v_pk_mul_f32 v[76:77], v[8:9], v[36:37] op_sel:[0,1]
	v_pk_mul_f32 v[78:79], v[10:11], v[38:39] op_sel_hi:[1,0]
	v_pk_mul_f32 v[80:81], v[12:13], v[38:39] op_sel:[0,1]
	v_pk_mul_f32 v[82:83], v[14:15], v[40:41] op_sel_hi:[1,0]
	v_pk_mul_f32 v[84:85], v[16:17], v[40:41] op_sel:[0,1]
	ds_read_b128 v[34:37], v88 offset:2304
	ds_read_b128 v[38:41], v88 offset:2320
	v_add_f32_dpp v62, v62, v62 quad_perm:[1,0,3,2] row_mask:0xf bank_mask:0xf bound_ctrl:1
	v_add_f32_dpp v63, v63, v63 quad_perm:[1,0,3,2] row_mask:0xf bank_mask:0xf bound_ctrl:1
	v_add_f32_dpp v66, v66, v66 quad_perm:[1,0,3,2] row_mask:0xf bank_mask:0xf bound_ctrl:1
	v_add_f32_dpp v67, v67, v67 quad_perm:[1,0,3,2] row_mask:0xf bank_mask:0xf bound_ctrl:1
	s_waitcnt lgkmcnt(6)
	v_pk_fma_f32 v[70:71], v[58:59], v[42:43], v[70:71] op_sel_hi:[1,0,1]
	v_pk_fma_f32 v[72:73], v[58:59], v[42:43], v[72:73] op_sel:[0,1,0]
	v_pk_fma_f32 v[74:75], v[58:59], v[44:45], v[74:75] op_sel_hi:[1,0,1]
	v_pk_fma_f32 v[76:77], v[58:59], v[44:45], v[76:77] op_sel:[0,1,0]
	v_add_f32_dpp v62, v62, v62 quad_perm:[2,3,0,1] row_mask:0xf bank_mask:0xf bound_ctrl:1
	v_add_f32_dpp v63, v63, v63 quad_perm:[2,3,0,1] row_mask:0xf bank_mask:0xf bound_ctrl:1
	v_add_f32_dpp v66, v66, v66 quad_perm:[2,3,0,1] row_mask:0xf bank_mask:0xf bound_ctrl:1
	v_add_f32_dpp v67, v67, v67 quad_perm:[2,3,0,1] row_mask:0xf bank_mask:0xf bound_ctrl:1
	v_pk_fma_f32 v[78:79], v[58:59], v[46:47], v[78:79] op_sel_hi:[1,0,1]
	v_pk_fma_f32 v[80:81], v[58:59], v[46:47], v[80:81] op_sel:[0,1,0]
	v_pk_fma_f32 v[82:83], v[58:59], v[48:49], v[82:83] op_sel_hi:[1,0,1]
	v_pk_fma_f32 v[84:85], v[58:59], v[48:49], v[84:85] op_sel:[0,1,0]
	ds_read_b128 v[42:45], v88 offset:10496
	ds_read_b128 v[46:49], v88 offset:10512
	v_add_f32_dpp v62, v62, v62 row_half_mirror row_mask:0xf bank_mask:0xf bound_ctrl:1
	v_add_f32_dpp v63, v63, v63 row_half_mirror row_mask:0xf bank_mask:0xf bound_ctrl:1
	v_add_f32_dpp v66, v66, v66 row_half_mirror row_mask:0xf bank_mask:0xf bound_ctrl:1
	v_add_f32_dpp v67, v67, v67 row_half_mirror row_mask:0xf bank_mask:0xf bound_ctrl:1
	v_pk_fma_f32 v[2:3], v[62:63], v[50:51], v[70:71] op_sel_hi:[1,0,1]
	v_pk_fma_f32 v[4:5], v[62:63], v[50:51], v[72:73] op_sel:[0,1,0]
	v_pk_fma_f32 v[6:7], v[62:63], v[52:53], v[74:75] op_sel_hi:[1,0,1]
	v_pk_fma_f32 v[8:9], v[62:63], v[52:53], v[76:77] op_sel:[0,1,0]
	v_pk_fma_f32 v[10:11], v[62:63], v[54:55], v[78:79] op_sel_hi:[1,0,1]
	v_pk_fma_f32 v[12:13], v[62:63], v[54:55], v[80:81] op_sel:[0,1,0]
	v_pk_fma_f32 v[14:15], v[62:63], v[56:57], v[82:83] op_sel_hi:[1,0,1]
	v_pk_fma_f32 v[16:17], v[62:63], v[56:57], v[84:85] op_sel:[0,1,0]
	ds_read_b128 v[50:53], v88 offset:26880
	ds_read_b128 v[54:57], v88 offset:26896
	v_pk_fma_f32 v[86:87], v[58:59], v[60:61], v[66:67] op_sel:[0,1,0]
	v_pk_fma_f32 v[86:87], v[62:63], v[60:61], v[86:87] op_sel_hi:[1,0,1]
	ds_read_b64 v[58:59], v89 offset:43264
	ds_read_b64 v[60:61], v90 offset:51208
	ds_write_b64 v91, v[86:87] offset:0
	s_waitcnt lgkmcnt(7)
	v_pk_mul_f32 v[62:63], v[2:3], v[18:19] op_sel_hi:[1,0]
	v_pk_mul_f32 v[64:65], v[4:5], v[18:19] op_sel:[0,1]
	v_pk_mul_f32 v[66:67], v[2:3], v[26:27] op_sel_hi:[1,0]
	v_pk_mul_f32 v[68:69], v[4:5], v[26:27] op_sel:[0,1]
	v_pk_fma_f32 v[62:63], v[6:7], v[20:21], v[62:63] op_sel_hi:[1,0,1]
	v_pk_fma_f32 v[66:67], v[6:7], v[28:29], v[66:67] op_sel_hi:[1,0,1]
	v_pk_fma_f32 v[64:65], v[8:9], v[20:21], v[64:65] op_sel:[0,1,0]
	v_pk_fma_f32 v[68:69], v[8:9], v[28:29], v[68:69] op_sel:[0,1,0]
	v_pk_fma_f32 v[62:63], v[10:11], v[22:23], v[62:63] op_sel_hi:[1,0,1]
	v_pk_fma_f32 v[66:67], v[10:11], v[30:31], v[66:67] op_sel_hi:[1,0,1]
	v_pk_fma_f32 v[64:65], v[12:13], v[22:23], v[64:65] op_sel:[0,1,0]
	v_pk_fma_f32 v[68:69], v[12:13], v[30:31], v[68:69] op_sel:[0,1,0]
	v_pk_fma_f32 v[62:63], v[14:15], v[24:25], v[62:63] op_sel_hi:[1,0,1]
	v_pk_fma_f32 v[66:67], v[14:15], v[32:33], v[66:67] op_sel_hi:[1,0,1]
	v_pk_fma_f32 v[64:65], v[16:17], v[24:25], v[64:65] op_sel:[0,1,0]
	v_pk_fma_f32 v[68:69], v[16:17], v[32:33], v[68:69] op_sel:[0,1,0]
	ds_read_b128 v[18:21], v88 offset:18944
	ds_read_b128 v[22:25], v88 offset:18960
	ds_read_b128 v[26:29], v88 offset:35328
	ds_read_b128 v[30:33], v88 offset:35344
	v_pk_add_f32 v[62:63], v[62:63], v[64:65]
	v_pk_add_f32 v[66:67], v[66:67], v[68:69]
	v_pk_mul_f32 v[70:71], v[2:3], v[34:35] op_sel_hi:[1,0]
	v_pk_mul_f32 v[72:73], v[4:5], v[34:35] op_sel:[0,1]
	v_pk_mul_f32 v[74:75], v[6:7], v[36:37] op_sel_hi:[1,0]
	v_pk_mul_f32 v[76:77], v[8:9], v[36:37] op_sel:[0,1]
	v_pk_mul_f32 v[78:79], v[10:11], v[38:39] op_sel_hi:[1,0]
	v_pk_mul_f32 v[80:81], v[12:13], v[38:39] op_sel:[0,1]
	v_pk_mul_f32 v[82:83], v[14:15], v[40:41] op_sel_hi:[1,0]
	v_pk_mul_f32 v[84:85], v[16:17], v[40:41] op_sel:[0,1]
	ds_read_b128 v[34:37], v88 offset:2560
	ds_read_b128 v[38:41], v88 offset:2576
	v_add_f32_dpp v62, v62, v62 quad_perm:[1,0,3,2] row_mask:0xf bank_mask:0xf bound_ctrl:1
	v_add_f32_dpp v63, v63, v63 quad_perm:[1,0,3,2] row_mask:0xf bank_mask:0xf bound_ctrl:1
	v_add_f32_dpp v66, v66, v66 quad_perm:[1,0,3,2] row_mask:0xf bank_mask:0xf bound_ctrl:1
	v_add_f32_dpp v67, v67, v67 quad_perm:[1,0,3,2] row_mask:0xf bank_mask:0xf bound_ctrl:1
	s_waitcnt lgkmcnt(7)
	v_pk_fma_f32 v[70:71], v[58:59], v[42:43], v[70:71] op_sel_hi:[1,0,1]
	v_pk_fma_f32 v[72:73], v[58:59], v[42:43], v[72:73] op_sel:[0,1,0]
	v_pk_fma_f32 v[74:75], v[58:59], v[44:45], v[74:75] op_sel_hi:[1,0,1]
	v_pk_fma_f32 v[76:77], v[58:59], v[44:45], v[76:77] op_sel:[0,1,0]
	v_add_f32_dpp v62, v62, v62 quad_perm:[2,3,0,1] row_mask:0xf bank_mask:0xf bound_ctrl:1
	v_add_f32_dpp v63, v63, v63 quad_perm:[2,3,0,1] row_mask:0xf bank_mask:0xf bound_ctrl:1
	v_add_f32_dpp v66, v66, v66 quad_perm:[2,3,0,1] row_mask:0xf bank_mask:0xf bound_ctrl:1
	v_add_f32_dpp v67, v67, v67 quad_perm:[2,3,0,1] row_mask:0xf bank_mask:0xf bound_ctrl:1
	v_pk_fma_f32 v[78:79], v[58:59], v[46:47], v[78:79] op_sel_hi:[1,0,1]
	v_pk_fma_f32 v[80:81], v[58:59], v[46:47], v[80:81] op_sel:[0,1,0]
	v_pk_fma_f32 v[82:83], v[58:59], v[48:49], v[82:83] op_sel_hi:[1,0,1]
	v_pk_fma_f32 v[84:85], v[58:59], v[48:49], v[84:85] op_sel:[0,1,0]
	ds_read_b128 v[42:45], v88 offset:10752
	ds_read_b128 v[46:49], v88 offset:10768
	v_add_f32_dpp v62, v62, v62 row_half_mirror row_mask:0xf bank_mask:0xf bound_ctrl:1
	v_add_f32_dpp v63, v63, v63 row_half_mirror row_mask:0xf bank_mask:0xf bound_ctrl:1
	v_add_f32_dpp v66, v66, v66 row_half_mirror row_mask:0xf bank_mask:0xf bound_ctrl:1
	v_add_f32_dpp v67, v67, v67 row_half_mirror row_mask:0xf bank_mask:0xf bound_ctrl:1
	v_pk_fma_f32 v[2:3], v[62:63], v[50:51], v[70:71] op_sel_hi:[1,0,1]
	v_pk_fma_f32 v[4:5], v[62:63], v[50:51], v[72:73] op_sel:[0,1,0]
	v_pk_fma_f32 v[6:7], v[62:63], v[52:53], v[74:75] op_sel_hi:[1,0,1]
	v_pk_fma_f32 v[8:9], v[62:63], v[52:53], v[76:77] op_sel:[0,1,0]
	v_pk_fma_f32 v[10:11], v[62:63], v[54:55], v[78:79] op_sel_hi:[1,0,1]
	v_pk_fma_f32 v[12:13], v[62:63], v[54:55], v[80:81] op_sel:[0,1,0]
	v_pk_fma_f32 v[14:15], v[62:63], v[56:57], v[82:83] op_sel_hi:[1,0,1]
	v_pk_fma_f32 v[16:17], v[62:63], v[56:57], v[84:85] op_sel:[0,1,0]
	ds_read_b128 v[50:53], v88 offset:27136
	ds_read_b128 v[54:57], v88 offset:27152
	v_pk_fma_f32 v[86:87], v[58:59], v[60:61], v[66:67] op_sel:[0,1,0]
	v_pk_fma_f32 v[86:87], v[62:63], v[60:61], v[86:87] op_sel_hi:[1,0,1]
	ds_read_b64 v[58:59], v89 offset:43520
	ds_read_b64 v[60:61], v90 offset:51216
	ds_write_b64 v91, v[86:87] offset:256
	s_waitcnt lgkmcnt(7)
	v_pk_mul_f32 v[62:63], v[2:3], v[18:19] op_sel_hi:[1,0]
	v_pk_mul_f32 v[64:65], v[4:5], v[18:19] op_sel:[0,1]
	v_pk_mul_f32 v[66:67], v[2:3], v[26:27] op_sel_hi:[1,0]
	v_pk_mul_f32 v[68:69], v[4:5], v[26:27] op_sel:[0,1]
	v_pk_fma_f32 v[62:63], v[6:7], v[20:21], v[62:63] op_sel_hi:[1,0,1]
	v_pk_fma_f32 v[66:67], v[6:7], v[28:29], v[66:67] op_sel_hi:[1,0,1]
	v_pk_fma_f32 v[64:65], v[8:9], v[20:21], v[64:65] op_sel:[0,1,0]
	v_pk_fma_f32 v[68:69], v[8:9], v[28:29], v[68:69] op_sel:[0,1,0]
	v_pk_fma_f32 v[62:63], v[10:11], v[22:23], v[62:63] op_sel_hi:[1,0,1]
	v_pk_fma_f32 v[66:67], v[10:11], v[30:31], v[66:67] op_sel_hi:[1,0,1]
	v_pk_fma_f32 v[64:65], v[12:13], v[22:23], v[64:65] op_sel:[0,1,0]
	v_pk_fma_f32 v[68:69], v[12:13], v[30:31], v[68:69] op_sel:[0,1,0]
	v_pk_fma_f32 v[62:63], v[14:15], v[24:25], v[62:63] op_sel_hi:[1,0,1]
	v_pk_fma_f32 v[66:67], v[14:15], v[32:33], v[66:67] op_sel_hi:[1,0,1]
	v_pk_fma_f32 v[64:65], v[16:17], v[24:25], v[64:65] op_sel:[0,1,0]
	v_pk_fma_f32 v[68:69], v[16:17], v[32:33], v[68:69] op_sel:[0,1,0]
	ds_read_b128 v[18:21], v88 offset:19200
	ds_read_b128 v[22:25], v88 offset:19216
	ds_read_b128 v[26:29], v88 offset:35584
	ds_read_b128 v[30:33], v88 offset:35600
	v_pk_add_f32 v[62:63], v[62:63], v[64:65]
	v_pk_add_f32 v[66:67], v[66:67], v[68:69]
	v_pk_mul_f32 v[70:71], v[2:3], v[34:35] op_sel_hi:[1,0]
	v_pk_mul_f32 v[72:73], v[4:5], v[34:35] op_sel:[0,1]
	v_pk_mul_f32 v[74:75], v[6:7], v[36:37] op_sel_hi:[1,0]
	v_pk_mul_f32 v[76:77], v[8:9], v[36:37] op_sel:[0,1]
	v_pk_mul_f32 v[78:79], v[10:11], v[38:39] op_sel_hi:[1,0]
	v_pk_mul_f32 v[80:81], v[12:13], v[38:39] op_sel:[0,1]
	v_pk_mul_f32 v[82:83], v[14:15], v[40:41] op_sel_hi:[1,0]
	v_pk_mul_f32 v[84:85], v[16:17], v[40:41] op_sel:[0,1]
	ds_read_b128 v[34:37], v88 offset:2816
	ds_read_b128 v[38:41], v88 offset:2832
	v_add_f32_dpp v62, v62, v62 quad_perm:[1,0,3,2] row_mask:0xf bank_mask:0xf bound_ctrl:1
	v_add_f32_dpp v63, v63, v63 quad_perm:[1,0,3,2] row_mask:0xf bank_mask:0xf bound_ctrl:1
	v_add_f32_dpp v66, v66, v66 quad_perm:[1,0,3,2] row_mask:0xf bank_mask:0xf bound_ctrl:1
	v_add_f32_dpp v67, v67, v67 quad_perm:[1,0,3,2] row_mask:0xf bank_mask:0xf bound_ctrl:1
	s_waitcnt lgkmcnt(7)
	v_pk_fma_f32 v[70:71], v[58:59], v[42:43], v[70:71] op_sel_hi:[1,0,1]
	v_pk_fma_f32 v[72:73], v[58:59], v[42:43], v[72:73] op_sel:[0,1,0]
	v_pk_fma_f32 v[74:75], v[58:59], v[44:45], v[74:75] op_sel_hi:[1,0,1]
	v_pk_fma_f32 v[76:77], v[58:59], v[44:45], v[76:77] op_sel:[0,1,0]
	v_add_f32_dpp v62, v62, v62 quad_perm:[2,3,0,1] row_mask:0xf bank_mask:0xf bound_ctrl:1
	v_add_f32_dpp v63, v63, v63 quad_perm:[2,3,0,1] row_mask:0xf bank_mask:0xf bound_ctrl:1
	v_add_f32_dpp v66, v66, v66 quad_perm:[2,3,0,1] row_mask:0xf bank_mask:0xf bound_ctrl:1
	v_add_f32_dpp v67, v67, v67 quad_perm:[2,3,0,1] row_mask:0xf bank_mask:0xf bound_ctrl:1
	v_pk_fma_f32 v[78:79], v[58:59], v[46:47], v[78:79] op_sel_hi:[1,0,1]
	v_pk_fma_f32 v[80:81], v[58:59], v[46:47], v[80:81] op_sel:[0,1,0]
	v_pk_fma_f32 v[82:83], v[58:59], v[48:49], v[82:83] op_sel_hi:[1,0,1]
	v_pk_fma_f32 v[84:85], v[58:59], v[48:49], v[84:85] op_sel:[0,1,0]
	ds_read_b128 v[42:45], v88 offset:11008
	ds_read_b128 v[46:49], v88 offset:11024
	v_add_f32_dpp v62, v62, v62 row_half_mirror row_mask:0xf bank_mask:0xf bound_ctrl:1
	v_add_f32_dpp v63, v63, v63 row_half_mirror row_mask:0xf bank_mask:0xf bound_ctrl:1
	v_add_f32_dpp v66, v66, v66 row_half_mirror row_mask:0xf bank_mask:0xf bound_ctrl:1
	v_add_f32_dpp v67, v67, v67 row_half_mirror row_mask:0xf bank_mask:0xf bound_ctrl:1
	v_pk_fma_f32 v[2:3], v[62:63], v[50:51], v[70:71] op_sel_hi:[1,0,1]
	v_pk_fma_f32 v[4:5], v[62:63], v[50:51], v[72:73] op_sel:[0,1,0]
	v_pk_fma_f32 v[6:7], v[62:63], v[52:53], v[74:75] op_sel_hi:[1,0,1]
	v_pk_fma_f32 v[8:9], v[62:63], v[52:53], v[76:77] op_sel:[0,1,0]
	v_pk_fma_f32 v[10:11], v[62:63], v[54:55], v[78:79] op_sel_hi:[1,0,1]
	v_pk_fma_f32 v[12:13], v[62:63], v[54:55], v[80:81] op_sel:[0,1,0]
	v_pk_fma_f32 v[14:15], v[62:63], v[56:57], v[82:83] op_sel_hi:[1,0,1]
	v_pk_fma_f32 v[16:17], v[62:63], v[56:57], v[84:85] op_sel:[0,1,0]
	ds_read_b128 v[50:53], v88 offset:27392
	ds_read_b128 v[54:57], v88 offset:27408
	v_pk_fma_f32 v[86:87], v[58:59], v[60:61], v[66:67] op_sel:[0,1,0]
	v_pk_fma_f32 v[86:87], v[62:63], v[60:61], v[86:87] op_sel_hi:[1,0,1]
	ds_read_b64 v[58:59], v89 offset:43776
	ds_read_b64 v[60:61], v90 offset:51224
	ds_write_b64 v91, v[86:87] offset:512
	s_waitcnt lgkmcnt(7)
	v_pk_mul_f32 v[62:63], v[2:3], v[18:19] op_sel_hi:[1,0]
	v_pk_mul_f32 v[64:65], v[4:5], v[18:19] op_sel:[0,1]
	v_pk_mul_f32 v[66:67], v[2:3], v[26:27] op_sel_hi:[1,0]
	v_pk_mul_f32 v[68:69], v[4:5], v[26:27] op_sel:[0,1]
	v_pk_fma_f32 v[62:63], v[6:7], v[20:21], v[62:63] op_sel_hi:[1,0,1]
	v_pk_fma_f32 v[66:67], v[6:7], v[28:29], v[66:67] op_sel_hi:[1,0,1]
	v_pk_fma_f32 v[64:65], v[8:9], v[20:21], v[64:65] op_sel:[0,1,0]
	v_pk_fma_f32 v[68:69], v[8:9], v[28:29], v[68:69] op_sel:[0,1,0]
	v_pk_fma_f32 v[62:63], v[10:11], v[22:23], v[62:63] op_sel_hi:[1,0,1]
	v_pk_fma_f32 v[66:67], v[10:11], v[30:31], v[66:67] op_sel_hi:[1,0,1]
	v_pk_fma_f32 v[64:65], v[12:13], v[22:23], v[64:65] op_sel:[0,1,0]
	v_pk_fma_f32 v[68:69], v[12:13], v[30:31], v[68:69] op_sel:[0,1,0]
	v_pk_fma_f32 v[62:63], v[14:15], v[24:25], v[62:63] op_sel_hi:[1,0,1]
	v_pk_fma_f32 v[66:67], v[14:15], v[32:33], v[66:67] op_sel_hi:[1,0,1]
	v_pk_fma_f32 v[64:65], v[16:17], v[24:25], v[64:65] op_sel:[0,1,0]
	v_pk_fma_f32 v[68:69], v[16:17], v[32:33], v[68:69] op_sel:[0,1,0]
	ds_read_b128 v[18:21], v88 offset:19456
	ds_read_b128 v[22:25], v88 offset:19472
	ds_read_b128 v[26:29], v88 offset:35840
	ds_read_b128 v[30:33], v88 offset:35856
	v_pk_add_f32 v[62:63], v[62:63], v[64:65]
	v_pk_add_f32 v[66:67], v[66:67], v[68:69]
	v_pk_mul_f32 v[70:71], v[2:3], v[34:35] op_sel_hi:[1,0]
	v_pk_mul_f32 v[72:73], v[4:5], v[34:35] op_sel:[0,1]
	v_pk_mul_f32 v[74:75], v[6:7], v[36:37] op_sel_hi:[1,0]
	v_pk_mul_f32 v[76:77], v[8:9], v[36:37] op_sel:[0,1]
	v_pk_mul_f32 v[78:79], v[10:11], v[38:39] op_sel_hi:[1,0]
	v_pk_mul_f32 v[80:81], v[12:13], v[38:39] op_sel:[0,1]
	v_pk_mul_f32 v[82:83], v[14:15], v[40:41] op_sel_hi:[1,0]
	v_pk_mul_f32 v[84:85], v[16:17], v[40:41] op_sel:[0,1]
	ds_read_b128 v[34:37], v88 offset:3072
	ds_read_b128 v[38:41], v88 offset:3088
	v_add_f32_dpp v62, v62, v62 quad_perm:[1,0,3,2] row_mask:0xf bank_mask:0xf bound_ctrl:1
	v_add_f32_dpp v63, v63, v63 quad_perm:[1,0,3,2] row_mask:0xf bank_mask:0xf bound_ctrl:1
	v_add_f32_dpp v66, v66, v66 quad_perm:[1,0,3,2] row_mask:0xf bank_mask:0xf bound_ctrl:1
	v_add_f32_dpp v67, v67, v67 quad_perm:[1,0,3,2] row_mask:0xf bank_mask:0xf bound_ctrl:1
	s_waitcnt lgkmcnt(7)
	v_pk_fma_f32 v[70:71], v[58:59], v[42:43], v[70:71] op_sel_hi:[1,0,1]
	v_pk_fma_f32 v[72:73], v[58:59], v[42:43], v[72:73] op_sel:[0,1,0]
	v_pk_fma_f32 v[74:75], v[58:59], v[44:45], v[74:75] op_sel_hi:[1,0,1]
	v_pk_fma_f32 v[76:77], v[58:59], v[44:45], v[76:77] op_sel:[0,1,0]
	v_add_f32_dpp v62, v62, v62 quad_perm:[2,3,0,1] row_mask:0xf bank_mask:0xf bound_ctrl:1
	v_add_f32_dpp v63, v63, v63 quad_perm:[2,3,0,1] row_mask:0xf bank_mask:0xf bound_ctrl:1
	v_add_f32_dpp v66, v66, v66 quad_perm:[2,3,0,1] row_mask:0xf bank_mask:0xf bound_ctrl:1
	v_add_f32_dpp v67, v67, v67 quad_perm:[2,3,0,1] row_mask:0xf bank_mask:0xf bound_ctrl:1
	v_pk_fma_f32 v[78:79], v[58:59], v[46:47], v[78:79] op_sel_hi:[1,0,1]
	v_pk_fma_f32 v[80:81], v[58:59], v[46:47], v[80:81] op_sel:[0,1,0]
	v_pk_fma_f32 v[82:83], v[58:59], v[48:49], v[82:83] op_sel_hi:[1,0,1]
	v_pk_fma_f32 v[84:85], v[58:59], v[48:49], v[84:85] op_sel:[0,1,0]
	ds_read_b128 v[42:45], v88 offset:11264
	ds_read_b128 v[46:49], v88 offset:11280
	v_add_f32_dpp v62, v62, v62 row_half_mirror row_mask:0xf bank_mask:0xf bound_ctrl:1
	v_add_f32_dpp v63, v63, v63 row_half_mirror row_mask:0xf bank_mask:0xf bound_ctrl:1
	v_add_f32_dpp v66, v66, v66 row_half_mirror row_mask:0xf bank_mask:0xf bound_ctrl:1
	v_add_f32_dpp v67, v67, v67 row_half_mirror row_mask:0xf bank_mask:0xf bound_ctrl:1
	v_pk_fma_f32 v[2:3], v[62:63], v[50:51], v[70:71] op_sel_hi:[1,0,1]
	v_pk_fma_f32 v[4:5], v[62:63], v[50:51], v[72:73] op_sel:[0,1,0]
	v_pk_fma_f32 v[6:7], v[62:63], v[52:53], v[74:75] op_sel_hi:[1,0,1]
	v_pk_fma_f32 v[8:9], v[62:63], v[52:53], v[76:77] op_sel:[0,1,0]
	v_pk_fma_f32 v[10:11], v[62:63], v[54:55], v[78:79] op_sel_hi:[1,0,1]
	v_pk_fma_f32 v[12:13], v[62:63], v[54:55], v[80:81] op_sel:[0,1,0]
	v_pk_fma_f32 v[14:15], v[62:63], v[56:57], v[82:83] op_sel_hi:[1,0,1]
	v_pk_fma_f32 v[16:17], v[62:63], v[56:57], v[84:85] op_sel:[0,1,0]
	ds_read_b128 v[50:53], v88 offset:27648
	ds_read_b128 v[54:57], v88 offset:27664
	v_pk_fma_f32 v[86:87], v[58:59], v[60:61], v[66:67] op_sel:[0,1,0]
	v_pk_fma_f32 v[86:87], v[62:63], v[60:61], v[86:87] op_sel_hi:[1,0,1]
	ds_read_b64 v[58:59], v89 offset:44032
	ds_read_b64 v[60:61], v90 offset:51232
	ds_write_b64 v91, v[86:87] offset:768
	s_waitcnt lgkmcnt(7)
	v_pk_mul_f32 v[62:63], v[2:3], v[18:19] op_sel_hi:[1,0]
	v_pk_mul_f32 v[64:65], v[4:5], v[18:19] op_sel:[0,1]
	v_pk_mul_f32 v[66:67], v[2:3], v[26:27] op_sel_hi:[1,0]
	v_pk_mul_f32 v[68:69], v[4:5], v[26:27] op_sel:[0,1]
	v_pk_fma_f32 v[62:63], v[6:7], v[20:21], v[62:63] op_sel_hi:[1,0,1]
	v_pk_fma_f32 v[66:67], v[6:7], v[28:29], v[66:67] op_sel_hi:[1,0,1]
	v_pk_fma_f32 v[64:65], v[8:9], v[20:21], v[64:65] op_sel:[0,1,0]
	v_pk_fma_f32 v[68:69], v[8:9], v[28:29], v[68:69] op_sel:[0,1,0]
	v_pk_fma_f32 v[62:63], v[10:11], v[22:23], v[62:63] op_sel_hi:[1,0,1]
	v_pk_fma_f32 v[66:67], v[10:11], v[30:31], v[66:67] op_sel_hi:[1,0,1]
	v_pk_fma_f32 v[64:65], v[12:13], v[22:23], v[64:65] op_sel:[0,1,0]
	v_pk_fma_f32 v[68:69], v[12:13], v[30:31], v[68:69] op_sel:[0,1,0]
	v_pk_fma_f32 v[62:63], v[14:15], v[24:25], v[62:63] op_sel_hi:[1,0,1]
	v_pk_fma_f32 v[66:67], v[14:15], v[32:33], v[66:67] op_sel_hi:[1,0,1]
	v_pk_fma_f32 v[64:65], v[16:17], v[24:25], v[64:65] op_sel:[0,1,0]
	v_pk_fma_f32 v[68:69], v[16:17], v[32:33], v[68:69] op_sel:[0,1,0]
	ds_read_b128 v[18:21], v88 offset:19712
	ds_read_b128 v[22:25], v88 offset:19728
	ds_read_b128 v[26:29], v88 offset:36096
	ds_read_b128 v[30:33], v88 offset:36112
	v_pk_add_f32 v[62:63], v[62:63], v[64:65]
	v_pk_add_f32 v[66:67], v[66:67], v[68:69]
	v_pk_mul_f32 v[70:71], v[2:3], v[34:35] op_sel_hi:[1,0]
	v_pk_mul_f32 v[72:73], v[4:5], v[34:35] op_sel:[0,1]
	v_pk_mul_f32 v[74:75], v[6:7], v[36:37] op_sel_hi:[1,0]
	v_pk_mul_f32 v[76:77], v[8:9], v[36:37] op_sel:[0,1]
	v_pk_mul_f32 v[78:79], v[10:11], v[38:39] op_sel_hi:[1,0]
	v_pk_mul_f32 v[80:81], v[12:13], v[38:39] op_sel:[0,1]
	v_pk_mul_f32 v[82:83], v[14:15], v[40:41] op_sel_hi:[1,0]
	v_pk_mul_f32 v[84:85], v[16:17], v[40:41] op_sel:[0,1]
	ds_read_b128 v[34:37], v88 offset:3328
	ds_read_b128 v[38:41], v88 offset:3344
	v_add_f32_dpp v62, v62, v62 quad_perm:[1,0,3,2] row_mask:0xf bank_mask:0xf bound_ctrl:1
	v_add_f32_dpp v63, v63, v63 quad_perm:[1,0,3,2] row_mask:0xf bank_mask:0xf bound_ctrl:1
	v_add_f32_dpp v66, v66, v66 quad_perm:[1,0,3,2] row_mask:0xf bank_mask:0xf bound_ctrl:1
	v_add_f32_dpp v67, v67, v67 quad_perm:[1,0,3,2] row_mask:0xf bank_mask:0xf bound_ctrl:1
	s_waitcnt lgkmcnt(7)
	v_pk_fma_f32 v[70:71], v[58:59], v[42:43], v[70:71] op_sel_hi:[1,0,1]
	v_pk_fma_f32 v[72:73], v[58:59], v[42:43], v[72:73] op_sel:[0,1,0]
	v_pk_fma_f32 v[74:75], v[58:59], v[44:45], v[74:75] op_sel_hi:[1,0,1]
	v_pk_fma_f32 v[76:77], v[58:59], v[44:45], v[76:77] op_sel:[0,1,0]
	v_add_f32_dpp v62, v62, v62 quad_perm:[2,3,0,1] row_mask:0xf bank_mask:0xf bound_ctrl:1
	v_add_f32_dpp v63, v63, v63 quad_perm:[2,3,0,1] row_mask:0xf bank_mask:0xf bound_ctrl:1
	v_add_f32_dpp v66, v66, v66 quad_perm:[2,3,0,1] row_mask:0xf bank_mask:0xf bound_ctrl:1
	v_add_f32_dpp v67, v67, v67 quad_perm:[2,3,0,1] row_mask:0xf bank_mask:0xf bound_ctrl:1
	v_pk_fma_f32 v[78:79], v[58:59], v[46:47], v[78:79] op_sel_hi:[1,0,1]
	v_pk_fma_f32 v[80:81], v[58:59], v[46:47], v[80:81] op_sel:[0,1,0]
	v_pk_fma_f32 v[82:83], v[58:59], v[48:49], v[82:83] op_sel_hi:[1,0,1]
	v_pk_fma_f32 v[84:85], v[58:59], v[48:49], v[84:85] op_sel:[0,1,0]
	ds_read_b128 v[42:45], v88 offset:11520
	ds_read_b128 v[46:49], v88 offset:11536
	v_add_f32_dpp v62, v62, v62 row_half_mirror row_mask:0xf bank_mask:0xf bound_ctrl:1
	v_add_f32_dpp v63, v63, v63 row_half_mirror row_mask:0xf bank_mask:0xf bound_ctrl:1
	v_add_f32_dpp v66, v66, v66 row_half_mirror row_mask:0xf bank_mask:0xf bound_ctrl:1
	v_add_f32_dpp v67, v67, v67 row_half_mirror row_mask:0xf bank_mask:0xf bound_ctrl:1
	v_pk_fma_f32 v[2:3], v[62:63], v[50:51], v[70:71] op_sel_hi:[1,0,1]
	v_pk_fma_f32 v[4:5], v[62:63], v[50:51], v[72:73] op_sel:[0,1,0]
	v_pk_fma_f32 v[6:7], v[62:63], v[52:53], v[74:75] op_sel_hi:[1,0,1]
	v_pk_fma_f32 v[8:9], v[62:63], v[52:53], v[76:77] op_sel:[0,1,0]
	v_pk_fma_f32 v[10:11], v[62:63], v[54:55], v[78:79] op_sel_hi:[1,0,1]
	v_pk_fma_f32 v[12:13], v[62:63], v[54:55], v[80:81] op_sel:[0,1,0]
	v_pk_fma_f32 v[14:15], v[62:63], v[56:57], v[82:83] op_sel_hi:[1,0,1]
	v_pk_fma_f32 v[16:17], v[62:63], v[56:57], v[84:85] op_sel:[0,1,0]
	ds_read_b128 v[50:53], v88 offset:27904
	ds_read_b128 v[54:57], v88 offset:27920
	v_pk_fma_f32 v[86:87], v[58:59], v[60:61], v[66:67] op_sel:[0,1,0]
	v_pk_fma_f32 v[86:87], v[62:63], v[60:61], v[86:87] op_sel_hi:[1,0,1]
	ds_read_b64 v[58:59], v89 offset:44288
	ds_read_b64 v[60:61], v90 offset:51240
	ds_write_b64 v91, v[86:87] offset:1024
	s_waitcnt lgkmcnt(7)
	v_pk_mul_f32 v[62:63], v[2:3], v[18:19] op_sel_hi:[1,0]
	v_pk_mul_f32 v[64:65], v[4:5], v[18:19] op_sel:[0,1]
	v_pk_mul_f32 v[66:67], v[2:3], v[26:27] op_sel_hi:[1,0]
	v_pk_mul_f32 v[68:69], v[4:5], v[26:27] op_sel:[0,1]
	v_pk_fma_f32 v[62:63], v[6:7], v[20:21], v[62:63] op_sel_hi:[1,0,1]
	v_pk_fma_f32 v[66:67], v[6:7], v[28:29], v[66:67] op_sel_hi:[1,0,1]
	v_pk_fma_f32 v[64:65], v[8:9], v[20:21], v[64:65] op_sel:[0,1,0]
	v_pk_fma_f32 v[68:69], v[8:9], v[28:29], v[68:69] op_sel:[0,1,0]
	v_pk_fma_f32 v[62:63], v[10:11], v[22:23], v[62:63] op_sel_hi:[1,0,1]
	v_pk_fma_f32 v[66:67], v[10:11], v[30:31], v[66:67] op_sel_hi:[1,0,1]
	v_pk_fma_f32 v[64:65], v[12:13], v[22:23], v[64:65] op_sel:[0,1,0]
	v_pk_fma_f32 v[68:69], v[12:13], v[30:31], v[68:69] op_sel:[0,1,0]
	v_pk_fma_f32 v[62:63], v[14:15], v[24:25], v[62:63] op_sel_hi:[1,0,1]
	v_pk_fma_f32 v[66:67], v[14:15], v[32:33], v[66:67] op_sel_hi:[1,0,1]
	v_pk_fma_f32 v[64:65], v[16:17], v[24:25], v[64:65] op_sel:[0,1,0]
	v_pk_fma_f32 v[68:69], v[16:17], v[32:33], v[68:69] op_sel:[0,1,0]
	ds_read_b128 v[18:21], v88 offset:19968
	ds_read_b128 v[22:25], v88 offset:19984
	ds_read_b128 v[26:29], v88 offset:36352
	ds_read_b128 v[30:33], v88 offset:36368
	v_pk_add_f32 v[62:63], v[62:63], v[64:65]
	v_pk_add_f32 v[66:67], v[66:67], v[68:69]
	v_pk_mul_f32 v[70:71], v[2:3], v[34:35] op_sel_hi:[1,0]
	v_pk_mul_f32 v[72:73], v[4:5], v[34:35] op_sel:[0,1]
	v_pk_mul_f32 v[74:75], v[6:7], v[36:37] op_sel_hi:[1,0]
	v_pk_mul_f32 v[76:77], v[8:9], v[36:37] op_sel:[0,1]
	v_pk_mul_f32 v[78:79], v[10:11], v[38:39] op_sel_hi:[1,0]
	v_pk_mul_f32 v[80:81], v[12:13], v[38:39] op_sel:[0,1]
	v_pk_mul_f32 v[82:83], v[14:15], v[40:41] op_sel_hi:[1,0]
	v_pk_mul_f32 v[84:85], v[16:17], v[40:41] op_sel:[0,1]
	ds_read_b128 v[34:37], v88 offset:3584
	ds_read_b128 v[38:41], v88 offset:3600
	v_add_f32_dpp v62, v62, v62 quad_perm:[1,0,3,2] row_mask:0xf bank_mask:0xf bound_ctrl:1
	v_add_f32_dpp v63, v63, v63 quad_perm:[1,0,3,2] row_mask:0xf bank_mask:0xf bound_ctrl:1
	v_add_f32_dpp v66, v66, v66 quad_perm:[1,0,3,2] row_mask:0xf bank_mask:0xf bound_ctrl:1
	v_add_f32_dpp v67, v67, v67 quad_perm:[1,0,3,2] row_mask:0xf bank_mask:0xf bound_ctrl:1
	s_waitcnt lgkmcnt(7)
	v_pk_fma_f32 v[70:71], v[58:59], v[42:43], v[70:71] op_sel_hi:[1,0,1]
	v_pk_fma_f32 v[72:73], v[58:59], v[42:43], v[72:73] op_sel:[0,1,0]
	v_pk_fma_f32 v[74:75], v[58:59], v[44:45], v[74:75] op_sel_hi:[1,0,1]
	v_pk_fma_f32 v[76:77], v[58:59], v[44:45], v[76:77] op_sel:[0,1,0]
	v_add_f32_dpp v62, v62, v62 quad_perm:[2,3,0,1] row_mask:0xf bank_mask:0xf bound_ctrl:1
	v_add_f32_dpp v63, v63, v63 quad_perm:[2,3,0,1] row_mask:0xf bank_mask:0xf bound_ctrl:1
	v_add_f32_dpp v66, v66, v66 quad_perm:[2,3,0,1] row_mask:0xf bank_mask:0xf bound_ctrl:1
	v_add_f32_dpp v67, v67, v67 quad_perm:[2,3,0,1] row_mask:0xf bank_mask:0xf bound_ctrl:1
	v_pk_fma_f32 v[78:79], v[58:59], v[46:47], v[78:79] op_sel_hi:[1,0,1]
	v_pk_fma_f32 v[80:81], v[58:59], v[46:47], v[80:81] op_sel:[0,1,0]
	v_pk_fma_f32 v[82:83], v[58:59], v[48:49], v[82:83] op_sel_hi:[1,0,1]
	v_pk_fma_f32 v[84:85], v[58:59], v[48:49], v[84:85] op_sel:[0,1,0]
	ds_read_b128 v[42:45], v88 offset:11776
	ds_read_b128 v[46:49], v88 offset:11792
	v_add_f32_dpp v62, v62, v62 row_half_mirror row_mask:0xf bank_mask:0xf bound_ctrl:1
	v_add_f32_dpp v63, v63, v63 row_half_mirror row_mask:0xf bank_mask:0xf bound_ctrl:1
	v_add_f32_dpp v66, v66, v66 row_half_mirror row_mask:0xf bank_mask:0xf bound_ctrl:1
	v_add_f32_dpp v67, v67, v67 row_half_mirror row_mask:0xf bank_mask:0xf bound_ctrl:1
	v_pk_fma_f32 v[2:3], v[62:63], v[50:51], v[70:71] op_sel_hi:[1,0,1]
	v_pk_fma_f32 v[4:5], v[62:63], v[50:51], v[72:73] op_sel:[0,1,0]
	v_pk_fma_f32 v[6:7], v[62:63], v[52:53], v[74:75] op_sel_hi:[1,0,1]
	v_pk_fma_f32 v[8:9], v[62:63], v[52:53], v[76:77] op_sel:[0,1,0]
	v_pk_fma_f32 v[10:11], v[62:63], v[54:55], v[78:79] op_sel_hi:[1,0,1]
	v_pk_fma_f32 v[12:13], v[62:63], v[54:55], v[80:81] op_sel:[0,1,0]
	v_pk_fma_f32 v[14:15], v[62:63], v[56:57], v[82:83] op_sel_hi:[1,0,1]
	v_pk_fma_f32 v[16:17], v[62:63], v[56:57], v[84:85] op_sel:[0,1,0]
	ds_read_b128 v[50:53], v88 offset:28160
	ds_read_b128 v[54:57], v88 offset:28176
	v_pk_fma_f32 v[86:87], v[58:59], v[60:61], v[66:67] op_sel:[0,1,0]
	v_pk_fma_f32 v[86:87], v[62:63], v[60:61], v[86:87] op_sel_hi:[1,0,1]
	ds_read_b64 v[58:59], v89 offset:44544
	ds_read_b64 v[60:61], v90 offset:51248
	ds_write_b64 v91, v[86:87] offset:1280
	s_waitcnt lgkmcnt(7)
	v_pk_mul_f32 v[62:63], v[2:3], v[18:19] op_sel_hi:[1,0]
	v_pk_mul_f32 v[64:65], v[4:5], v[18:19] op_sel:[0,1]
	v_pk_mul_f32 v[66:67], v[2:3], v[26:27] op_sel_hi:[1,0]
	v_pk_mul_f32 v[68:69], v[4:5], v[26:27] op_sel:[0,1]
	v_pk_fma_f32 v[62:63], v[6:7], v[20:21], v[62:63] op_sel_hi:[1,0,1]
	v_pk_fma_f32 v[66:67], v[6:7], v[28:29], v[66:67] op_sel_hi:[1,0,1]
	v_pk_fma_f32 v[64:65], v[8:9], v[20:21], v[64:65] op_sel:[0,1,0]
	v_pk_fma_f32 v[68:69], v[8:9], v[28:29], v[68:69] op_sel:[0,1,0]
	v_pk_fma_f32 v[62:63], v[10:11], v[22:23], v[62:63] op_sel_hi:[1,0,1]
	v_pk_fma_f32 v[66:67], v[10:11], v[30:31], v[66:67] op_sel_hi:[1,0,1]
	v_pk_fma_f32 v[64:65], v[12:13], v[22:23], v[64:65] op_sel:[0,1,0]
	v_pk_fma_f32 v[68:69], v[12:13], v[30:31], v[68:69] op_sel:[0,1,0]
	v_pk_fma_f32 v[62:63], v[14:15], v[24:25], v[62:63] op_sel_hi:[1,0,1]
	v_pk_fma_f32 v[66:67], v[14:15], v[32:33], v[66:67] op_sel_hi:[1,0,1]
	v_pk_fma_f32 v[64:65], v[16:17], v[24:25], v[64:65] op_sel:[0,1,0]
	v_pk_fma_f32 v[68:69], v[16:17], v[32:33], v[68:69] op_sel:[0,1,0]
	ds_read_b128 v[18:21], v88 offset:20224
	ds_read_b128 v[22:25], v88 offset:20240
	ds_read_b128 v[26:29], v88 offset:36608
	ds_read_b128 v[30:33], v88 offset:36624
	v_pk_add_f32 v[62:63], v[62:63], v[64:65]
	v_pk_add_f32 v[66:67], v[66:67], v[68:69]
	v_pk_mul_f32 v[70:71], v[2:3], v[34:35] op_sel_hi:[1,0]
	v_pk_mul_f32 v[72:73], v[4:5], v[34:35] op_sel:[0,1]
	v_pk_mul_f32 v[74:75], v[6:7], v[36:37] op_sel_hi:[1,0]
	v_pk_mul_f32 v[76:77], v[8:9], v[36:37] op_sel:[0,1]
	v_pk_mul_f32 v[78:79], v[10:11], v[38:39] op_sel_hi:[1,0]
	v_pk_mul_f32 v[80:81], v[12:13], v[38:39] op_sel:[0,1]
	v_pk_mul_f32 v[82:83], v[14:15], v[40:41] op_sel_hi:[1,0]
	v_pk_mul_f32 v[84:85], v[16:17], v[40:41] op_sel:[0,1]
	ds_read_b128 v[34:37], v88 offset:3840
	ds_read_b128 v[38:41], v88 offset:3856
	v_add_f32_dpp v62, v62, v62 quad_perm:[1,0,3,2] row_mask:0xf bank_mask:0xf bound_ctrl:1
	v_add_f32_dpp v63, v63, v63 quad_perm:[1,0,3,2] row_mask:0xf bank_mask:0xf bound_ctrl:1
	v_add_f32_dpp v66, v66, v66 quad_perm:[1,0,3,2] row_mask:0xf bank_mask:0xf bound_ctrl:1
	v_add_f32_dpp v67, v67, v67 quad_perm:[1,0,3,2] row_mask:0xf bank_mask:0xf bound_ctrl:1
	s_waitcnt lgkmcnt(7)
	v_pk_fma_f32 v[70:71], v[58:59], v[42:43], v[70:71] op_sel_hi:[1,0,1]
	v_pk_fma_f32 v[72:73], v[58:59], v[42:43], v[72:73] op_sel:[0,1,0]
	v_pk_fma_f32 v[74:75], v[58:59], v[44:45], v[74:75] op_sel_hi:[1,0,1]
	v_pk_fma_f32 v[76:77], v[58:59], v[44:45], v[76:77] op_sel:[0,1,0]
	v_add_f32_dpp v62, v62, v62 quad_perm:[2,3,0,1] row_mask:0xf bank_mask:0xf bound_ctrl:1
	v_add_f32_dpp v63, v63, v63 quad_perm:[2,3,0,1] row_mask:0xf bank_mask:0xf bound_ctrl:1
	v_add_f32_dpp v66, v66, v66 quad_perm:[2,3,0,1] row_mask:0xf bank_mask:0xf bound_ctrl:1
	v_add_f32_dpp v67, v67, v67 quad_perm:[2,3,0,1] row_mask:0xf bank_mask:0xf bound_ctrl:1
	v_pk_fma_f32 v[78:79], v[58:59], v[46:47], v[78:79] op_sel_hi:[1,0,1]
	v_pk_fma_f32 v[80:81], v[58:59], v[46:47], v[80:81] op_sel:[0,1,0]
	v_pk_fma_f32 v[82:83], v[58:59], v[48:49], v[82:83] op_sel_hi:[1,0,1]
	v_pk_fma_f32 v[84:85], v[58:59], v[48:49], v[84:85] op_sel:[0,1,0]
	ds_read_b128 v[42:45], v88 offset:12032
	ds_read_b128 v[46:49], v88 offset:12048
	v_add_f32_dpp v62, v62, v62 row_half_mirror row_mask:0xf bank_mask:0xf bound_ctrl:1
	v_add_f32_dpp v63, v63, v63 row_half_mirror row_mask:0xf bank_mask:0xf bound_ctrl:1
	v_add_f32_dpp v66, v66, v66 row_half_mirror row_mask:0xf bank_mask:0xf bound_ctrl:1
	v_add_f32_dpp v67, v67, v67 row_half_mirror row_mask:0xf bank_mask:0xf bound_ctrl:1
	v_pk_fma_f32 v[2:3], v[62:63], v[50:51], v[70:71] op_sel_hi:[1,0,1]
	v_pk_fma_f32 v[4:5], v[62:63], v[50:51], v[72:73] op_sel:[0,1,0]
	v_pk_fma_f32 v[6:7], v[62:63], v[52:53], v[74:75] op_sel_hi:[1,0,1]
	v_pk_fma_f32 v[8:9], v[62:63], v[52:53], v[76:77] op_sel:[0,1,0]
	v_pk_fma_f32 v[10:11], v[62:63], v[54:55], v[78:79] op_sel_hi:[1,0,1]
	v_pk_fma_f32 v[12:13], v[62:63], v[54:55], v[80:81] op_sel:[0,1,0]
	v_pk_fma_f32 v[14:15], v[62:63], v[56:57], v[82:83] op_sel_hi:[1,0,1]
	v_pk_fma_f32 v[16:17], v[62:63], v[56:57], v[84:85] op_sel:[0,1,0]
	ds_read_b128 v[50:53], v88 offset:28416
	ds_read_b128 v[54:57], v88 offset:28432
	v_pk_fma_f32 v[86:87], v[58:59], v[60:61], v[66:67] op_sel:[0,1,0]
	v_pk_fma_f32 v[86:87], v[62:63], v[60:61], v[86:87] op_sel_hi:[1,0,1]
	ds_read_b64 v[58:59], v89 offset:44800
	ds_read_b64 v[60:61], v90 offset:51256
	ds_write_b64 v91, v[86:87] offset:1536
	s_waitcnt lgkmcnt(7)
	v_pk_mul_f32 v[62:63], v[2:3], v[18:19] op_sel_hi:[1,0]
	v_pk_mul_f32 v[64:65], v[4:5], v[18:19] op_sel:[0,1]
	v_pk_mul_f32 v[66:67], v[2:3], v[26:27] op_sel_hi:[1,0]
	v_pk_mul_f32 v[68:69], v[4:5], v[26:27] op_sel:[0,1]
	v_pk_fma_f32 v[62:63], v[6:7], v[20:21], v[62:63] op_sel_hi:[1,0,1]
	v_pk_fma_f32 v[66:67], v[6:7], v[28:29], v[66:67] op_sel_hi:[1,0,1]
	v_pk_fma_f32 v[64:65], v[8:9], v[20:21], v[64:65] op_sel:[0,1,0]
	v_pk_fma_f32 v[68:69], v[8:9], v[28:29], v[68:69] op_sel:[0,1,0]
	v_pk_fma_f32 v[62:63], v[10:11], v[22:23], v[62:63] op_sel_hi:[1,0,1]
	v_pk_fma_f32 v[66:67], v[10:11], v[30:31], v[66:67] op_sel_hi:[1,0,1]
	v_pk_fma_f32 v[64:65], v[12:13], v[22:23], v[64:65] op_sel:[0,1,0]
	v_pk_fma_f32 v[68:69], v[12:13], v[30:31], v[68:69] op_sel:[0,1,0]
	v_pk_fma_f32 v[62:63], v[14:15], v[24:25], v[62:63] op_sel_hi:[1,0,1]
	v_pk_fma_f32 v[66:67], v[14:15], v[32:33], v[66:67] op_sel_hi:[1,0,1]
	v_pk_fma_f32 v[64:65], v[16:17], v[24:25], v[64:65] op_sel:[0,1,0]
	v_pk_fma_f32 v[68:69], v[16:17], v[32:33], v[68:69] op_sel:[0,1,0]
	ds_read_b128 v[18:21], v88 offset:20480
	ds_read_b128 v[22:25], v88 offset:20496
	ds_read_b128 v[26:29], v88 offset:36864
	ds_read_b128 v[30:33], v88 offset:36880
	v_pk_add_f32 v[62:63], v[62:63], v[64:65]
	v_pk_add_f32 v[66:67], v[66:67], v[68:69]
	v_pk_mul_f32 v[70:71], v[2:3], v[34:35] op_sel_hi:[1,0]
	v_pk_mul_f32 v[72:73], v[4:5], v[34:35] op_sel:[0,1]
	v_pk_mul_f32 v[74:75], v[6:7], v[36:37] op_sel_hi:[1,0]
	v_pk_mul_f32 v[76:77], v[8:9], v[36:37] op_sel:[0,1]
	v_pk_mul_f32 v[78:79], v[10:11], v[38:39] op_sel_hi:[1,0]
	v_pk_mul_f32 v[80:81], v[12:13], v[38:39] op_sel:[0,1]
	v_pk_mul_f32 v[82:83], v[14:15], v[40:41] op_sel_hi:[1,0]
	v_pk_mul_f32 v[84:85], v[16:17], v[40:41] op_sel:[0,1]
	ds_read_b128 v[34:37], v88 offset:4096
	ds_read_b128 v[38:41], v88 offset:4112
	v_add_f32_dpp v62, v62, v62 quad_perm:[1,0,3,2] row_mask:0xf bank_mask:0xf bound_ctrl:1
	v_add_f32_dpp v63, v63, v63 quad_perm:[1,0,3,2] row_mask:0xf bank_mask:0xf bound_ctrl:1
	v_add_f32_dpp v66, v66, v66 quad_perm:[1,0,3,2] row_mask:0xf bank_mask:0xf bound_ctrl:1
	v_add_f32_dpp v67, v67, v67 quad_perm:[1,0,3,2] row_mask:0xf bank_mask:0xf bound_ctrl:1
	s_waitcnt lgkmcnt(7)
	v_pk_fma_f32 v[70:71], v[58:59], v[42:43], v[70:71] op_sel_hi:[1,0,1]
	v_pk_fma_f32 v[72:73], v[58:59], v[42:43], v[72:73] op_sel:[0,1,0]
	v_pk_fma_f32 v[74:75], v[58:59], v[44:45], v[74:75] op_sel_hi:[1,0,1]
	v_pk_fma_f32 v[76:77], v[58:59], v[44:45], v[76:77] op_sel:[0,1,0]
	v_add_f32_dpp v62, v62, v62 quad_perm:[2,3,0,1] row_mask:0xf bank_mask:0xf bound_ctrl:1
	v_add_f32_dpp v63, v63, v63 quad_perm:[2,3,0,1] row_mask:0xf bank_mask:0xf bound_ctrl:1
	v_add_f32_dpp v66, v66, v66 quad_perm:[2,3,0,1] row_mask:0xf bank_mask:0xf bound_ctrl:1
	v_add_f32_dpp v67, v67, v67 quad_perm:[2,3,0,1] row_mask:0xf bank_mask:0xf bound_ctrl:1
	v_pk_fma_f32 v[78:79], v[58:59], v[46:47], v[78:79] op_sel_hi:[1,0,1]
	v_pk_fma_f32 v[80:81], v[58:59], v[46:47], v[80:81] op_sel:[0,1,0]
	v_pk_fma_f32 v[82:83], v[58:59], v[48:49], v[82:83] op_sel_hi:[1,0,1]
	v_pk_fma_f32 v[84:85], v[58:59], v[48:49], v[84:85] op_sel:[0,1,0]
	ds_read_b128 v[42:45], v88 offset:12288
	ds_read_b128 v[46:49], v88 offset:12304
	v_add_f32_dpp v62, v62, v62 row_half_mirror row_mask:0xf bank_mask:0xf bound_ctrl:1
	v_add_f32_dpp v63, v63, v63 row_half_mirror row_mask:0xf bank_mask:0xf bound_ctrl:1
	v_add_f32_dpp v66, v66, v66 row_half_mirror row_mask:0xf bank_mask:0xf bound_ctrl:1
	v_add_f32_dpp v67, v67, v67 row_half_mirror row_mask:0xf bank_mask:0xf bound_ctrl:1
	v_pk_fma_f32 v[2:3], v[62:63], v[50:51], v[70:71] op_sel_hi:[1,0,1]
	v_pk_fma_f32 v[4:5], v[62:63], v[50:51], v[72:73] op_sel:[0,1,0]
	v_pk_fma_f32 v[6:7], v[62:63], v[52:53], v[74:75] op_sel_hi:[1,0,1]
	v_pk_fma_f32 v[8:9], v[62:63], v[52:53], v[76:77] op_sel:[0,1,0]
	v_pk_fma_f32 v[10:11], v[62:63], v[54:55], v[78:79] op_sel_hi:[1,0,1]
	v_pk_fma_f32 v[12:13], v[62:63], v[54:55], v[80:81] op_sel:[0,1,0]
	v_pk_fma_f32 v[14:15], v[62:63], v[56:57], v[82:83] op_sel_hi:[1,0,1]
	v_pk_fma_f32 v[16:17], v[62:63], v[56:57], v[84:85] op_sel:[0,1,0]
	ds_read_b128 v[50:53], v88 offset:28672
	ds_read_b128 v[54:57], v88 offset:28688
	v_pk_fma_f32 v[86:87], v[58:59], v[60:61], v[66:67] op_sel:[0,1,0]
	v_pk_fma_f32 v[86:87], v[62:63], v[60:61], v[86:87] op_sel_hi:[1,0,1]
	ds_read_b64 v[58:59], v89 offset:45056
	ds_read_b64 v[60:61], v90 offset:51264
	ds_write_b64 v91, v[86:87] offset:1792
	s_waitcnt lgkmcnt(7)
	v_pk_mul_f32 v[62:63], v[2:3], v[18:19] op_sel_hi:[1,0]
	v_pk_mul_f32 v[64:65], v[4:5], v[18:19] op_sel:[0,1]
	v_pk_mul_f32 v[66:67], v[2:3], v[26:27] op_sel_hi:[1,0]
	v_pk_mul_f32 v[68:69], v[4:5], v[26:27] op_sel:[0,1]
	v_pk_fma_f32 v[62:63], v[6:7], v[20:21], v[62:63] op_sel_hi:[1,0,1]
	v_pk_fma_f32 v[66:67], v[6:7], v[28:29], v[66:67] op_sel_hi:[1,0,1]
	v_pk_fma_f32 v[64:65], v[8:9], v[20:21], v[64:65] op_sel:[0,1,0]
	v_pk_fma_f32 v[68:69], v[8:9], v[28:29], v[68:69] op_sel:[0,1,0]
	v_pk_fma_f32 v[62:63], v[10:11], v[22:23], v[62:63] op_sel_hi:[1,0,1]
	v_pk_fma_f32 v[66:67], v[10:11], v[30:31], v[66:67] op_sel_hi:[1,0,1]
	v_pk_fma_f32 v[64:65], v[12:13], v[22:23], v[64:65] op_sel:[0,1,0]
	v_pk_fma_f32 v[68:69], v[12:13], v[30:31], v[68:69] op_sel:[0,1,0]
	v_pk_fma_f32 v[62:63], v[14:15], v[24:25], v[62:63] op_sel_hi:[1,0,1]
	v_pk_fma_f32 v[66:67], v[14:15], v[32:33], v[66:67] op_sel_hi:[1,0,1]
	v_pk_fma_f32 v[64:65], v[16:17], v[24:25], v[64:65] op_sel:[0,1,0]
	v_pk_fma_f32 v[68:69], v[16:17], v[32:33], v[68:69] op_sel:[0,1,0]
	ds_read_b128 v[18:21], v88 offset:20736
	ds_read_b128 v[22:25], v88 offset:20752
	ds_read_b128 v[26:29], v88 offset:37120
	ds_read_b128 v[30:33], v88 offset:37136
	v_pk_add_f32 v[62:63], v[62:63], v[64:65]
	v_pk_add_f32 v[66:67], v[66:67], v[68:69]
	v_pk_mul_f32 v[70:71], v[2:3], v[34:35] op_sel_hi:[1,0]
	v_pk_mul_f32 v[72:73], v[4:5], v[34:35] op_sel:[0,1]
	v_pk_mul_f32 v[74:75], v[6:7], v[36:37] op_sel_hi:[1,0]
	v_pk_mul_f32 v[76:77], v[8:9], v[36:37] op_sel:[0,1]
	v_pk_mul_f32 v[78:79], v[10:11], v[38:39] op_sel_hi:[1,0]
	v_pk_mul_f32 v[80:81], v[12:13], v[38:39] op_sel:[0,1]
	v_pk_mul_f32 v[82:83], v[14:15], v[40:41] op_sel_hi:[1,0]
	v_pk_mul_f32 v[84:85], v[16:17], v[40:41] op_sel:[0,1]
	ds_read_b128 v[34:37], v88 offset:4352
	ds_read_b128 v[38:41], v88 offset:4368
	v_add_f32_dpp v62, v62, v62 quad_perm:[1,0,3,2] row_mask:0xf bank_mask:0xf bound_ctrl:1
	v_add_f32_dpp v63, v63, v63 quad_perm:[1,0,3,2] row_mask:0xf bank_mask:0xf bound_ctrl:1
	v_add_f32_dpp v66, v66, v66 quad_perm:[1,0,3,2] row_mask:0xf bank_mask:0xf bound_ctrl:1
	v_add_f32_dpp v67, v67, v67 quad_perm:[1,0,3,2] row_mask:0xf bank_mask:0xf bound_ctrl:1
	s_waitcnt lgkmcnt(7)
	v_pk_fma_f32 v[70:71], v[58:59], v[42:43], v[70:71] op_sel_hi:[1,0,1]
	v_pk_fma_f32 v[72:73], v[58:59], v[42:43], v[72:73] op_sel:[0,1,0]
	v_pk_fma_f32 v[74:75], v[58:59], v[44:45], v[74:75] op_sel_hi:[1,0,1]
	v_pk_fma_f32 v[76:77], v[58:59], v[44:45], v[76:77] op_sel:[0,1,0]
	v_add_f32_dpp v62, v62, v62 quad_perm:[2,3,0,1] row_mask:0xf bank_mask:0xf bound_ctrl:1
	v_add_f32_dpp v63, v63, v63 quad_perm:[2,3,0,1] row_mask:0xf bank_mask:0xf bound_ctrl:1
	v_add_f32_dpp v66, v66, v66 quad_perm:[2,3,0,1] row_mask:0xf bank_mask:0xf bound_ctrl:1
	v_add_f32_dpp v67, v67, v67 quad_perm:[2,3,0,1] row_mask:0xf bank_mask:0xf bound_ctrl:1
	v_pk_fma_f32 v[78:79], v[58:59], v[46:47], v[78:79] op_sel_hi:[1,0,1]
	v_pk_fma_f32 v[80:81], v[58:59], v[46:47], v[80:81] op_sel:[0,1,0]
	v_pk_fma_f32 v[82:83], v[58:59], v[48:49], v[82:83] op_sel_hi:[1,0,1]
	v_pk_fma_f32 v[84:85], v[58:59], v[48:49], v[84:85] op_sel:[0,1,0]
	ds_read_b128 v[42:45], v88 offset:12544
	ds_read_b128 v[46:49], v88 offset:12560
	v_add_f32_dpp v62, v62, v62 row_half_mirror row_mask:0xf bank_mask:0xf bound_ctrl:1
	v_add_f32_dpp v63, v63, v63 row_half_mirror row_mask:0xf bank_mask:0xf bound_ctrl:1
	v_add_f32_dpp v66, v66, v66 row_half_mirror row_mask:0xf bank_mask:0xf bound_ctrl:1
	v_add_f32_dpp v67, v67, v67 row_half_mirror row_mask:0xf bank_mask:0xf bound_ctrl:1
	v_pk_fma_f32 v[2:3], v[62:63], v[50:51], v[70:71] op_sel_hi:[1,0,1]
	v_pk_fma_f32 v[4:5], v[62:63], v[50:51], v[72:73] op_sel:[0,1,0]
	v_pk_fma_f32 v[6:7], v[62:63], v[52:53], v[74:75] op_sel_hi:[1,0,1]
	v_pk_fma_f32 v[8:9], v[62:63], v[52:53], v[76:77] op_sel:[0,1,0]
	v_pk_fma_f32 v[10:11], v[62:63], v[54:55], v[78:79] op_sel_hi:[1,0,1]
	v_pk_fma_f32 v[12:13], v[62:63], v[54:55], v[80:81] op_sel:[0,1,0]
	v_pk_fma_f32 v[14:15], v[62:63], v[56:57], v[82:83] op_sel_hi:[1,0,1]
	v_pk_fma_f32 v[16:17], v[62:63], v[56:57], v[84:85] op_sel:[0,1,0]
	ds_read_b128 v[50:53], v88 offset:28928
	ds_read_b128 v[54:57], v88 offset:28944
	v_pk_fma_f32 v[86:87], v[58:59], v[60:61], v[66:67] op_sel:[0,1,0]
	v_pk_fma_f32 v[86:87], v[62:63], v[60:61], v[86:87] op_sel_hi:[1,0,1]
	ds_read_b64 v[58:59], v89 offset:45312
	ds_read_b64 v[60:61], v90 offset:51272
	ds_write_b64 v91, v[86:87] offset:2048
	s_waitcnt lgkmcnt(7)
	v_pk_mul_f32 v[62:63], v[2:3], v[18:19] op_sel_hi:[1,0]
	v_pk_mul_f32 v[64:65], v[4:5], v[18:19] op_sel:[0,1]
	v_pk_mul_f32 v[66:67], v[2:3], v[26:27] op_sel_hi:[1,0]
	v_pk_mul_f32 v[68:69], v[4:5], v[26:27] op_sel:[0,1]
	v_pk_fma_f32 v[62:63], v[6:7], v[20:21], v[62:63] op_sel_hi:[1,0,1]
	v_pk_fma_f32 v[66:67], v[6:7], v[28:29], v[66:67] op_sel_hi:[1,0,1]
	v_pk_fma_f32 v[64:65], v[8:9], v[20:21], v[64:65] op_sel:[0,1,0]
	v_pk_fma_f32 v[68:69], v[8:9], v[28:29], v[68:69] op_sel:[0,1,0]
	v_pk_fma_f32 v[62:63], v[10:11], v[22:23], v[62:63] op_sel_hi:[1,0,1]
	v_pk_fma_f32 v[66:67], v[10:11], v[30:31], v[66:67] op_sel_hi:[1,0,1]
	v_pk_fma_f32 v[64:65], v[12:13], v[22:23], v[64:65] op_sel:[0,1,0]
	v_pk_fma_f32 v[68:69], v[12:13], v[30:31], v[68:69] op_sel:[0,1,0]
	v_pk_fma_f32 v[62:63], v[14:15], v[24:25], v[62:63] op_sel_hi:[1,0,1]
	v_pk_fma_f32 v[66:67], v[14:15], v[32:33], v[66:67] op_sel_hi:[1,0,1]
	v_pk_fma_f32 v[64:65], v[16:17], v[24:25], v[64:65] op_sel:[0,1,0]
	v_pk_fma_f32 v[68:69], v[16:17], v[32:33], v[68:69] op_sel:[0,1,0]
	ds_read_b128 v[18:21], v88 offset:20992
	ds_read_b128 v[22:25], v88 offset:21008
	ds_read_b128 v[26:29], v88 offset:37376
	ds_read_b128 v[30:33], v88 offset:37392
	v_pk_add_f32 v[62:63], v[62:63], v[64:65]
	v_pk_add_f32 v[66:67], v[66:67], v[68:69]
	v_pk_mul_f32 v[70:71], v[2:3], v[34:35] op_sel_hi:[1,0]
	v_pk_mul_f32 v[72:73], v[4:5], v[34:35] op_sel:[0,1]
	v_pk_mul_f32 v[74:75], v[6:7], v[36:37] op_sel_hi:[1,0]
	v_pk_mul_f32 v[76:77], v[8:9], v[36:37] op_sel:[0,1]
	v_pk_mul_f32 v[78:79], v[10:11], v[38:39] op_sel_hi:[1,0]
	v_pk_mul_f32 v[80:81], v[12:13], v[38:39] op_sel:[0,1]
	v_pk_mul_f32 v[82:83], v[14:15], v[40:41] op_sel_hi:[1,0]
	v_pk_mul_f32 v[84:85], v[16:17], v[40:41] op_sel:[0,1]
	ds_read_b128 v[34:37], v88 offset:4608
	ds_read_b128 v[38:41], v88 offset:4624
	v_add_f32_dpp v62, v62, v62 quad_perm:[1,0,3,2] row_mask:0xf bank_mask:0xf bound_ctrl:1
	v_add_f32_dpp v63, v63, v63 quad_perm:[1,0,3,2] row_mask:0xf bank_mask:0xf bound_ctrl:1
	v_add_f32_dpp v66, v66, v66 quad_perm:[1,0,3,2] row_mask:0xf bank_mask:0xf bound_ctrl:1
	v_add_f32_dpp v67, v67, v67 quad_perm:[1,0,3,2] row_mask:0xf bank_mask:0xf bound_ctrl:1
	s_waitcnt lgkmcnt(7)
	v_pk_fma_f32 v[70:71], v[58:59], v[42:43], v[70:71] op_sel_hi:[1,0,1]
	v_pk_fma_f32 v[72:73], v[58:59], v[42:43], v[72:73] op_sel:[0,1,0]
	v_pk_fma_f32 v[74:75], v[58:59], v[44:45], v[74:75] op_sel_hi:[1,0,1]
	v_pk_fma_f32 v[76:77], v[58:59], v[44:45], v[76:77] op_sel:[0,1,0]
	v_add_f32_dpp v62, v62, v62 quad_perm:[2,3,0,1] row_mask:0xf bank_mask:0xf bound_ctrl:1
	v_add_f32_dpp v63, v63, v63 quad_perm:[2,3,0,1] row_mask:0xf bank_mask:0xf bound_ctrl:1
	v_add_f32_dpp v66, v66, v66 quad_perm:[2,3,0,1] row_mask:0xf bank_mask:0xf bound_ctrl:1
	v_add_f32_dpp v67, v67, v67 quad_perm:[2,3,0,1] row_mask:0xf bank_mask:0xf bound_ctrl:1
	v_pk_fma_f32 v[78:79], v[58:59], v[46:47], v[78:79] op_sel_hi:[1,0,1]
	v_pk_fma_f32 v[80:81], v[58:59], v[46:47], v[80:81] op_sel:[0,1,0]
	v_pk_fma_f32 v[82:83], v[58:59], v[48:49], v[82:83] op_sel_hi:[1,0,1]
	v_pk_fma_f32 v[84:85], v[58:59], v[48:49], v[84:85] op_sel:[0,1,0]
	ds_read_b128 v[42:45], v88 offset:12800
	ds_read_b128 v[46:49], v88 offset:12816
	v_add_f32_dpp v62, v62, v62 row_half_mirror row_mask:0xf bank_mask:0xf bound_ctrl:1
	v_add_f32_dpp v63, v63, v63 row_half_mirror row_mask:0xf bank_mask:0xf bound_ctrl:1
	v_add_f32_dpp v66, v66, v66 row_half_mirror row_mask:0xf bank_mask:0xf bound_ctrl:1
	v_add_f32_dpp v67, v67, v67 row_half_mirror row_mask:0xf bank_mask:0xf bound_ctrl:1
	v_pk_fma_f32 v[2:3], v[62:63], v[50:51], v[70:71] op_sel_hi:[1,0,1]
	v_pk_fma_f32 v[4:5], v[62:63], v[50:51], v[72:73] op_sel:[0,1,0]
	v_pk_fma_f32 v[6:7], v[62:63], v[52:53], v[74:75] op_sel_hi:[1,0,1]
	v_pk_fma_f32 v[8:9], v[62:63], v[52:53], v[76:77] op_sel:[0,1,0]
	v_pk_fma_f32 v[10:11], v[62:63], v[54:55], v[78:79] op_sel_hi:[1,0,1]
	v_pk_fma_f32 v[12:13], v[62:63], v[54:55], v[80:81] op_sel:[0,1,0]
	v_pk_fma_f32 v[14:15], v[62:63], v[56:57], v[82:83] op_sel_hi:[1,0,1]
	v_pk_fma_f32 v[16:17], v[62:63], v[56:57], v[84:85] op_sel:[0,1,0]
	ds_read_b128 v[50:53], v88 offset:29184
	ds_read_b128 v[54:57], v88 offset:29200
	v_pk_fma_f32 v[86:87], v[58:59], v[60:61], v[66:67] op_sel:[0,1,0]
	v_pk_fma_f32 v[86:87], v[62:63], v[60:61], v[86:87] op_sel_hi:[1,0,1]
	ds_read_b64 v[58:59], v89 offset:45568
	ds_read_b64 v[60:61], v90 offset:51280
	ds_write_b64 v91, v[86:87] offset:2304
	s_waitcnt lgkmcnt(7)
	v_pk_mul_f32 v[62:63], v[2:3], v[18:19] op_sel_hi:[1,0]
	v_pk_mul_f32 v[64:65], v[4:5], v[18:19] op_sel:[0,1]
	v_pk_mul_f32 v[66:67], v[2:3], v[26:27] op_sel_hi:[1,0]
	v_pk_mul_f32 v[68:69], v[4:5], v[26:27] op_sel:[0,1]
	v_pk_fma_f32 v[62:63], v[6:7], v[20:21], v[62:63] op_sel_hi:[1,0,1]
	v_pk_fma_f32 v[66:67], v[6:7], v[28:29], v[66:67] op_sel_hi:[1,0,1]
	v_pk_fma_f32 v[64:65], v[8:9], v[20:21], v[64:65] op_sel:[0,1,0]
	v_pk_fma_f32 v[68:69], v[8:9], v[28:29], v[68:69] op_sel:[0,1,0]
	v_pk_fma_f32 v[62:63], v[10:11], v[22:23], v[62:63] op_sel_hi:[1,0,1]
	v_pk_fma_f32 v[66:67], v[10:11], v[30:31], v[66:67] op_sel_hi:[1,0,1]
	v_pk_fma_f32 v[64:65], v[12:13], v[22:23], v[64:65] op_sel:[0,1,0]
	v_pk_fma_f32 v[68:69], v[12:13], v[30:31], v[68:69] op_sel:[0,1,0]
	v_pk_fma_f32 v[62:63], v[14:15], v[24:25], v[62:63] op_sel_hi:[1,0,1]
	v_pk_fma_f32 v[66:67], v[14:15], v[32:33], v[66:67] op_sel_hi:[1,0,1]
	v_pk_fma_f32 v[64:65], v[16:17], v[24:25], v[64:65] op_sel:[0,1,0]
	v_pk_fma_f32 v[68:69], v[16:17], v[32:33], v[68:69] op_sel:[0,1,0]
	ds_read_b128 v[18:21], v88 offset:21248
	ds_read_b128 v[22:25], v88 offset:21264
	ds_read_b128 v[26:29], v88 offset:37632
	ds_read_b128 v[30:33], v88 offset:37648
	v_pk_add_f32 v[62:63], v[62:63], v[64:65]
	v_pk_add_f32 v[66:67], v[66:67], v[68:69]
	v_pk_mul_f32 v[70:71], v[2:3], v[34:35] op_sel_hi:[1,0]
	v_pk_mul_f32 v[72:73], v[4:5], v[34:35] op_sel:[0,1]
	v_pk_mul_f32 v[74:75], v[6:7], v[36:37] op_sel_hi:[1,0]
	v_pk_mul_f32 v[76:77], v[8:9], v[36:37] op_sel:[0,1]
	v_pk_mul_f32 v[78:79], v[10:11], v[38:39] op_sel_hi:[1,0]
	v_pk_mul_f32 v[80:81], v[12:13], v[38:39] op_sel:[0,1]
	v_pk_mul_f32 v[82:83], v[14:15], v[40:41] op_sel_hi:[1,0]
	v_pk_mul_f32 v[84:85], v[16:17], v[40:41] op_sel:[0,1]
	ds_read_b128 v[34:37], v88 offset:4864
	ds_read_b128 v[38:41], v88 offset:4880
	v_add_f32_dpp v62, v62, v62 quad_perm:[1,0,3,2] row_mask:0xf bank_mask:0xf bound_ctrl:1
	v_add_f32_dpp v63, v63, v63 quad_perm:[1,0,3,2] row_mask:0xf bank_mask:0xf bound_ctrl:1
	v_add_f32_dpp v66, v66, v66 quad_perm:[1,0,3,2] row_mask:0xf bank_mask:0xf bound_ctrl:1
	v_add_f32_dpp v67, v67, v67 quad_perm:[1,0,3,2] row_mask:0xf bank_mask:0xf bound_ctrl:1
	s_waitcnt lgkmcnt(7)
	v_pk_fma_f32 v[70:71], v[58:59], v[42:43], v[70:71] op_sel_hi:[1,0,1]
	v_pk_fma_f32 v[72:73], v[58:59], v[42:43], v[72:73] op_sel:[0,1,0]
	v_pk_fma_f32 v[74:75], v[58:59], v[44:45], v[74:75] op_sel_hi:[1,0,1]
	v_pk_fma_f32 v[76:77], v[58:59], v[44:45], v[76:77] op_sel:[0,1,0]
	v_add_f32_dpp v62, v62, v62 quad_perm:[2,3,0,1] row_mask:0xf bank_mask:0xf bound_ctrl:1
	v_add_f32_dpp v63, v63, v63 quad_perm:[2,3,0,1] row_mask:0xf bank_mask:0xf bound_ctrl:1
	v_add_f32_dpp v66, v66, v66 quad_perm:[2,3,0,1] row_mask:0xf bank_mask:0xf bound_ctrl:1
	v_add_f32_dpp v67, v67, v67 quad_perm:[2,3,0,1] row_mask:0xf bank_mask:0xf bound_ctrl:1
	v_pk_fma_f32 v[78:79], v[58:59], v[46:47], v[78:79] op_sel_hi:[1,0,1]
	v_pk_fma_f32 v[80:81], v[58:59], v[46:47], v[80:81] op_sel:[0,1,0]
	v_pk_fma_f32 v[82:83], v[58:59], v[48:49], v[82:83] op_sel_hi:[1,0,1]
	v_pk_fma_f32 v[84:85], v[58:59], v[48:49], v[84:85] op_sel:[0,1,0]
	ds_read_b128 v[42:45], v88 offset:13056
	ds_read_b128 v[46:49], v88 offset:13072
	v_add_f32_dpp v62, v62, v62 row_half_mirror row_mask:0xf bank_mask:0xf bound_ctrl:1
	v_add_f32_dpp v63, v63, v63 row_half_mirror row_mask:0xf bank_mask:0xf bound_ctrl:1
	v_add_f32_dpp v66, v66, v66 row_half_mirror row_mask:0xf bank_mask:0xf bound_ctrl:1
	v_add_f32_dpp v67, v67, v67 row_half_mirror row_mask:0xf bank_mask:0xf bound_ctrl:1
	v_pk_fma_f32 v[2:3], v[62:63], v[50:51], v[70:71] op_sel_hi:[1,0,1]
	v_pk_fma_f32 v[4:5], v[62:63], v[50:51], v[72:73] op_sel:[0,1,0]
	v_pk_fma_f32 v[6:7], v[62:63], v[52:53], v[74:75] op_sel_hi:[1,0,1]
	v_pk_fma_f32 v[8:9], v[62:63], v[52:53], v[76:77] op_sel:[0,1,0]
	v_pk_fma_f32 v[10:11], v[62:63], v[54:55], v[78:79] op_sel_hi:[1,0,1]
	v_pk_fma_f32 v[12:13], v[62:63], v[54:55], v[80:81] op_sel:[0,1,0]
	v_pk_fma_f32 v[14:15], v[62:63], v[56:57], v[82:83] op_sel_hi:[1,0,1]
	v_pk_fma_f32 v[16:17], v[62:63], v[56:57], v[84:85] op_sel:[0,1,0]
	ds_read_b128 v[50:53], v88 offset:29440
	ds_read_b128 v[54:57], v88 offset:29456
	v_pk_fma_f32 v[86:87], v[58:59], v[60:61], v[66:67] op_sel:[0,1,0]
	v_pk_fma_f32 v[86:87], v[62:63], v[60:61], v[86:87] op_sel_hi:[1,0,1]
	ds_read_b64 v[58:59], v89 offset:45824
	ds_read_b64 v[60:61], v90 offset:51288
	ds_write_b64 v91, v[86:87] offset:2560
	s_waitcnt lgkmcnt(7)
	v_pk_mul_f32 v[62:63], v[2:3], v[18:19] op_sel_hi:[1,0]
	v_pk_mul_f32 v[64:65], v[4:5], v[18:19] op_sel:[0,1]
	v_pk_mul_f32 v[66:67], v[2:3], v[26:27] op_sel_hi:[1,0]
	v_pk_mul_f32 v[68:69], v[4:5], v[26:27] op_sel:[0,1]
	v_pk_fma_f32 v[62:63], v[6:7], v[20:21], v[62:63] op_sel_hi:[1,0,1]
	v_pk_fma_f32 v[66:67], v[6:7], v[28:29], v[66:67] op_sel_hi:[1,0,1]
	v_pk_fma_f32 v[64:65], v[8:9], v[20:21], v[64:65] op_sel:[0,1,0]
	v_pk_fma_f32 v[68:69], v[8:9], v[28:29], v[68:69] op_sel:[0,1,0]
	v_pk_fma_f32 v[62:63], v[10:11], v[22:23], v[62:63] op_sel_hi:[1,0,1]
	v_pk_fma_f32 v[66:67], v[10:11], v[30:31], v[66:67] op_sel_hi:[1,0,1]
	v_pk_fma_f32 v[64:65], v[12:13], v[22:23], v[64:65] op_sel:[0,1,0]
	v_pk_fma_f32 v[68:69], v[12:13], v[30:31], v[68:69] op_sel:[0,1,0]
	v_pk_fma_f32 v[62:63], v[14:15], v[24:25], v[62:63] op_sel_hi:[1,0,1]
	v_pk_fma_f32 v[66:67], v[14:15], v[32:33], v[66:67] op_sel_hi:[1,0,1]
	v_pk_fma_f32 v[64:65], v[16:17], v[24:25], v[64:65] op_sel:[0,1,0]
	v_pk_fma_f32 v[68:69], v[16:17], v[32:33], v[68:69] op_sel:[0,1,0]
	ds_read_b128 v[18:21], v88 offset:21504
	ds_read_b128 v[22:25], v88 offset:21520
	ds_read_b128 v[26:29], v88 offset:37888
	ds_read_b128 v[30:33], v88 offset:37904
	v_pk_add_f32 v[62:63], v[62:63], v[64:65]
	v_pk_add_f32 v[66:67], v[66:67], v[68:69]
	v_pk_mul_f32 v[70:71], v[2:3], v[34:35] op_sel_hi:[1,0]
	v_pk_mul_f32 v[72:73], v[4:5], v[34:35] op_sel:[0,1]
	v_pk_mul_f32 v[74:75], v[6:7], v[36:37] op_sel_hi:[1,0]
	v_pk_mul_f32 v[76:77], v[8:9], v[36:37] op_sel:[0,1]
	v_pk_mul_f32 v[78:79], v[10:11], v[38:39] op_sel_hi:[1,0]
	v_pk_mul_f32 v[80:81], v[12:13], v[38:39] op_sel:[0,1]
	v_pk_mul_f32 v[82:83], v[14:15], v[40:41] op_sel_hi:[1,0]
	v_pk_mul_f32 v[84:85], v[16:17], v[40:41] op_sel:[0,1]
	ds_read_b128 v[34:37], v88 offset:5120
	ds_read_b128 v[38:41], v88 offset:5136
	v_add_f32_dpp v62, v62, v62 quad_perm:[1,0,3,2] row_mask:0xf bank_mask:0xf bound_ctrl:1
	v_add_f32_dpp v63, v63, v63 quad_perm:[1,0,3,2] row_mask:0xf bank_mask:0xf bound_ctrl:1
	v_add_f32_dpp v66, v66, v66 quad_perm:[1,0,3,2] row_mask:0xf bank_mask:0xf bound_ctrl:1
	v_add_f32_dpp v67, v67, v67 quad_perm:[1,0,3,2] row_mask:0xf bank_mask:0xf bound_ctrl:1
	s_waitcnt lgkmcnt(7)
	v_pk_fma_f32 v[70:71], v[58:59], v[42:43], v[70:71] op_sel_hi:[1,0,1]
	v_pk_fma_f32 v[72:73], v[58:59], v[42:43], v[72:73] op_sel:[0,1,0]
	v_pk_fma_f32 v[74:75], v[58:59], v[44:45], v[74:75] op_sel_hi:[1,0,1]
	v_pk_fma_f32 v[76:77], v[58:59], v[44:45], v[76:77] op_sel:[0,1,0]
	v_add_f32_dpp v62, v62, v62 quad_perm:[2,3,0,1] row_mask:0xf bank_mask:0xf bound_ctrl:1
	v_add_f32_dpp v63, v63, v63 quad_perm:[2,3,0,1] row_mask:0xf bank_mask:0xf bound_ctrl:1
	v_add_f32_dpp v66, v66, v66 quad_perm:[2,3,0,1] row_mask:0xf bank_mask:0xf bound_ctrl:1
	v_add_f32_dpp v67, v67, v67 quad_perm:[2,3,0,1] row_mask:0xf bank_mask:0xf bound_ctrl:1
	v_pk_fma_f32 v[78:79], v[58:59], v[46:47], v[78:79] op_sel_hi:[1,0,1]
	v_pk_fma_f32 v[80:81], v[58:59], v[46:47], v[80:81] op_sel:[0,1,0]
	v_pk_fma_f32 v[82:83], v[58:59], v[48:49], v[82:83] op_sel_hi:[1,0,1]
	v_pk_fma_f32 v[84:85], v[58:59], v[48:49], v[84:85] op_sel:[0,1,0]
	ds_read_b128 v[42:45], v88 offset:13312
	ds_read_b128 v[46:49], v88 offset:13328
	v_add_f32_dpp v62, v62, v62 row_half_mirror row_mask:0xf bank_mask:0xf bound_ctrl:1
	v_add_f32_dpp v63, v63, v63 row_half_mirror row_mask:0xf bank_mask:0xf bound_ctrl:1
	v_add_f32_dpp v66, v66, v66 row_half_mirror row_mask:0xf bank_mask:0xf bound_ctrl:1
	v_add_f32_dpp v67, v67, v67 row_half_mirror row_mask:0xf bank_mask:0xf bound_ctrl:1
	v_pk_fma_f32 v[2:3], v[62:63], v[50:51], v[70:71] op_sel_hi:[1,0,1]
	v_pk_fma_f32 v[4:5], v[62:63], v[50:51], v[72:73] op_sel:[0,1,0]
	v_pk_fma_f32 v[6:7], v[62:63], v[52:53], v[74:75] op_sel_hi:[1,0,1]
	v_pk_fma_f32 v[8:9], v[62:63], v[52:53], v[76:77] op_sel:[0,1,0]
	v_pk_fma_f32 v[10:11], v[62:63], v[54:55], v[78:79] op_sel_hi:[1,0,1]
	v_pk_fma_f32 v[12:13], v[62:63], v[54:55], v[80:81] op_sel:[0,1,0]
	v_pk_fma_f32 v[14:15], v[62:63], v[56:57], v[82:83] op_sel_hi:[1,0,1]
	v_pk_fma_f32 v[16:17], v[62:63], v[56:57], v[84:85] op_sel:[0,1,0]
	ds_read_b128 v[50:53], v88 offset:29696
	ds_read_b128 v[54:57], v88 offset:29712
	v_pk_fma_f32 v[86:87], v[58:59], v[60:61], v[66:67] op_sel:[0,1,0]
	v_pk_fma_f32 v[86:87], v[62:63], v[60:61], v[86:87] op_sel_hi:[1,0,1]
	ds_read_b64 v[58:59], v89 offset:46080
	ds_read_b64 v[60:61], v90 offset:51296
	ds_write_b64 v91, v[86:87] offset:2816
	s_waitcnt lgkmcnt(7)
	v_pk_mul_f32 v[62:63], v[2:3], v[18:19] op_sel_hi:[1,0]
	v_pk_mul_f32 v[64:65], v[4:5], v[18:19] op_sel:[0,1]
	v_pk_mul_f32 v[66:67], v[2:3], v[26:27] op_sel_hi:[1,0]
	v_pk_mul_f32 v[68:69], v[4:5], v[26:27] op_sel:[0,1]
	v_pk_fma_f32 v[62:63], v[6:7], v[20:21], v[62:63] op_sel_hi:[1,0,1]
	v_pk_fma_f32 v[66:67], v[6:7], v[28:29], v[66:67] op_sel_hi:[1,0,1]
	v_pk_fma_f32 v[64:65], v[8:9], v[20:21], v[64:65] op_sel:[0,1,0]
	v_pk_fma_f32 v[68:69], v[8:9], v[28:29], v[68:69] op_sel:[0,1,0]
	v_pk_fma_f32 v[62:63], v[10:11], v[22:23], v[62:63] op_sel_hi:[1,0,1]
	v_pk_fma_f32 v[66:67], v[10:11], v[30:31], v[66:67] op_sel_hi:[1,0,1]
	v_pk_fma_f32 v[64:65], v[12:13], v[22:23], v[64:65] op_sel:[0,1,0]
	v_pk_fma_f32 v[68:69], v[12:13], v[30:31], v[68:69] op_sel:[0,1,0]
	v_pk_fma_f32 v[62:63], v[14:15], v[24:25], v[62:63] op_sel_hi:[1,0,1]
	v_pk_fma_f32 v[66:67], v[14:15], v[32:33], v[66:67] op_sel_hi:[1,0,1]
	v_pk_fma_f32 v[64:65], v[16:17], v[24:25], v[64:65] op_sel:[0,1,0]
	v_pk_fma_f32 v[68:69], v[16:17], v[32:33], v[68:69] op_sel:[0,1,0]
	ds_read_b128 v[18:21], v88 offset:21760
	ds_read_b128 v[22:25], v88 offset:21776
	ds_read_b128 v[26:29], v88 offset:38144
	ds_read_b128 v[30:33], v88 offset:38160
	v_pk_add_f32 v[62:63], v[62:63], v[64:65]
	v_pk_add_f32 v[66:67], v[66:67], v[68:69]
	v_pk_mul_f32 v[70:71], v[2:3], v[34:35] op_sel_hi:[1,0]
	v_pk_mul_f32 v[72:73], v[4:5], v[34:35] op_sel:[0,1]
	v_pk_mul_f32 v[74:75], v[6:7], v[36:37] op_sel_hi:[1,0]
	v_pk_mul_f32 v[76:77], v[8:9], v[36:37] op_sel:[0,1]
	v_pk_mul_f32 v[78:79], v[10:11], v[38:39] op_sel_hi:[1,0]
	v_pk_mul_f32 v[80:81], v[12:13], v[38:39] op_sel:[0,1]
	v_pk_mul_f32 v[82:83], v[14:15], v[40:41] op_sel_hi:[1,0]
	v_pk_mul_f32 v[84:85], v[16:17], v[40:41] op_sel:[0,1]
	ds_read_b128 v[34:37], v88 offset:5376
	ds_read_b128 v[38:41], v88 offset:5392
	v_add_f32_dpp v62, v62, v62 quad_perm:[1,0,3,2] row_mask:0xf bank_mask:0xf bound_ctrl:1
	v_add_f32_dpp v63, v63, v63 quad_perm:[1,0,3,2] row_mask:0xf bank_mask:0xf bound_ctrl:1
	v_add_f32_dpp v66, v66, v66 quad_perm:[1,0,3,2] row_mask:0xf bank_mask:0xf bound_ctrl:1
	v_add_f32_dpp v67, v67, v67 quad_perm:[1,0,3,2] row_mask:0xf bank_mask:0xf bound_ctrl:1
	s_waitcnt lgkmcnt(7)
	v_pk_fma_f32 v[70:71], v[58:59], v[42:43], v[70:71] op_sel_hi:[1,0,1]
	v_pk_fma_f32 v[72:73], v[58:59], v[42:43], v[72:73] op_sel:[0,1,0]
	v_pk_fma_f32 v[74:75], v[58:59], v[44:45], v[74:75] op_sel_hi:[1,0,1]
	v_pk_fma_f32 v[76:77], v[58:59], v[44:45], v[76:77] op_sel:[0,1,0]
	v_add_f32_dpp v62, v62, v62 quad_perm:[2,3,0,1] row_mask:0xf bank_mask:0xf bound_ctrl:1
	v_add_f32_dpp v63, v63, v63 quad_perm:[2,3,0,1] row_mask:0xf bank_mask:0xf bound_ctrl:1
	v_add_f32_dpp v66, v66, v66 quad_perm:[2,3,0,1] row_mask:0xf bank_mask:0xf bound_ctrl:1
	v_add_f32_dpp v67, v67, v67 quad_perm:[2,3,0,1] row_mask:0xf bank_mask:0xf bound_ctrl:1
	v_pk_fma_f32 v[78:79], v[58:59], v[46:47], v[78:79] op_sel_hi:[1,0,1]
	v_pk_fma_f32 v[80:81], v[58:59], v[46:47], v[80:81] op_sel:[0,1,0]
	v_pk_fma_f32 v[82:83], v[58:59], v[48:49], v[82:83] op_sel_hi:[1,0,1]
	v_pk_fma_f32 v[84:85], v[58:59], v[48:49], v[84:85] op_sel:[0,1,0]
	ds_read_b128 v[42:45], v88 offset:13568
	ds_read_b128 v[46:49], v88 offset:13584
	v_add_f32_dpp v62, v62, v62 row_half_mirror row_mask:0xf bank_mask:0xf bound_ctrl:1
	v_add_f32_dpp v63, v63, v63 row_half_mirror row_mask:0xf bank_mask:0xf bound_ctrl:1
	v_add_f32_dpp v66, v66, v66 row_half_mirror row_mask:0xf bank_mask:0xf bound_ctrl:1
	v_add_f32_dpp v67, v67, v67 row_half_mirror row_mask:0xf bank_mask:0xf bound_ctrl:1
	v_pk_fma_f32 v[2:3], v[62:63], v[50:51], v[70:71] op_sel_hi:[1,0,1]
	v_pk_fma_f32 v[4:5], v[62:63], v[50:51], v[72:73] op_sel:[0,1,0]
	v_pk_fma_f32 v[6:7], v[62:63], v[52:53], v[74:75] op_sel_hi:[1,0,1]
	v_pk_fma_f32 v[8:9], v[62:63], v[52:53], v[76:77] op_sel:[0,1,0]
	v_pk_fma_f32 v[10:11], v[62:63], v[54:55], v[78:79] op_sel_hi:[1,0,1]
	v_pk_fma_f32 v[12:13], v[62:63], v[54:55], v[80:81] op_sel:[0,1,0]
	v_pk_fma_f32 v[14:15], v[62:63], v[56:57], v[82:83] op_sel_hi:[1,0,1]
	v_pk_fma_f32 v[16:17], v[62:63], v[56:57], v[84:85] op_sel:[0,1,0]
	ds_read_b128 v[50:53], v88 offset:29952
	ds_read_b128 v[54:57], v88 offset:29968
	v_pk_fma_f32 v[86:87], v[58:59], v[60:61], v[66:67] op_sel:[0,1,0]
	v_pk_fma_f32 v[86:87], v[62:63], v[60:61], v[86:87] op_sel_hi:[1,0,1]
	ds_read_b64 v[58:59], v89 offset:46336
	ds_read_b64 v[60:61], v90 offset:51304
	ds_write_b64 v91, v[86:87] offset:3072
	s_waitcnt lgkmcnt(7)
	v_pk_mul_f32 v[62:63], v[2:3], v[18:19] op_sel_hi:[1,0]
	v_pk_mul_f32 v[64:65], v[4:5], v[18:19] op_sel:[0,1]
	v_pk_mul_f32 v[66:67], v[2:3], v[26:27] op_sel_hi:[1,0]
	v_pk_mul_f32 v[68:69], v[4:5], v[26:27] op_sel:[0,1]
	v_pk_fma_f32 v[62:63], v[6:7], v[20:21], v[62:63] op_sel_hi:[1,0,1]
	v_pk_fma_f32 v[66:67], v[6:7], v[28:29], v[66:67] op_sel_hi:[1,0,1]
	v_pk_fma_f32 v[64:65], v[8:9], v[20:21], v[64:65] op_sel:[0,1,0]
	v_pk_fma_f32 v[68:69], v[8:9], v[28:29], v[68:69] op_sel:[0,1,0]
	v_pk_fma_f32 v[62:63], v[10:11], v[22:23], v[62:63] op_sel_hi:[1,0,1]
	v_pk_fma_f32 v[66:67], v[10:11], v[30:31], v[66:67] op_sel_hi:[1,0,1]
	v_pk_fma_f32 v[64:65], v[12:13], v[22:23], v[64:65] op_sel:[0,1,0]
	v_pk_fma_f32 v[68:69], v[12:13], v[30:31], v[68:69] op_sel:[0,1,0]
	v_pk_fma_f32 v[62:63], v[14:15], v[24:25], v[62:63] op_sel_hi:[1,0,1]
	v_pk_fma_f32 v[66:67], v[14:15], v[32:33], v[66:67] op_sel_hi:[1,0,1]
	v_pk_fma_f32 v[64:65], v[16:17], v[24:25], v[64:65] op_sel:[0,1,0]
	v_pk_fma_f32 v[68:69], v[16:17], v[32:33], v[68:69] op_sel:[0,1,0]
	ds_read_b128 v[18:21], v88 offset:22016
	ds_read_b128 v[22:25], v88 offset:22032
	ds_read_b128 v[26:29], v88 offset:38400
	ds_read_b128 v[30:33], v88 offset:38416
	v_pk_add_f32 v[62:63], v[62:63], v[64:65]
	v_pk_add_f32 v[66:67], v[66:67], v[68:69]
	v_pk_mul_f32 v[70:71], v[2:3], v[34:35] op_sel_hi:[1,0]
	v_pk_mul_f32 v[72:73], v[4:5], v[34:35] op_sel:[0,1]
	v_pk_mul_f32 v[74:75], v[6:7], v[36:37] op_sel_hi:[1,0]
	v_pk_mul_f32 v[76:77], v[8:9], v[36:37] op_sel:[0,1]
	v_pk_mul_f32 v[78:79], v[10:11], v[38:39] op_sel_hi:[1,0]
	v_pk_mul_f32 v[80:81], v[12:13], v[38:39] op_sel:[0,1]
	v_pk_mul_f32 v[82:83], v[14:15], v[40:41] op_sel_hi:[1,0]
	v_pk_mul_f32 v[84:85], v[16:17], v[40:41] op_sel:[0,1]
	ds_read_b128 v[34:37], v88 offset:5632
	ds_read_b128 v[38:41], v88 offset:5648
	v_add_f32_dpp v62, v62, v62 quad_perm:[1,0,3,2] row_mask:0xf bank_mask:0xf bound_ctrl:1
	v_add_f32_dpp v63, v63, v63 quad_perm:[1,0,3,2] row_mask:0xf bank_mask:0xf bound_ctrl:1
	v_add_f32_dpp v66, v66, v66 quad_perm:[1,0,3,2] row_mask:0xf bank_mask:0xf bound_ctrl:1
	v_add_f32_dpp v67, v67, v67 quad_perm:[1,0,3,2] row_mask:0xf bank_mask:0xf bound_ctrl:1
	s_waitcnt lgkmcnt(7)
	v_pk_fma_f32 v[70:71], v[58:59], v[42:43], v[70:71] op_sel_hi:[1,0,1]
	v_pk_fma_f32 v[72:73], v[58:59], v[42:43], v[72:73] op_sel:[0,1,0]
	v_pk_fma_f32 v[74:75], v[58:59], v[44:45], v[74:75] op_sel_hi:[1,0,1]
	v_pk_fma_f32 v[76:77], v[58:59], v[44:45], v[76:77] op_sel:[0,1,0]
	v_add_f32_dpp v62, v62, v62 quad_perm:[2,3,0,1] row_mask:0xf bank_mask:0xf bound_ctrl:1
	v_add_f32_dpp v63, v63, v63 quad_perm:[2,3,0,1] row_mask:0xf bank_mask:0xf bound_ctrl:1
	v_add_f32_dpp v66, v66, v66 quad_perm:[2,3,0,1] row_mask:0xf bank_mask:0xf bound_ctrl:1
	v_add_f32_dpp v67, v67, v67 quad_perm:[2,3,0,1] row_mask:0xf bank_mask:0xf bound_ctrl:1
	v_pk_fma_f32 v[78:79], v[58:59], v[46:47], v[78:79] op_sel_hi:[1,0,1]
	v_pk_fma_f32 v[80:81], v[58:59], v[46:47], v[80:81] op_sel:[0,1,0]
	v_pk_fma_f32 v[82:83], v[58:59], v[48:49], v[82:83] op_sel_hi:[1,0,1]
	v_pk_fma_f32 v[84:85], v[58:59], v[48:49], v[84:85] op_sel:[0,1,0]
	ds_read_b128 v[42:45], v88 offset:13824
	ds_read_b128 v[46:49], v88 offset:13840
	v_add_f32_dpp v62, v62, v62 row_half_mirror row_mask:0xf bank_mask:0xf bound_ctrl:1
	v_add_f32_dpp v63, v63, v63 row_half_mirror row_mask:0xf bank_mask:0xf bound_ctrl:1
	v_add_f32_dpp v66, v66, v66 row_half_mirror row_mask:0xf bank_mask:0xf bound_ctrl:1
	v_add_f32_dpp v67, v67, v67 row_half_mirror row_mask:0xf bank_mask:0xf bound_ctrl:1
	v_pk_fma_f32 v[2:3], v[62:63], v[50:51], v[70:71] op_sel_hi:[1,0,1]
	v_pk_fma_f32 v[4:5], v[62:63], v[50:51], v[72:73] op_sel:[0,1,0]
	v_pk_fma_f32 v[6:7], v[62:63], v[52:53], v[74:75] op_sel_hi:[1,0,1]
	v_pk_fma_f32 v[8:9], v[62:63], v[52:53], v[76:77] op_sel:[0,1,0]
	v_pk_fma_f32 v[10:11], v[62:63], v[54:55], v[78:79] op_sel_hi:[1,0,1]
	v_pk_fma_f32 v[12:13], v[62:63], v[54:55], v[80:81] op_sel:[0,1,0]
	v_pk_fma_f32 v[14:15], v[62:63], v[56:57], v[82:83] op_sel_hi:[1,0,1]
	v_pk_fma_f32 v[16:17], v[62:63], v[56:57], v[84:85] op_sel:[0,1,0]
	ds_read_b128 v[50:53], v88 offset:30208
	ds_read_b128 v[54:57], v88 offset:30224
	v_pk_fma_f32 v[86:87], v[58:59], v[60:61], v[66:67] op_sel:[0,1,0]
	v_pk_fma_f32 v[86:87], v[62:63], v[60:61], v[86:87] op_sel_hi:[1,0,1]
	ds_read_b64 v[58:59], v89 offset:46592
	ds_read_b64 v[60:61], v90 offset:51312
	ds_write_b64 v91, v[86:87] offset:3328
	s_waitcnt lgkmcnt(7)
	v_pk_mul_f32 v[62:63], v[2:3], v[18:19] op_sel_hi:[1,0]
	v_pk_mul_f32 v[64:65], v[4:5], v[18:19] op_sel:[0,1]
	v_pk_mul_f32 v[66:67], v[2:3], v[26:27] op_sel_hi:[1,0]
	v_pk_mul_f32 v[68:69], v[4:5], v[26:27] op_sel:[0,1]
	v_pk_fma_f32 v[62:63], v[6:7], v[20:21], v[62:63] op_sel_hi:[1,0,1]
	v_pk_fma_f32 v[66:67], v[6:7], v[28:29], v[66:67] op_sel_hi:[1,0,1]
	v_pk_fma_f32 v[64:65], v[8:9], v[20:21], v[64:65] op_sel:[0,1,0]
	v_pk_fma_f32 v[68:69], v[8:9], v[28:29], v[68:69] op_sel:[0,1,0]
	v_pk_fma_f32 v[62:63], v[10:11], v[22:23], v[62:63] op_sel_hi:[1,0,1]
	v_pk_fma_f32 v[66:67], v[10:11], v[30:31], v[66:67] op_sel_hi:[1,0,1]
	v_pk_fma_f32 v[64:65], v[12:13], v[22:23], v[64:65] op_sel:[0,1,0]
	v_pk_fma_f32 v[68:69], v[12:13], v[30:31], v[68:69] op_sel:[0,1,0]
	v_pk_fma_f32 v[62:63], v[14:15], v[24:25], v[62:63] op_sel_hi:[1,0,1]
	v_pk_fma_f32 v[66:67], v[14:15], v[32:33], v[66:67] op_sel_hi:[1,0,1]
	v_pk_fma_f32 v[64:65], v[16:17], v[24:25], v[64:65] op_sel:[0,1,0]
	v_pk_fma_f32 v[68:69], v[16:17], v[32:33], v[68:69] op_sel:[0,1,0]
	ds_read_b128 v[18:21], v88 offset:22272
	ds_read_b128 v[22:25], v88 offset:22288
	ds_read_b128 v[26:29], v88 offset:38656
	ds_read_b128 v[30:33], v88 offset:38672
	v_pk_add_f32 v[62:63], v[62:63], v[64:65]
	v_pk_add_f32 v[66:67], v[66:67], v[68:69]
	v_pk_mul_f32 v[70:71], v[2:3], v[34:35] op_sel_hi:[1,0]
	v_pk_mul_f32 v[72:73], v[4:5], v[34:35] op_sel:[0,1]
	v_pk_mul_f32 v[74:75], v[6:7], v[36:37] op_sel_hi:[1,0]
	v_pk_mul_f32 v[76:77], v[8:9], v[36:37] op_sel:[0,1]
	v_pk_mul_f32 v[78:79], v[10:11], v[38:39] op_sel_hi:[1,0]
	v_pk_mul_f32 v[80:81], v[12:13], v[38:39] op_sel:[0,1]
	v_pk_mul_f32 v[82:83], v[14:15], v[40:41] op_sel_hi:[1,0]
	v_pk_mul_f32 v[84:85], v[16:17], v[40:41] op_sel:[0,1]
	ds_read_b128 v[34:37], v88 offset:5888
	ds_read_b128 v[38:41], v88 offset:5904
	v_add_f32_dpp v62, v62, v62 quad_perm:[1,0,3,2] row_mask:0xf bank_mask:0xf bound_ctrl:1
	v_add_f32_dpp v63, v63, v63 quad_perm:[1,0,3,2] row_mask:0xf bank_mask:0xf bound_ctrl:1
	v_add_f32_dpp v66, v66, v66 quad_perm:[1,0,3,2] row_mask:0xf bank_mask:0xf bound_ctrl:1
	v_add_f32_dpp v67, v67, v67 quad_perm:[1,0,3,2] row_mask:0xf bank_mask:0xf bound_ctrl:1
	s_waitcnt lgkmcnt(7)
	v_pk_fma_f32 v[70:71], v[58:59], v[42:43], v[70:71] op_sel_hi:[1,0,1]
	v_pk_fma_f32 v[72:73], v[58:59], v[42:43], v[72:73] op_sel:[0,1,0]
	v_pk_fma_f32 v[74:75], v[58:59], v[44:45], v[74:75] op_sel_hi:[1,0,1]
	v_pk_fma_f32 v[76:77], v[58:59], v[44:45], v[76:77] op_sel:[0,1,0]
	v_add_f32_dpp v62, v62, v62 quad_perm:[2,3,0,1] row_mask:0xf bank_mask:0xf bound_ctrl:1
	v_add_f32_dpp v63, v63, v63 quad_perm:[2,3,0,1] row_mask:0xf bank_mask:0xf bound_ctrl:1
	v_add_f32_dpp v66, v66, v66 quad_perm:[2,3,0,1] row_mask:0xf bank_mask:0xf bound_ctrl:1
	v_add_f32_dpp v67, v67, v67 quad_perm:[2,3,0,1] row_mask:0xf bank_mask:0xf bound_ctrl:1
	v_pk_fma_f32 v[78:79], v[58:59], v[46:47], v[78:79] op_sel_hi:[1,0,1]
	v_pk_fma_f32 v[80:81], v[58:59], v[46:47], v[80:81] op_sel:[0,1,0]
	v_pk_fma_f32 v[82:83], v[58:59], v[48:49], v[82:83] op_sel_hi:[1,0,1]
	v_pk_fma_f32 v[84:85], v[58:59], v[48:49], v[84:85] op_sel:[0,1,0]
	ds_read_b128 v[42:45], v88 offset:14080
	ds_read_b128 v[46:49], v88 offset:14096
	v_add_f32_dpp v62, v62, v62 row_half_mirror row_mask:0xf bank_mask:0xf bound_ctrl:1
	v_add_f32_dpp v63, v63, v63 row_half_mirror row_mask:0xf bank_mask:0xf bound_ctrl:1
	v_add_f32_dpp v66, v66, v66 row_half_mirror row_mask:0xf bank_mask:0xf bound_ctrl:1
	v_add_f32_dpp v67, v67, v67 row_half_mirror row_mask:0xf bank_mask:0xf bound_ctrl:1
	v_pk_fma_f32 v[2:3], v[62:63], v[50:51], v[70:71] op_sel_hi:[1,0,1]
	v_pk_fma_f32 v[4:5], v[62:63], v[50:51], v[72:73] op_sel:[0,1,0]
	v_pk_fma_f32 v[6:7], v[62:63], v[52:53], v[74:75] op_sel_hi:[1,0,1]
	v_pk_fma_f32 v[8:9], v[62:63], v[52:53], v[76:77] op_sel:[0,1,0]
	v_pk_fma_f32 v[10:11], v[62:63], v[54:55], v[78:79] op_sel_hi:[1,0,1]
	v_pk_fma_f32 v[12:13], v[62:63], v[54:55], v[80:81] op_sel:[0,1,0]
	v_pk_fma_f32 v[14:15], v[62:63], v[56:57], v[82:83] op_sel_hi:[1,0,1]
	v_pk_fma_f32 v[16:17], v[62:63], v[56:57], v[84:85] op_sel:[0,1,0]
	ds_read_b128 v[50:53], v88 offset:30464
	ds_read_b128 v[54:57], v88 offset:30480
	v_pk_fma_f32 v[86:87], v[58:59], v[60:61], v[66:67] op_sel:[0,1,0]
	v_pk_fma_f32 v[86:87], v[62:63], v[60:61], v[86:87] op_sel_hi:[1,0,1]
	ds_read_b64 v[58:59], v89 offset:46848
	ds_read_b64 v[60:61], v90 offset:51320
	ds_write_b64 v91, v[86:87] offset:3584
	s_waitcnt lgkmcnt(7)
	v_pk_mul_f32 v[62:63], v[2:3], v[18:19] op_sel_hi:[1,0]
	v_pk_mul_f32 v[64:65], v[4:5], v[18:19] op_sel:[0,1]
	v_pk_mul_f32 v[66:67], v[2:3], v[26:27] op_sel_hi:[1,0]
	v_pk_mul_f32 v[68:69], v[4:5], v[26:27] op_sel:[0,1]
	v_pk_fma_f32 v[62:63], v[6:7], v[20:21], v[62:63] op_sel_hi:[1,0,1]
	v_pk_fma_f32 v[66:67], v[6:7], v[28:29], v[66:67] op_sel_hi:[1,0,1]
	v_pk_fma_f32 v[64:65], v[8:9], v[20:21], v[64:65] op_sel:[0,1,0]
	v_pk_fma_f32 v[68:69], v[8:9], v[28:29], v[68:69] op_sel:[0,1,0]
	v_pk_fma_f32 v[62:63], v[10:11], v[22:23], v[62:63] op_sel_hi:[1,0,1]
	v_pk_fma_f32 v[66:67], v[10:11], v[30:31], v[66:67] op_sel_hi:[1,0,1]
	v_pk_fma_f32 v[64:65], v[12:13], v[22:23], v[64:65] op_sel:[0,1,0]
	v_pk_fma_f32 v[68:69], v[12:13], v[30:31], v[68:69] op_sel:[0,1,0]
	v_pk_fma_f32 v[62:63], v[14:15], v[24:25], v[62:63] op_sel_hi:[1,0,1]
	v_pk_fma_f32 v[66:67], v[14:15], v[32:33], v[66:67] op_sel_hi:[1,0,1]
	v_pk_fma_f32 v[64:65], v[16:17], v[24:25], v[64:65] op_sel:[0,1,0]
	v_pk_fma_f32 v[68:69], v[16:17], v[32:33], v[68:69] op_sel:[0,1,0]
	v_add_u32_e32 v88, s48, v88
	ds_read_b128 v[18:21], v88 offset:18432
	ds_read_b128 v[22:25], v88 offset:18448
	ds_read_b128 v[26:29], v88 offset:34816
	ds_read_b128 v[30:33], v88 offset:34832
	v_pk_add_f32 v[62:63], v[62:63], v[64:65]
	v_pk_add_f32 v[66:67], v[66:67], v[68:69]
	v_pk_mul_f32 v[70:71], v[2:3], v[34:35] op_sel_hi:[1,0]
	v_pk_mul_f32 v[72:73], v[4:5], v[34:35] op_sel:[0,1]
	v_pk_mul_f32 v[74:75], v[6:7], v[36:37] op_sel_hi:[1,0]
	v_pk_mul_f32 v[76:77], v[8:9], v[36:37] op_sel:[0,1]
	v_pk_mul_f32 v[78:79], v[10:11], v[38:39] op_sel_hi:[1,0]
	v_pk_mul_f32 v[80:81], v[12:13], v[38:39] op_sel:[0,1]
	v_pk_mul_f32 v[82:83], v[14:15], v[40:41] op_sel_hi:[1,0]
	v_pk_mul_f32 v[84:85], v[16:17], v[40:41] op_sel:[0,1]
	ds_read_b128 v[34:37], v88 offset:2048
	ds_read_b128 v[38:41], v88 offset:2064
	v_add_f32_dpp v62, v62, v62 quad_perm:[1,0,3,2] row_mask:0xf bank_mask:0xf bound_ctrl:1
	v_add_f32_dpp v63, v63, v63 quad_perm:[1,0,3,2] row_mask:0xf bank_mask:0xf bound_ctrl:1
	v_add_f32_dpp v66, v66, v66 quad_perm:[1,0,3,2] row_mask:0xf bank_mask:0xf bound_ctrl:1
	v_add_f32_dpp v67, v67, v67 quad_perm:[1,0,3,2] row_mask:0xf bank_mask:0xf bound_ctrl:1
	s_waitcnt lgkmcnt(7)
	v_pk_fma_f32 v[70:71], v[58:59], v[42:43], v[70:71] op_sel_hi:[1,0,1]
	v_pk_fma_f32 v[72:73], v[58:59], v[42:43], v[72:73] op_sel:[0,1,0]
	v_pk_fma_f32 v[74:75], v[58:59], v[44:45], v[74:75] op_sel_hi:[1,0,1]
	v_pk_fma_f32 v[76:77], v[58:59], v[44:45], v[76:77] op_sel:[0,1,0]
	v_add_f32_dpp v62, v62, v62 quad_perm:[2,3,0,1] row_mask:0xf bank_mask:0xf bound_ctrl:1
	v_add_f32_dpp v63, v63, v63 quad_perm:[2,3,0,1] row_mask:0xf bank_mask:0xf bound_ctrl:1
	v_add_f32_dpp v66, v66, v66 quad_perm:[2,3,0,1] row_mask:0xf bank_mask:0xf bound_ctrl:1
	v_add_f32_dpp v67, v67, v67 quad_perm:[2,3,0,1] row_mask:0xf bank_mask:0xf bound_ctrl:1
	v_pk_fma_f32 v[78:79], v[58:59], v[46:47], v[78:79] op_sel_hi:[1,0,1]
	v_pk_fma_f32 v[80:81], v[58:59], v[46:47], v[80:81] op_sel:[0,1,0]
	v_pk_fma_f32 v[82:83], v[58:59], v[48:49], v[82:83] op_sel_hi:[1,0,1]
	v_pk_fma_f32 v[84:85], v[58:59], v[48:49], v[84:85] op_sel:[0,1,0]
	ds_read_b128 v[42:45], v88 offset:10240
	ds_read_b128 v[46:49], v88 offset:10256
	v_add_f32_dpp v62, v62, v62 row_half_mirror row_mask:0xf bank_mask:0xf bound_ctrl:1
	v_add_f32_dpp v63, v63, v63 row_half_mirror row_mask:0xf bank_mask:0xf bound_ctrl:1
	v_add_f32_dpp v66, v66, v66 row_half_mirror row_mask:0xf bank_mask:0xf bound_ctrl:1
	v_add_f32_dpp v67, v67, v67 row_half_mirror row_mask:0xf bank_mask:0xf bound_ctrl:1
	v_add_u32_e32 v89, s48, v89
	v_pk_fma_f32 v[2:3], v[62:63], v[50:51], v[70:71] op_sel_hi:[1,0,1]
	v_pk_fma_f32 v[4:5], v[62:63], v[50:51], v[72:73] op_sel:[0,1,0]
	v_pk_fma_f32 v[6:7], v[62:63], v[52:53], v[74:75] op_sel_hi:[1,0,1]
	v_pk_fma_f32 v[8:9], v[62:63], v[52:53], v[76:77] op_sel:[0,1,0]
	v_pk_fma_f32 v[10:11], v[62:63], v[54:55], v[78:79] op_sel_hi:[1,0,1]
	v_pk_fma_f32 v[12:13], v[62:63], v[54:55], v[80:81] op_sel:[0,1,0]
	v_pk_fma_f32 v[14:15], v[62:63], v[56:57], v[82:83] op_sel_hi:[1,0,1]
	v_pk_fma_f32 v[16:17], v[62:63], v[56:57], v[84:85] op_sel:[0,1,0]
	ds_read_b128 v[50:53], v88 offset:26624
	ds_read_b128 v[54:57], v88 offset:26640
	v_pk_fma_f32 v[86:87], v[58:59], v[60:61], v[66:67] op_sel:[0,1,0]
	v_pk_fma_f32 v[86:87], v[62:63], v[60:61], v[86:87] op_sel_hi:[1,0,1]
	v_add_u32_e32 v90, s49, v90
	ds_read_b64 v[58:59], v89 offset:43008
	ds_read_b64 v[60:61], v90 offset:51200
	ds_write_b64 v91, v[86:87] offset:3840
	v_add_u32_e32 v91, s48, v91
	s_sub_u32 s100, s100, 1
	s_cmp_lg_u32 s100, 0
	s_cbranch_scc1 .Lrec_fwd_loop
	s_branch .Lrec0_ret
.Lrec_bwd:
	s_add_i32 s48, s101, 4096
	s_add_i32 s49, s101, 128
	s_add_i32 s100, s100, 4096
	v_add_u32_e32 v88, s48, v92
	v_add_u32_e32 v89, s48, v93
	v_mov_b32_e32 v90, s49
	v_add_u32_e32 v91, s100, v93
	ds_read_b128 v[18:21], v88 offset:22272
	ds_read_b128 v[22:25], v88 offset:22288
	ds_read_b128 v[26:29], v88 offset:38656
	ds_read_b128 v[30:33], v88 offset:38672
	ds_read_b128 v[34:37], v88 offset:5888
	ds_read_b128 v[38:41], v88 offset:5904
	ds_read_b128 v[42:45], v88 offset:14080
	ds_read_b128 v[46:49], v88 offset:14096
	ds_read_b128 v[50:53], v88 offset:30464
	ds_read_b128 v[54:57], v88 offset:30480
	ds_read_b64 v[58:59], v89 offset:46848
	ds_read_b64 v[60:61], v90 offset:51320
	s_movk_i32 s48, -4096
	s_movk_i32 s49, -128
	s_movk_i32 s100, 2
.Lrec_bwd_loop:
	s_waitcnt lgkmcnt(6)
	v_pk_mul_f32 v[62:63], v[2:3], v[18:19] op_sel_hi:[1,0]
	v_pk_mul_f32 v[64:65], v[4:5], v[18:19] op_sel:[0,1]
	v_pk_mul_f32 v[66:67], v[2:3], v[26:27] op_sel_hi:[1,0]
	v_pk_mul_f32 v[68:69], v[4:5], v[26:27] op_sel:[0,1]
	v_pk_fma_f32 v[62:63], v[6:7], v[20:21], v[62:63] op_sel_hi:[1,0,1]
	v_pk_fma_f32 v[66:67], v[6:7], v[28:29], v[66:67] op_sel_hi:[1,0,1]
	v_pk_fma_f32 v[64:65], v[8:9], v[20:21], v[64:65] op_sel:[0,1,0]
	v_pk_fma_f32 v[68:69], v[8:9], v[28:29], v[68:69] op_sel:[0,1,0]
	v_pk_fma_f32 v[62:63], v[10:11], v[22:23], v[62:63] op_sel_hi:[1,0,1]
	v_pk_fma_f32 v[66:67], v[10:11], v[30:31], v[66:67] op_sel_hi:[1,0,1]
	v_pk_fma_f32 v[64:65], v[12:13], v[22:23], v[64:65] op_sel:[0,1,0]
	v_pk_fma_f32 v[68:69], v[12:13], v[30:31], v[68:69] op_sel:[0,1,0]
	v_pk_fma_f32 v[62:63], v[14:15], v[24:25], v[62:63] op_sel_hi:[1,0,1]
	v_pk_fma_f32 v[66:67], v[14:15], v[32:33], v[66:67] op_sel_hi:[1,0,1]
	v_pk_fma_f32 v[64:65], v[16:17], v[24:25], v[64:65] op_sel:[0,1,0]
	v_pk_fma_f32 v[68:69], v[16:17], v[32:33], v[68:69] op_sel:[0,1,0]
	ds_read_b128 v[18:21], v88 offset:22016
	ds_read_b128 v[22:25], v88 offset:22032
	ds_read_b128 v[26:29], v88 offset:38400
	ds_read_b128 v[30:33], v88 offset:38416
	v_pk_add_f32 v[62:63], v[62:63], v[64:65]
	v_pk_add_f32 v[66:67], v[66:67], v[68:69]
	v_pk_mul_f32 v[70:71], v[2:3], v[34:35] op_sel_hi:[1,0]
	v_pk_mul_f32 v[72:73], v[4:5], v[34:35] op_sel:[0,1]
	v_pk_mul_f32 v[74:75], v[6:7], v[36:37] op_sel_hi:[1,0]
	v_pk_mul_f32 v[76:77], v[8:9], v[36:37] op_sel:[0,1]
	v_pk_mul_f32 v[78:79], v[10:11], v[38:39] op_sel_hi:[1,0]
	v_pk_mul_f32 v[80:81], v[12:13], v[38:39] op_sel:[0,1]
	v_pk_mul_f32 v[82:83], v[14:15], v[40:41] op_sel_hi:[1,0]
	v_pk_mul_f32 v[84:85], v[16:17], v[40:41] op_sel:[0,1]
	ds_read_b128 v[34:37], v88 offset:5632
	ds_read_b128 v[38:41], v88 offset:5648
	v_add_f32_dpp v62, v62, v62 quad_perm:[1,0,3,2] row_mask:0xf bank_mask:0xf bound_ctrl:1
	v_add_f32_dpp v63, v63, v63 quad_perm:[1,0,3,2] row_mask:0xf bank_mask:0xf bound_ctrl:1
	v_add_f32_dpp v66, v66, v66 quad_perm:[1,0,3,2] row_mask:0xf bank_mask:0xf bound_ctrl:1
	v_add_f32_dpp v67, v67, v67 quad_perm:[1,0,3,2] row_mask:0xf bank_mask:0xf bound_ctrl:1
	s_waitcnt lgkmcnt(6)
	v_pk_fma_f32 v[70:71], v[58:59], v[42:43], v[70:71] op_sel_hi:[1,0,1]
	v_pk_fma_f32 v[72:73], v[58:59], v[42:43], v[72:73] op_sel:[0,1,0]
	v_pk_fma_f32 v[74:75], v[58:59], v[44:45], v[74:75] op_sel_hi:[1,0,1]
	v_pk_fma_f32 v[76:77], v[58:59], v[44:45], v[76:77] op_sel:[0,1,0]
	v_add_f32_dpp v62, v62, v62 quad_perm:[2,3,0,1] row_mask:0xf bank_mask:0xf bound_ctrl:1
	v_add_f32_dpp v63, v63, v63 quad_perm:[2,3,0,1] row_mask:0xf bank_mask:0xf bound_ctrl:1
	v_add_f32_dpp v66, v66, v66 quad_perm:[2,3,0,1] row_mask:0xf bank_mask:0xf bound_ctrl:1
	v_add_f32_dpp v67, v67, v67 quad_perm:[2,3,0,1] row_mask:0xf bank_mask:0xf bound_ctrl:1
	v_pk_fma_f32 v[78:79], v[58:59], v[46:47], v[78:79] op_sel_hi:[1,0,1]
	v_pk_fma_f32 v[80:81], v[58:59], v[46:47], v[80:81] op_sel:[0,1,0]
	v_pk_fma_f32 v[82:83], v[58:59], v[48:49], v[82:83] op_sel_hi:[1,0,1]
	v_pk_fma_f32 v[84:85], v[58:59], v[48:49], v[84:85] op_sel:[0,1,0]
	ds_read_b128 v[42:45], v88 offset:13824
	ds_read_b128 v[46:49], v88 offset:13840
	v_add_f32_dpp v62, v62, v62 row_half_mirror row_mask:0xf bank_mask:0xf bound_ctrl:1
	v_add_f32_dpp v63, v63, v63 row_half_mirror row_mask:0xf bank_mask:0xf bound_ctrl:1
	v_add_f32_dpp v66, v66, v66 row_half_mirror row_mask:0xf bank_mask:0xf bound_ctrl:1
	v_add_f32_dpp v67, v67, v67 row_half_mirror row_mask:0xf bank_mask:0xf bound_ctrl:1
	v_pk_fma_f32 v[2:3], v[62:63], v[50:51], v[70:71] op_sel_hi:[1,0,1]
	v_pk_fma_f32 v[4:5], v[62:63], v[50:51], v[72:73] op_sel:[0,1,0]
	v_pk_fma_f32 v[6:7], v[62:63], v[52:53], v[74:75] op_sel_hi:[1,0,1]
	v_pk_fma_f32 v[8:9], v[62:63], v[52:53], v[76:77] op_sel:[0,1,0]
	v_pk_fma_f32 v[10:11], v[62:63], v[54:55], v[78:79] op_sel_hi:[1,0,1]
	v_pk_fma_f32 v[12:13], v[62:63], v[54:55], v[80:81] op_sel:[0,1,0]
	v_pk_fma_f32 v[14:15], v[62:63], v[56:57], v[82:83] op_sel_hi:[1,0,1]
	v_pk_fma_f32 v[16:17], v[62:63], v[56:57], v[84:85] op_sel:[0,1,0]
	ds_read_b128 v[50:53], v88 offset:30208
	ds_read_b128 v[54:57], v88 offset:30224
	v_pk_fma_f32 v[86:87], v[58:59], v[60:61], v[66:67] op_sel:[0,1,0]
	v_pk_fma_f32 v[86:87], v[62:63], v[60:61], v[86:87] op_sel_hi:[1,0,1]
	ds_read_b64 v[58:59], v89 offset:46592
	ds_read_b64 v[60:61], v90 offset:51312
	ds_write_b64 v91, v[86:87] offset:3840
	s_waitcnt lgkmcnt(7)
	v_pk_mul_f32 v[62:63], v[2:3], v[18:19] op_sel_hi:[1,0]
	v_pk_mul_f32 v[64:65], v[4:5], v[18:19] op_sel:[0,1]
	v_pk_mul_f32 v[66:67], v[2:3], v[26:27] op_sel_hi:[1,0]
	v_pk_mul_f32 v[68:69], v[4:5], v[26:27] op_sel:[0,1]
	v_pk_fma_f32 v[62:63], v[6:7], v[20:21], v[62:63] op_sel_hi:[1,0,1]
	v_pk_fma_f32 v[66:67], v[6:7], v[28:29], v[66:67] op_sel_hi:[1,0,1]
	v_pk_fma_f32 v[64:65], v[8:9], v[20:21], v[64:65] op_sel:[0,1,0]
	v_pk_fma_f32 v[68:69], v[8:9], v[28:29], v[68:69] op_sel:[0,1,0]
	v_pk_fma_f32 v[62:63], v[10:11], v[22:23], v[62:63] op_sel_hi:[1,0,1]
	v_pk_fma_f32 v[66:67], v[10:11], v[30:31], v[66:67] op_sel_hi:[1,0,1]
	v_pk_fma_f32 v[64:65], v[12:13], v[22:23], v[64:65] op_sel:[0,1,0]
	v_pk_fma_f32 v[68:69], v[12:13], v[30:31], v[68:69] op_sel:[0,1,0]
	v_pk_fma_f32 v[62:63], v[14:15], v[24:25], v[62:63] op_sel_hi:[1,0,1]
	v_pk_fma_f32 v[66:67], v[14:15], v[32:33], v[66:67] op_sel_hi:[1,0,1]
	v_pk_fma_f32 v[64:65], v[16:17], v[24:25], v[64:65] op_sel:[0,1,0]
	v_pk_fma_f32 v[68:69], v[16:17], v[32:33], v[68:69] op_sel:[0,1,0]
	ds_read_b128 v[18:21], v88 offset:21760
	ds_read_b128 v[22:25], v88 offset:21776
	ds_read_b128 v[26:29], v88 offset:38144
	ds_read_b128 v[30:33], v88 offset:38160
	v_pk_add_f32 v[62:63], v[62:63], v[64:65]
	v_pk_add_f32 v[66:67], v[66:67], v[68:69]
	v_pk_mul_f32 v[70:71], v[2:3], v[34:35] op_sel_hi:[1,0]
	v_pk_mul_f32 v[72:73], v[4:5], v[34:35] op_sel:[0,1]
	v_pk_mul_f32 v[74:75], v[6:7], v[36:37] op_sel_hi:[1,0]
	v_pk_mul_f32 v[76:77], v[8:9], v[36:37] op_sel:[0,1]
	v_pk_mul_f32 v[78:79], v[10:11], v[38:39] op_sel_hi:[1,0]
	v_pk_mul_f32 v[80:81], v[12:13], v[38:39] op_sel:[0,1]
	v_pk_mul_f32 v[82:83], v[14:15], v[40:41] op_sel_hi:[1,0]
	v_pk_mul_f32 v[84:85], v[16:17], v[40:41] op_sel:[0,1]
	ds_read_b128 v[34:37], v88 offset:5376
	ds_read_b128 v[38:41], v88 offset:5392
	v_add_f32_dpp v62, v62, v62 quad_perm:[1,0,3,2] row_mask:0xf bank_mask:0xf bound_ctrl:1
	v_add_f32_dpp v63, v63, v63 quad_perm:[1,0,3,2] row_mask:0xf bank_mask:0xf bound_ctrl:1
	v_add_f32_dpp v66, v66, v66 quad_perm:[1,0,3,2] row_mask:0xf bank_mask:0xf bound_ctrl:1
	v_add_f32_dpp v67, v67, v67 quad_perm:[1,0,3,2] row_mask:0xf bank_mask:0xf bound_ctrl:1
	s_waitcnt lgkmcnt(7)
	v_pk_fma_f32 v[70:71], v[58:59], v[42:43], v[70:71] op_sel_hi:[1,0,1]
	v_pk_fma_f32 v[72:73], v[58:59], v[42:43], v[72:73] op_sel:[0,1,0]
	v_pk_fma_f32 v[74:75], v[58:59], v[44:45], v[74:75] op_sel_hi:[1,0,1]
	v_pk_fma_f32 v[76:77], v[58:59], v[44:45], v[76:77] op_sel:[0,1,0]
	v_add_f32_dpp v62, v62, v62 quad_perm:[2,3,0,1] row_mask:0xf bank_mask:0xf bound_ctrl:1
	v_add_f32_dpp v63, v63, v63 quad_perm:[2,3,0,1] row_mask:0xf bank_mask:0xf bound_ctrl:1
	v_add_f32_dpp v66, v66, v66 quad_perm:[2,3,0,1] row_mask:0xf bank_mask:0xf bound_ctrl:1
	v_add_f32_dpp v67, v67, v67 quad_perm:[2,3,0,1] row_mask:0xf bank_mask:0xf bound_ctrl:1
	v_pk_fma_f32 v[78:79], v[58:59], v[46:47], v[78:79] op_sel_hi:[1,0,1]
	v_pk_fma_f32 v[80:81], v[58:59], v[46:47], v[80:81] op_sel:[0,1,0]
	v_pk_fma_f32 v[82:83], v[58:59], v[48:49], v[82:83] op_sel_hi:[1,0,1]
	v_pk_fma_f32 v[84:85], v[58:59], v[48:49], v[84:85] op_sel:[0,1,0]
	ds_read_b128 v[42:45], v88 offset:13568
	ds_read_b128 v[46:49], v88 offset:13584
	v_add_f32_dpp v62, v62, v62 row_half_mirror row_mask:0xf bank_mask:0xf bound_ctrl:1
	v_add_f32_dpp v63, v63, v63 row_half_mirror row_mask:0xf bank_mask:0xf bound_ctrl:1
	v_add_f32_dpp v66, v66, v66 row_half_mirror row_mask:0xf bank_mask:0xf bound_ctrl:1
	v_add_f32_dpp v67, v67, v67 row_half_mirror row_mask:0xf bank_mask:0xf bound_ctrl:1
	v_pk_fma_f32 v[2:3], v[62:63], v[50:51], v[70:71] op_sel_hi:[1,0,1]
	v_pk_fma_f32 v[4:5], v[62:63], v[50:51], v[72:73] op_sel:[0,1,0]
	v_pk_fma_f32 v[6:7], v[62:63], v[52:53], v[74:75] op_sel_hi:[1,0,1]
	v_pk_fma_f32 v[8:9], v[62:63], v[52:53], v[76:77] op_sel:[0,1,0]
	v_pk_fma_f32 v[10:11], v[62:63], v[54:55], v[78:79] op_sel_hi:[1,0,1]
	v_pk_fma_f32 v[12:13], v[62:63], v[54:55], v[80:81] op_sel:[0,1,0]
	v_pk_fma_f32 v[14:15], v[62:63], v[56:57], v[82:83] op_sel_hi:[1,0,1]
	v_pk_fma_f32 v[16:17], v[62:63], v[56:57], v[84:85] op_sel:[0,1,0]
	ds_read_b128 v[50:53], v88 offset:29952
	ds_read_b128 v[54:57], v88 offset:29968
	v_pk_fma_f32 v[86:87], v[58:59], v[60:61], v[66:67] op_sel:[0,1,0]
	v_pk_fma_f32 v[86:87], v[62:63], v[60:61], v[86:87] op_sel_hi:[1,0,1]
	ds_read_b64 v[58:59], v89 offset:46336
	ds_read_b64 v[60:61], v90 offset:51304
	ds_write_b64 v91, v[86:87] offset:3584
	s_waitcnt lgkmcnt(7)
	v_pk_mul_f32 v[62:63], v[2:3], v[18:19] op_sel_hi:[1,0]
	v_pk_mul_f32 v[64:65], v[4:5], v[18:19] op_sel:[0,1]
	v_pk_mul_f32 v[66:67], v[2:3], v[26:27] op_sel_hi:[1,0]
	v_pk_mul_f32 v[68:69], v[4:5], v[26:27] op_sel:[0,1]
	v_pk_fma_f32 v[62:63], v[6:7], v[20:21], v[62:63] op_sel_hi:[1,0,1]
	v_pk_fma_f32 v[66:67], v[6:7], v[28:29], v[66:67] op_sel_hi:[1,0,1]
	v_pk_fma_f32 v[64:65], v[8:9], v[20:21], v[64:65] op_sel:[0,1,0]
	v_pk_fma_f32 v[68:69], v[8:9], v[28:29], v[68:69] op_sel:[0,1,0]
	v_pk_fma_f32 v[62:63], v[10:11], v[22:23], v[62:63] op_sel_hi:[1,0,1]
	v_pk_fma_f32 v[66:67], v[10:11], v[30:31], v[66:67] op_sel_hi:[1,0,1]
	v_pk_fma_f32 v[64:65], v[12:13], v[22:23], v[64:65] op_sel:[0,1,0]
	v_pk_fma_f32 v[68:69], v[12:13], v[30:31], v[68:69] op_sel:[0,1,0]
	v_pk_fma_f32 v[62:63], v[14:15], v[24:25], v[62:63] op_sel_hi:[1,0,1]
	v_pk_fma_f32 v[66:67], v[14:15], v[32:33], v[66:67] op_sel_hi:[1,0,1]
	v_pk_fma_f32 v[64:65], v[16:17], v[24:25], v[64:65] op_sel:[0,1,0]
	v_pk_fma_f32 v[68:69], v[16:17], v[32:33], v[68:69] op_sel:[0,1,0]
	ds_read_b128 v[18:21], v88 offset:21504
	ds_read_b128 v[22:25], v88 offset:21520
	ds_read_b128 v[26:29], v88 offset:37888
	ds_read_b128 v[30:33], v88 offset:37904
	v_pk_add_f32 v[62:63], v[62:63], v[64:65]
	v_pk_add_f32 v[66:67], v[66:67], v[68:69]
	v_pk_mul_f32 v[70:71], v[2:3], v[34:35] op_sel_hi:[1,0]
	v_pk_mul_f32 v[72:73], v[4:5], v[34:35] op_sel:[0,1]
	v_pk_mul_f32 v[74:75], v[6:7], v[36:37] op_sel_hi:[1,0]
	v_pk_mul_f32 v[76:77], v[8:9], v[36:37] op_sel:[0,1]
	v_pk_mul_f32 v[78:79], v[10:11], v[38:39] op_sel_hi:[1,0]
	v_pk_mul_f32 v[80:81], v[12:13], v[38:39] op_sel:[0,1]
	v_pk_mul_f32 v[82:83], v[14:15], v[40:41] op_sel_hi:[1,0]
	v_pk_mul_f32 v[84:85], v[16:17], v[40:41] op_sel:[0,1]
	ds_read_b128 v[34:37], v88 offset:5120
	ds_read_b128 v[38:41], v88 offset:5136
	v_add_f32_dpp v62, v62, v62 quad_perm:[1,0,3,2] row_mask:0xf bank_mask:0xf bound_ctrl:1
	v_add_f32_dpp v63, v63, v63 quad_perm:[1,0,3,2] row_mask:0xf bank_mask:0xf bound_ctrl:1
	v_add_f32_dpp v66, v66, v66 quad_perm:[1,0,3,2] row_mask:0xf bank_mask:0xf bound_ctrl:1
	v_add_f32_dpp v67, v67, v67 quad_perm:[1,0,3,2] row_mask:0xf bank_mask:0xf bound_ctrl:1
	s_waitcnt lgkmcnt(7)
	v_pk_fma_f32 v[70:71], v[58:59], v[42:43], v[70:71] op_sel_hi:[1,0,1]
	v_pk_fma_f32 v[72:73], v[58:59], v[42:43], v[72:73] op_sel:[0,1,0]
	v_pk_fma_f32 v[74:75], v[58:59], v[44:45], v[74:75] op_sel_hi:[1,0,1]
	v_pk_fma_f32 v[76:77], v[58:59], v[44:45], v[76:77] op_sel:[0,1,0]
	v_add_f32_dpp v62, v62, v62 quad_perm:[2,3,0,1] row_mask:0xf bank_mask:0xf bound_ctrl:1
	v_add_f32_dpp v63, v63, v63 quad_perm:[2,3,0,1] row_mask:0xf bank_mask:0xf bound_ctrl:1
	v_add_f32_dpp v66, v66, v66 quad_perm:[2,3,0,1] row_mask:0xf bank_mask:0xf bound_ctrl:1
	v_add_f32_dpp v67, v67, v67 quad_perm:[2,3,0,1] row_mask:0xf bank_mask:0xf bound_ctrl:1
	v_pk_fma_f32 v[78:79], v[58:59], v[46:47], v[78:79] op_sel_hi:[1,0,1]
	v_pk_fma_f32 v[80:81], v[58:59], v[46:47], v[80:81] op_sel:[0,1,0]
	v_pk_fma_f32 v[82:83], v[58:59], v[48:49], v[82:83] op_sel_hi:[1,0,1]
	v_pk_fma_f32 v[84:85], v[58:59], v[48:49], v[84:85] op_sel:[0,1,0]
	ds_read_b128 v[42:45], v88 offset:13312
	ds_read_b128 v[46:49], v88 offset:13328
	v_add_f32_dpp v62, v62, v62 row_half_mirror row_mask:0xf bank_mask:0xf bound_ctrl:1
	v_add_f32_dpp v63, v63, v63 row_half_mirror row_mask:0xf bank_mask:0xf bound_ctrl:1
	v_add_f32_dpp v66, v66, v66 row_half_mirror row_mask:0xf bank_mask:0xf bound_ctrl:1
	v_add_f32_dpp v67, v67, v67 row_half_mirror row_mask:0xf bank_mask:0xf bound_ctrl:1
	v_pk_fma_f32 v[2:3], v[62:63], v[50:51], v[70:71] op_sel_hi:[1,0,1]
	v_pk_fma_f32 v[4:5], v[62:63], v[50:51], v[72:73] op_sel:[0,1,0]
	v_pk_fma_f32 v[6:7], v[62:63], v[52:53], v[74:75] op_sel_hi:[1,0,1]
	v_pk_fma_f32 v[8:9], v[62:63], v[52:53], v[76:77] op_sel:[0,1,0]
	v_pk_fma_f32 v[10:11], v[62:63], v[54:55], v[78:79] op_sel_hi:[1,0,1]
	v_pk_fma_f32 v[12:13], v[62:63], v[54:55], v[80:81] op_sel:[0,1,0]
	v_pk_fma_f32 v[14:15], v[62:63], v[56:57], v[82:83] op_sel_hi:[1,0,1]
	v_pk_fma_f32 v[16:17], v[62:63], v[56:57], v[84:85] op_sel:[0,1,0]
	ds_read_b128 v[50:53], v88 offset:29696
	ds_read_b128 v[54:57], v88 offset:29712
	v_pk_fma_f32 v[86:87], v[58:59], v[60:61], v[66:67] op_sel:[0,1,0]
	v_pk_fma_f32 v[86:87], v[62:63], v[60:61], v[86:87] op_sel_hi:[1,0,1]
	ds_read_b64 v[58:59], v89 offset:46080
	ds_read_b64 v[60:61], v90 offset:51296
	ds_write_b64 v91, v[86:87] offset:3328
	s_waitcnt lgkmcnt(7)
	v_pk_mul_f32 v[62:63], v[2:3], v[18:19] op_sel_hi:[1,0]
	v_pk_mul_f32 v[64:65], v[4:5], v[18:19] op_sel:[0,1]
	v_pk_mul_f32 v[66:67], v[2:3], v[26:27] op_sel_hi:[1,0]
	v_pk_mul_f32 v[68:69], v[4:5], v[26:27] op_sel:[0,1]
	v_pk_fma_f32 v[62:63], v[6:7], v[20:21], v[62:63] op_sel_hi:[1,0,1]
	v_pk_fma_f32 v[66:67], v[6:7], v[28:29], v[66:67] op_sel_hi:[1,0,1]
	v_pk_fma_f32 v[64:65], v[8:9], v[20:21], v[64:65] op_sel:[0,1,0]
	v_pk_fma_f32 v[68:69], v[8:9], v[28:29], v[68:69] op_sel:[0,1,0]
	v_pk_fma_f32 v[62:63], v[10:11], v[22:23], v[62:63] op_sel_hi:[1,0,1]
	v_pk_fma_f32 v[66:67], v[10:11], v[30:31], v[66:67] op_sel_hi:[1,0,1]
	v_pk_fma_f32 v[64:65], v[12:13], v[22:23], v[64:65] op_sel:[0,1,0]
	v_pk_fma_f32 v[68:69], v[12:13], v[30:31], v[68:69] op_sel:[0,1,0]
	v_pk_fma_f32 v[62:63], v[14:15], v[24:25], v[62:63] op_sel_hi:[1,0,1]
	v_pk_fma_f32 v[66:67], v[14:15], v[32:33], v[66:67] op_sel_hi:[1,0,1]
	v_pk_fma_f32 v[64:65], v[16:17], v[24:25], v[64:65] op_sel:[0,1,0]
	v_pk_fma_f32 v[68:69], v[16:17], v[32:33], v[68:69] op_sel:[0,1,0]
	ds_read_b128 v[18:21], v88 offset:21248
	ds_read_b128 v[22:25], v88 offset:21264
	ds_read_b128 v[26:29], v88 offset:37632
	ds_read_b128 v[30:33], v88 offset:37648
	v_pk_add_f32 v[62:63], v[62:63], v[64:65]
	v_pk_add_f32 v[66:67], v[66:67], v[68:69]
	v_pk_mul_f32 v[70:71], v[2:3], v[34:35] op_sel_hi:[1,0]
	v_pk_mul_f32 v[72:73], v[4:5], v[34:35] op_sel:[0,1]
	v_pk_mul_f32 v[74:75], v[6:7], v[36:37] op_sel_hi:[1,0]
	v_pk_mul_f32 v[76:77], v[8:9], v[36:37] op_sel:[0,1]
	v_pk_mul_f32 v[78:79], v[10:11], v[38:39] op_sel_hi:[1,0]
	v_pk_mul_f32 v[80:81], v[12:13], v[38:39] op_sel:[0,1]
	v_pk_mul_f32 v[82:83], v[14:15], v[40:41] op_sel_hi:[1,0]
	v_pk_mul_f32 v[84:85], v[16:17], v[40:41] op_sel:[0,1]
	ds_read_b128 v[34:37], v88 offset:4864
	ds_read_b128 v[38:41], v88 offset:4880
	v_add_f32_dpp v62, v62, v62 quad_perm:[1,0,3,2] row_mask:0xf bank_mask:0xf bound_ctrl:1
	v_add_f32_dpp v63, v63, v63 quad_perm:[1,0,3,2] row_mask:0xf bank_mask:0xf bound_ctrl:1
	v_add_f32_dpp v66, v66, v66 quad_perm:[1,0,3,2] row_mask:0xf bank_mask:0xf bound_ctrl:1
	v_add_f32_dpp v67, v67, v67 quad_perm:[1,0,3,2] row_mask:0xf bank_mask:0xf bound_ctrl:1
	s_waitcnt lgkmcnt(7)
	v_pk_fma_f32 v[70:71], v[58:59], v[42:43], v[70:71] op_sel_hi:[1,0,1]
	v_pk_fma_f32 v[72:73], v[58:59], v[42:43], v[72:73] op_sel:[0,1,0]
	v_pk_fma_f32 v[74:75], v[58:59], v[44:45], v[74:75] op_sel_hi:[1,0,1]
	v_pk_fma_f32 v[76:77], v[58:59], v[44:45], v[76:77] op_sel:[0,1,0]
	v_add_f32_dpp v62, v62, v62 quad_perm:[2,3,0,1] row_mask:0xf bank_mask:0xf bound_ctrl:1
	v_add_f32_dpp v63, v63, v63 quad_perm:[2,3,0,1] row_mask:0xf bank_mask:0xf bound_ctrl:1
	v_add_f32_dpp v66, v66, v66 quad_perm:[2,3,0,1] row_mask:0xf bank_mask:0xf bound_ctrl:1
	v_add_f32_dpp v67, v67, v67 quad_perm:[2,3,0,1] row_mask:0xf bank_mask:0xf bound_ctrl:1
	v_pk_fma_f32 v[78:79], v[58:59], v[46:47], v[78:79] op_sel_hi:[1,0,1]
	v_pk_fma_f32 v[80:81], v[58:59], v[46:47], v[80:81] op_sel:[0,1,0]
	v_pk_fma_f32 v[82:83], v[58:59], v[48:49], v[82:83] op_sel_hi:[1,0,1]
	v_pk_fma_f32 v[84:85], v[58:59], v[48:49], v[84:85] op_sel:[0,1,0]
	ds_read_b128 v[42:45], v88 offset:13056
	ds_read_b128 v[46:49], v88 offset:13072
	v_add_f32_dpp v62, v62, v62 row_half_mirror row_mask:0xf bank_mask:0xf bound_ctrl:1
	v_add_f32_dpp v63, v63, v63 row_half_mirror row_mask:0xf bank_mask:0xf bound_ctrl:1
	v_add_f32_dpp v66, v66, v66 row_half_mirror row_mask:0xf bank_mask:0xf bound_ctrl:1
	v_add_f32_dpp v67, v67, v67 row_half_mirror row_mask:0xf bank_mask:0xf bound_ctrl:1
	v_pk_fma_f32 v[2:3], v[62:63], v[50:51], v[70:71] op_sel_hi:[1,0,1]
	v_pk_fma_f32 v[4:5], v[62:63], v[50:51], v[72:73] op_sel:[0,1,0]
	v_pk_fma_f32 v[6:7], v[62:63], v[52:53], v[74:75] op_sel_hi:[1,0,1]
	v_pk_fma_f32 v[8:9], v[62:63], v[52:53], v[76:77] op_sel:[0,1,0]
	v_pk_fma_f32 v[10:11], v[62:63], v[54:55], v[78:79] op_sel_hi:[1,0,1]
	v_pk_fma_f32 v[12:13], v[62:63], v[54:55], v[80:81] op_sel:[0,1,0]
	v_pk_fma_f32 v[14:15], v[62:63], v[56:57], v[82:83] op_sel_hi:[1,0,1]
	v_pk_fma_f32 v[16:17], v[62:63], v[56:57], v[84:85] op_sel:[0,1,0]
	ds_read_b128 v[50:53], v88 offset:29440
	ds_read_b128 v[54:57], v88 offset:29456
	v_pk_fma_f32 v[86:87], v[58:59], v[60:61], v[66:67] op_sel:[0,1,0]
	v_pk_fma_f32 v[86:87], v[62:63], v[60:61], v[86:87] op_sel_hi:[1,0,1]
	ds_read_b64 v[58:59], v89 offset:45824
	ds_read_b64 v[60:61], v90 offset:51288
	ds_write_b64 v91, v[86:87] offset:3072
	s_waitcnt lgkmcnt(7)
	v_pk_mul_f32 v[62:63], v[2:3], v[18:19] op_sel_hi:[1,0]
	v_pk_mul_f32 v[64:65], v[4:5], v[18:19] op_sel:[0,1]
	v_pk_mul_f32 v[66:67], v[2:3], v[26:27] op_sel_hi:[1,0]
	v_pk_mul_f32 v[68:69], v[4:5], v[26:27] op_sel:[0,1]
	v_pk_fma_f32 v[62:63], v[6:7], v[20:21], v[62:63] op_sel_hi:[1,0,1]
	v_pk_fma_f32 v[66:67], v[6:7], v[28:29], v[66:67] op_sel_hi:[1,0,1]
	v_pk_fma_f32 v[64:65], v[8:9], v[20:21], v[64:65] op_sel:[0,1,0]
	v_pk_fma_f32 v[68:69], v[8:9], v[28:29], v[68:69] op_sel:[0,1,0]
	v_pk_fma_f32 v[62:63], v[10:11], v[22:23], v[62:63] op_sel_hi:[1,0,1]
	v_pk_fma_f32 v[66:67], v[10:11], v[30:31], v[66:67] op_sel_hi:[1,0,1]
	v_pk_fma_f32 v[64:65], v[12:13], v[22:23], v[64:65] op_sel:[0,1,0]
	v_pk_fma_f32 v[68:69], v[12:13], v[30:31], v[68:69] op_sel:[0,1,0]
	v_pk_fma_f32 v[62:63], v[14:15], v[24:25], v[62:63] op_sel_hi:[1,0,1]
	v_pk_fma_f32 v[66:67], v[14:15], v[32:33], v[66:67] op_sel_hi:[1,0,1]
	v_pk_fma_f32 v[64:65], v[16:17], v[24:25], v[64:65] op_sel:[0,1,0]
	v_pk_fma_f32 v[68:69], v[16:17], v[32:33], v[68:69] op_sel:[0,1,0]
	ds_read_b128 v[18:21], v88 offset:20992
	ds_read_b128 v[22:25], v88 offset:21008
	ds_read_b128 v[26:29], v88 offset:37376
	ds_read_b128 v[30:33], v88 offset:37392
	v_pk_add_f32 v[62:63], v[62:63], v[64:65]
	v_pk_add_f32 v[66:67], v[66:67], v[68:69]
	v_pk_mul_f32 v[70:71], v[2:3], v[34:35] op_sel_hi:[1,0]
	v_pk_mul_f32 v[72:73], v[4:5], v[34:35] op_sel:[0,1]
	v_pk_mul_f32 v[74:75], v[6:7], v[36:37] op_sel_hi:[1,0]
	v_pk_mul_f32 v[76:77], v[8:9], v[36:37] op_sel:[0,1]
	v_pk_mul_f32 v[78:79], v[10:11], v[38:39] op_sel_hi:[1,0]
	v_pk_mul_f32 v[80:81], v[12:13], v[38:39] op_sel:[0,1]
	v_pk_mul_f32 v[82:83], v[14:15], v[40:41] op_sel_hi:[1,0]
	v_pk_mul_f32 v[84:85], v[16:17], v[40:41] op_sel:[0,1]
	ds_read_b128 v[34:37], v88 offset:4608
	ds_read_b128 v[38:41], v88 offset:4624
	v_add_f32_dpp v62, v62, v62 quad_perm:[1,0,3,2] row_mask:0xf bank_mask:0xf bound_ctrl:1
	v_add_f32_dpp v63, v63, v63 quad_perm:[1,0,3,2] row_mask:0xf bank_mask:0xf bound_ctrl:1
	v_add_f32_dpp v66, v66, v66 quad_perm:[1,0,3,2] row_mask:0xf bank_mask:0xf bound_ctrl:1
	v_add_f32_dpp v67, v67, v67 quad_perm:[1,0,3,2] row_mask:0xf bank_mask:0xf bound_ctrl:1
	s_waitcnt lgkmcnt(7)
	v_pk_fma_f32 v[70:71], v[58:59], v[42:43], v[70:71] op_sel_hi:[1,0,1]
	v_pk_fma_f32 v[72:73], v[58:59], v[42:43], v[72:73] op_sel:[0,1,0]
	v_pk_fma_f32 v[74:75], v[58:59], v[44:45], v[74:75] op_sel_hi:[1,0,1]
	v_pk_fma_f32 v[76:77], v[58:59], v[44:45], v[76:77] op_sel:[0,1,0]
	v_add_f32_dpp v62, v62, v62 quad_perm:[2,3,0,1] row_mask:0xf bank_mask:0xf bound_ctrl:1
	v_add_f32_dpp v63, v63, v63 quad_perm:[2,3,0,1] row_mask:0xf bank_mask:0xf bound_ctrl:1
	v_add_f32_dpp v66, v66, v66 quad_perm:[2,3,0,1] row_mask:0xf bank_mask:0xf bound_ctrl:1
	v_add_f32_dpp v67, v67, v67 quad_perm:[2,3,0,1] row_mask:0xf bank_mask:0xf bound_ctrl:1
	v_pk_fma_f32 v[78:79], v[58:59], v[46:47], v[78:79] op_sel_hi:[1,0,1]
	v_pk_fma_f32 v[80:81], v[58:59], v[46:47], v[80:81] op_sel:[0,1,0]
	v_pk_fma_f32 v[82:83], v[58:59], v[48:49], v[82:83] op_sel_hi:[1,0,1]
	v_pk_fma_f32 v[84:85], v[58:59], v[48:49], v[84:85] op_sel:[0,1,0]
	ds_read_b128 v[42:45], v88 offset:12800
	ds_read_b128 v[46:49], v88 offset:12816
	v_add_f32_dpp v62, v62, v62 row_half_mirror row_mask:0xf bank_mask:0xf bound_ctrl:1
	v_add_f32_dpp v63, v63, v63 row_half_mirror row_mask:0xf bank_mask:0xf bound_ctrl:1
	v_add_f32_dpp v66, v66, v66 row_half_mirror row_mask:0xf bank_mask:0xf bound_ctrl:1
	v_add_f32_dpp v67, v67, v67 row_half_mirror row_mask:0xf bank_mask:0xf bound_ctrl:1
	v_pk_fma_f32 v[2:3], v[62:63], v[50:51], v[70:71] op_sel_hi:[1,0,1]
	v_pk_fma_f32 v[4:5], v[62:63], v[50:51], v[72:73] op_sel:[0,1,0]
	v_pk_fma_f32 v[6:7], v[62:63], v[52:53], v[74:75] op_sel_hi:[1,0,1]
	v_pk_fma_f32 v[8:9], v[62:63], v[52:53], v[76:77] op_sel:[0,1,0]
	v_pk_fma_f32 v[10:11], v[62:63], v[54:55], v[78:79] op_sel_hi:[1,0,1]
	v_pk_fma_f32 v[12:13], v[62:63], v[54:55], v[80:81] op_sel:[0,1,0]
	v_pk_fma_f32 v[14:15], v[62:63], v[56:57], v[82:83] op_sel_hi:[1,0,1]
	v_pk_fma_f32 v[16:17], v[62:63], v[56:57], v[84:85] op_sel:[0,1,0]
	ds_read_b128 v[50:53], v88 offset:29184
	ds_read_b128 v[54:57], v88 offset:29200
	v_pk_fma_f32 v[86:87], v[58:59], v[60:61], v[66:67] op_sel:[0,1,0]
	v_pk_fma_f32 v[86:87], v[62:63], v[60:61], v[86:87] op_sel_hi:[1,0,1]
	ds_read_b64 v[58:59], v89 offset:45568
	ds_read_b64 v[60:61], v90 offset:51280
	ds_write_b64 v91, v[86:87] offset:2816
	s_waitcnt lgkmcnt(7)
	v_pk_mul_f32 v[62:63], v[2:3], v[18:19] op_sel_hi:[1,0]
	v_pk_mul_f32 v[64:65], v[4:5], v[18:19] op_sel:[0,1]
	v_pk_mul_f32 v[66:67], v[2:3], v[26:27] op_sel_hi:[1,0]
	v_pk_mul_f32 v[68:69], v[4:5], v[26:27] op_sel:[0,1]
	v_pk_fma_f32 v[62:63], v[6:7], v[20:21], v[62:63] op_sel_hi:[1,0,1]
	v_pk_fma_f32 v[66:67], v[6:7], v[28:29], v[66:67] op_sel_hi:[1,0,1]
	v_pk_fma_f32 v[64:65], v[8:9], v[20:21], v[64:65] op_sel:[0,1,0]
	v_pk_fma_f32 v[68:69], v[8:9], v[28:29], v[68:69] op_sel:[0,1,0]
	v_pk_fma_f32 v[62:63], v[10:11], v[22:23], v[62:63] op_sel_hi:[1,0,1]
	v_pk_fma_f32 v[66:67], v[10:11], v[30:31], v[66:67] op_sel_hi:[1,0,1]
	v_pk_fma_f32 v[64:65], v[12:13], v[22:23], v[64:65] op_sel:[0,1,0]
	v_pk_fma_f32 v[68:69], v[12:13], v[30:31], v[68:69] op_sel:[0,1,0]
	v_pk_fma_f32 v[62:63], v[14:15], v[24:25], v[62:63] op_sel_hi:[1,0,1]
	v_pk_fma_f32 v[66:67], v[14:15], v[32:33], v[66:67] op_sel_hi:[1,0,1]
	v_pk_fma_f32 v[64:65], v[16:17], v[24:25], v[64:65] op_sel:[0,1,0]
	v_pk_fma_f32 v[68:69], v[16:17], v[32:33], v[68:69] op_sel:[0,1,0]
	ds_read_b128 v[18:21], v88 offset:20736
	ds_read_b128 v[22:25], v88 offset:20752
	ds_read_b128 v[26:29], v88 offset:37120
	ds_read_b128 v[30:33], v88 offset:37136
	v_pk_add_f32 v[62:63], v[62:63], v[64:65]
	v_pk_add_f32 v[66:67], v[66:67], v[68:69]
	v_pk_mul_f32 v[70:71], v[2:3], v[34:35] op_sel_hi:[1,0]
	v_pk_mul_f32 v[72:73], v[4:5], v[34:35] op_sel:[0,1]
	v_pk_mul_f32 v[74:75], v[6:7], v[36:37] op_sel_hi:[1,0]
	v_pk_mul_f32 v[76:77], v[8:9], v[36:37] op_sel:[0,1]
	v_pk_mul_f32 v[78:79], v[10:11], v[38:39] op_sel_hi:[1,0]
	v_pk_mul_f32 v[80:81], v[12:13], v[38:39] op_sel:[0,1]
	v_pk_mul_f32 v[82:83], v[14:15], v[40:41] op_sel_hi:[1,0]
	v_pk_mul_f32 v[84:85], v[16:17], v[40:41] op_sel:[0,1]
	ds_read_b128 v[34:37], v88 offset:4352
	ds_read_b128 v[38:41], v88 offset:4368
	v_add_f32_dpp v62, v62, v62 quad_perm:[1,0,3,2] row_mask:0xf bank_mask:0xf bound_ctrl:1
	v_add_f32_dpp v63, v63, v63 quad_perm:[1,0,3,2] row_mask:0xf bank_mask:0xf bound_ctrl:1
	v_add_f32_dpp v66, v66, v66 quad_perm:[1,0,3,2] row_mask:0xf bank_mask:0xf bound_ctrl:1
	v_add_f32_dpp v67, v67, v67 quad_perm:[1,0,3,2] row_mask:0xf bank_mask:0xf bound_ctrl:1
	s_waitcnt lgkmcnt(7)
	v_pk_fma_f32 v[70:71], v[58:59], v[42:43], v[70:71] op_sel_hi:[1,0,1]
	v_pk_fma_f32 v[72:73], v[58:59], v[42:43], v[72:73] op_sel:[0,1,0]
	v_pk_fma_f32 v[74:75], v[58:59], v[44:45], v[74:75] op_sel_hi:[1,0,1]
	v_pk_fma_f32 v[76:77], v[58:59], v[44:45], v[76:77] op_sel:[0,1,0]
	v_add_f32_dpp v62, v62, v62 quad_perm:[2,3,0,1] row_mask:0xf bank_mask:0xf bound_ctrl:1
	v_add_f32_dpp v63, v63, v63 quad_perm:[2,3,0,1] row_mask:0xf bank_mask:0xf bound_ctrl:1
	v_add_f32_dpp v66, v66, v66 quad_perm:[2,3,0,1] row_mask:0xf bank_mask:0xf bound_ctrl:1
	v_add_f32_dpp v67, v67, v67 quad_perm:[2,3,0,1] row_mask:0xf bank_mask:0xf bound_ctrl:1
	v_pk_fma_f32 v[78:79], v[58:59], v[46:47], v[78:79] op_sel_hi:[1,0,1]
	v_pk_fma_f32 v[80:81], v[58:59], v[46:47], v[80:81] op_sel:[0,1,0]
	v_pk_fma_f32 v[82:83], v[58:59], v[48:49], v[82:83] op_sel_hi:[1,0,1]
	v_pk_fma_f32 v[84:85], v[58:59], v[48:49], v[84:85] op_sel:[0,1,0]
	ds_read_b128 v[42:45], v88 offset:12544
	ds_read_b128 v[46:49], v88 offset:12560
	v_add_f32_dpp v62, v62, v62 row_half_mirror row_mask:0xf bank_mask:0xf bound_ctrl:1
	v_add_f32_dpp v63, v63, v63 row_half_mirror row_mask:0xf bank_mask:0xf bound_ctrl:1
	v_add_f32_dpp v66, v66, v66 row_half_mirror row_mask:0xf bank_mask:0xf bound_ctrl:1
	v_add_f32_dpp v67, v67, v67 row_half_mirror row_mask:0xf bank_mask:0xf bound_ctrl:1
	v_pk_fma_f32 v[2:3], v[62:63], v[50:51], v[70:71] op_sel_hi:[1,0,1]
	v_pk_fma_f32 v[4:5], v[62:63], v[50:51], v[72:73] op_sel:[0,1,0]
	v_pk_fma_f32 v[6:7], v[62:63], v[52:53], v[74:75] op_sel_hi:[1,0,1]
	v_pk_fma_f32 v[8:9], v[62:63], v[52:53], v[76:77] op_sel:[0,1,0]
	v_pk_fma_f32 v[10:11], v[62:63], v[54:55], v[78:79] op_sel_hi:[1,0,1]
	v_pk_fma_f32 v[12:13], v[62:63], v[54:55], v[80:81] op_sel:[0,1,0]
	v_pk_fma_f32 v[14:15], v[62:63], v[56:57], v[82:83] op_sel_hi:[1,0,1]
	v_pk_fma_f32 v[16:17], v[62:63], v[56:57], v[84:85] op_sel:[0,1,0]
	ds_read_b128 v[50:53], v88 offset:28928
	ds_read_b128 v[54:57], v88 offset:28944
	v_pk_fma_f32 v[86:87], v[58:59], v[60:61], v[66:67] op_sel:[0,1,0]
	v_pk_fma_f32 v[86:87], v[62:63], v[60:61], v[86:87] op_sel_hi:[1,0,1]
	ds_read_b64 v[58:59], v89 offset:45312
	ds_read_b64 v[60:61], v90 offset:51272
	ds_write_b64 v91, v[86:87] offset:2560
	s_waitcnt lgkmcnt(7)
	v_pk_mul_f32 v[62:63], v[2:3], v[18:19] op_sel_hi:[1,0]
	v_pk_mul_f32 v[64:65], v[4:5], v[18:19] op_sel:[0,1]
	v_pk_mul_f32 v[66:67], v[2:3], v[26:27] op_sel_hi:[1,0]
	v_pk_mul_f32 v[68:69], v[4:5], v[26:27] op_sel:[0,1]
	v_pk_fma_f32 v[62:63], v[6:7], v[20:21], v[62:63] op_sel_hi:[1,0,1]
	v_pk_fma_f32 v[66:67], v[6:7], v[28:29], v[66:67] op_sel_hi:[1,0,1]
	v_pk_fma_f32 v[64:65], v[8:9], v[20:21], v[64:65] op_sel:[0,1,0]
	v_pk_fma_f32 v[68:69], v[8:9], v[28:29], v[68:69] op_sel:[0,1,0]
	v_pk_fma_f32 v[62:63], v[10:11], v[22:23], v[62:63] op_sel_hi:[1,0,1]
	v_pk_fma_f32 v[66:67], v[10:11], v[30:31], v[66:67] op_sel_hi:[1,0,1]
	v_pk_fma_f32 v[64:65], v[12:13], v[22:23], v[64:65] op_sel:[0,1,0]
	v_pk_fma_f32 v[68:69], v[12:13], v[30:31], v[68:69] op_sel:[0,1,0]
	v_pk_fma_f32 v[62:63], v[14:15], v[24:25], v[62:63] op_sel_hi:[1,0,1]
	v_pk_fma_f32 v[66:67], v[14:15], v[32:33], v[66:67] op_sel_hi:[1,0,1]
	v_pk_fma_f32 v[64:65], v[16:17], v[24:25], v[64:65] op_sel:[0,1,0]
	v_pk_fma_f32 v[68:69], v[16:17], v[32:33], v[68:69] op_sel:[0,1,0]
	ds_read_b128 v[18:21], v88 offset:20480
	ds_read_b128 v[22:25], v88 offset:20496
	ds_read_b128 v[26:29], v88 offset:36864
	ds_read_b128 v[30:33], v88 offset:36880
	v_pk_add_f32 v[62:63], v[62:63], v[64:65]
	v_pk_add_f32 v[66:67], v[66:67], v[68:69]
	v_pk_mul_f32 v[70:71], v[2:3], v[34:35] op_sel_hi:[1,0]
	v_pk_mul_f32 v[72:73], v[4:5], v[34:35] op_sel:[0,1]
	v_pk_mul_f32 v[74:75], v[6:7], v[36:37] op_sel_hi:[1,0]
	v_pk_mul_f32 v[76:77], v[8:9], v[36:37] op_sel:[0,1]
	v_pk_mul_f32 v[78:79], v[10:11], v[38:39] op_sel_hi:[1,0]
	v_pk_mul_f32 v[80:81], v[12:13], v[38:39] op_sel:[0,1]
	v_pk_mul_f32 v[82:83], v[14:15], v[40:41] op_sel_hi:[1,0]
	v_pk_mul_f32 v[84:85], v[16:17], v[40:41] op_sel:[0,1]
	ds_read_b128 v[34:37], v88 offset:4096
	ds_read_b128 v[38:41], v88 offset:4112
	v_add_f32_dpp v62, v62, v62 quad_perm:[1,0,3,2] row_mask:0xf bank_mask:0xf bound_ctrl:1
	v_add_f32_dpp v63, v63, v63 quad_perm:[1,0,3,2] row_mask:0xf bank_mask:0xf bound_ctrl:1
	v_add_f32_dpp v66, v66, v66 quad_perm:[1,0,3,2] row_mask:0xf bank_mask:0xf bound_ctrl:1
	v_add_f32_dpp v67, v67, v67 quad_perm:[1,0,3,2] row_mask:0xf bank_mask:0xf bound_ctrl:1
	s_waitcnt lgkmcnt(7)
	v_pk_fma_f32 v[70:71], v[58:59], v[42:43], v[70:71] op_sel_hi:[1,0,1]
	v_pk_fma_f32 v[72:73], v[58:59], v[42:43], v[72:73] op_sel:[0,1,0]
	v_pk_fma_f32 v[74:75], v[58:59], v[44:45], v[74:75] op_sel_hi:[1,0,1]
	v_pk_fma_f32 v[76:77], v[58:59], v[44:45], v[76:77] op_sel:[0,1,0]
	v_add_f32_dpp v62, v62, v62 quad_perm:[2,3,0,1] row_mask:0xf bank_mask:0xf bound_ctrl:1
	v_add_f32_dpp v63, v63, v63 quad_perm:[2,3,0,1] row_mask:0xf bank_mask:0xf bound_ctrl:1
	v_add_f32_dpp v66, v66, v66 quad_perm:[2,3,0,1] row_mask:0xf bank_mask:0xf bound_ctrl:1
	v_add_f32_dpp v67, v67, v67 quad_perm:[2,3,0,1] row_mask:0xf bank_mask:0xf bound_ctrl:1
	v_pk_fma_f32 v[78:79], v[58:59], v[46:47], v[78:79] op_sel_hi:[1,0,1]
	v_pk_fma_f32 v[80:81], v[58:59], v[46:47], v[80:81] op_sel:[0,1,0]
	v_pk_fma_f32 v[82:83], v[58:59], v[48:49], v[82:83] op_sel_hi:[1,0,1]
	v_pk_fma_f32 v[84:85], v[58:59], v[48:49], v[84:85] op_sel:[0,1,0]
	ds_read_b128 v[42:45], v88 offset:12288
	ds_read_b128 v[46:49], v88 offset:12304
	v_add_f32_dpp v62, v62, v62 row_half_mirror row_mask:0xf bank_mask:0xf bound_ctrl:1
	v_add_f32_dpp v63, v63, v63 row_half_mirror row_mask:0xf bank_mask:0xf bound_ctrl:1
	v_add_f32_dpp v66, v66, v66 row_half_mirror row_mask:0xf bank_mask:0xf bound_ctrl:1
	v_add_f32_dpp v67, v67, v67 row_half_mirror row_mask:0xf bank_mask:0xf bound_ctrl:1
	v_pk_fma_f32 v[2:3], v[62:63], v[50:51], v[70:71] op_sel_hi:[1,0,1]
	v_pk_fma_f32 v[4:5], v[62:63], v[50:51], v[72:73] op_sel:[0,1,0]
	v_pk_fma_f32 v[6:7], v[62:63], v[52:53], v[74:75] op_sel_hi:[1,0,1]
	v_pk_fma_f32 v[8:9], v[62:63], v[52:53], v[76:77] op_sel:[0,1,0]
	v_pk_fma_f32 v[10:11], v[62:63], v[54:55], v[78:79] op_sel_hi:[1,0,1]
	v_pk_fma_f32 v[12:13], v[62:63], v[54:55], v[80:81] op_sel:[0,1,0]
	v_pk_fma_f32 v[14:15], v[62:63], v[56:57], v[82:83] op_sel_hi:[1,0,1]
	v_pk_fma_f32 v[16:17], v[62:63], v[56:57], v[84:85] op_sel:[0,1,0]
	ds_read_b128 v[50:53], v88 offset:28672
	ds_read_b128 v[54:57], v88 offset:28688
	v_pk_fma_f32 v[86:87], v[58:59], v[60:61], v[66:67] op_sel:[0,1,0]
	v_pk_fma_f32 v[86:87], v[62:63], v[60:61], v[86:87] op_sel_hi:[1,0,1]
	ds_read_b64 v[58:59], v89 offset:45056
	ds_read_b64 v[60:61], v90 offset:51264
	ds_write_b64 v91, v[86:87] offset:2304
	s_waitcnt lgkmcnt(7)
	v_pk_mul_f32 v[62:63], v[2:3], v[18:19] op_sel_hi:[1,0]
	v_pk_mul_f32 v[64:65], v[4:5], v[18:19] op_sel:[0,1]
	v_pk_mul_f32 v[66:67], v[2:3], v[26:27] op_sel_hi:[1,0]
	v_pk_mul_f32 v[68:69], v[4:5], v[26:27] op_sel:[0,1]
	v_pk_fma_f32 v[62:63], v[6:7], v[20:21], v[62:63] op_sel_hi:[1,0,1]
	v_pk_fma_f32 v[66:67], v[6:7], v[28:29], v[66:67] op_sel_hi:[1,0,1]
	v_pk_fma_f32 v[64:65], v[8:9], v[20:21], v[64:65] op_sel:[0,1,0]
	v_pk_fma_f32 v[68:69], v[8:9], v[28:29], v[68:69] op_sel:[0,1,0]
	v_pk_fma_f32 v[62:63], v[10:11], v[22:23], v[62:63] op_sel_hi:[1,0,1]
	v_pk_fma_f32 v[66:67], v[10:11], v[30:31], v[66:67] op_sel_hi:[1,0,1]
	v_pk_fma_f32 v[64:65], v[12:13], v[22:23], v[64:65] op_sel:[0,1,0]
	v_pk_fma_f32 v[68:69], v[12:13], v[30:31], v[68:69] op_sel:[0,1,0]
	v_pk_fma_f32 v[62:63], v[14:15], v[24:25], v[62:63] op_sel_hi:[1,0,1]
	v_pk_fma_f32 v[66:67], v[14:15], v[32:33], v[66:67] op_sel_hi:[1,0,1]
	v_pk_fma_f32 v[64:65], v[16:17], v[24:25], v[64:65] op_sel:[0,1,0]
	v_pk_fma_f32 v[68:69], v[16:17], v[32:33], v[68:69] op_sel:[0,1,0]
	ds_read_b128 v[18:21], v88 offset:20224
	ds_read_b128 v[22:25], v88 offset:20240
	ds_read_b128 v[26:29], v88 offset:36608
	ds_read_b128 v[30:33], v88 offset:36624
	v_pk_add_f32 v[62:63], v[62:63], v[64:65]
	v_pk_add_f32 v[66:67], v[66:67], v[68:69]
	v_pk_mul_f32 v[70:71], v[2:3], v[34:35] op_sel_hi:[1,0]
	v_pk_mul_f32 v[72:73], v[4:5], v[34:35] op_sel:[0,1]
	v_pk_mul_f32 v[74:75], v[6:7], v[36:37] op_sel_hi:[1,0]
	v_pk_mul_f32 v[76:77], v[8:9], v[36:37] op_sel:[0,1]
	v_pk_mul_f32 v[78:79], v[10:11], v[38:39] op_sel_hi:[1,0]
	v_pk_mul_f32 v[80:81], v[12:13], v[38:39] op_sel:[0,1]
	v_pk_mul_f32 v[82:83], v[14:15], v[40:41] op_sel_hi:[1,0]
	v_pk_mul_f32 v[84:85], v[16:17], v[40:41] op_sel:[0,1]
	ds_read_b128 v[34:37], v88 offset:3840
	ds_read_b128 v[38:41], v88 offset:3856
	v_add_f32_dpp v62, v62, v62 quad_perm:[1,0,3,2] row_mask:0xf bank_mask:0xf bound_ctrl:1
	v_add_f32_dpp v63, v63, v63 quad_perm:[1,0,3,2] row_mask:0xf bank_mask:0xf bound_ctrl:1
	v_add_f32_dpp v66, v66, v66 quad_perm:[1,0,3,2] row_mask:0xf bank_mask:0xf bound_ctrl:1
	v_add_f32_dpp v67, v67, v67 quad_perm:[1,0,3,2] row_mask:0xf bank_mask:0xf bound_ctrl:1
	s_waitcnt lgkmcnt(7)
	v_pk_fma_f32 v[70:71], v[58:59], v[42:43], v[70:71] op_sel_hi:[1,0,1]
	v_pk_fma_f32 v[72:73], v[58:59], v[42:43], v[72:73] op_sel:[0,1,0]
	v_pk_fma_f32 v[74:75], v[58:59], v[44:45], v[74:75] op_sel_hi:[1,0,1]
	v_pk_fma_f32 v[76:77], v[58:59], v[44:45], v[76:77] op_sel:[0,1,0]
	v_add_f32_dpp v62, v62, v62 quad_perm:[2,3,0,1] row_mask:0xf bank_mask:0xf bound_ctrl:1
	v_add_f32_dpp v63, v63, v63 quad_perm:[2,3,0,1] row_mask:0xf bank_mask:0xf bound_ctrl:1
	v_add_f32_dpp v66, v66, v66 quad_perm:[2,3,0,1] row_mask:0xf bank_mask:0xf bound_ctrl:1
	v_add_f32_dpp v67, v67, v67 quad_perm:[2,3,0,1] row_mask:0xf bank_mask:0xf bound_ctrl:1
	v_pk_fma_f32 v[78:79], v[58:59], v[46:47], v[78:79] op_sel_hi:[1,0,1]
	v_pk_fma_f32 v[80:81], v[58:59], v[46:47], v[80:81] op_sel:[0,1,0]
	v_pk_fma_f32 v[82:83], v[58:59], v[48:49], v[82:83] op_sel_hi:[1,0,1]
	v_pk_fma_f32 v[84:85], v[58:59], v[48:49], v[84:85] op_sel:[0,1,0]
	ds_read_b128 v[42:45], v88 offset:12032
	ds_read_b128 v[46:49], v88 offset:12048
	v_add_f32_dpp v62, v62, v62 row_half_mirror row_mask:0xf bank_mask:0xf bound_ctrl:1
	v_add_f32_dpp v63, v63, v63 row_half_mirror row_mask:0xf bank_mask:0xf bound_ctrl:1
	v_add_f32_dpp v66, v66, v66 row_half_mirror row_mask:0xf bank_mask:0xf bound_ctrl:1
	v_add_f32_dpp v67, v67, v67 row_half_mirror row_mask:0xf bank_mask:0xf bound_ctrl:1
	v_pk_fma_f32 v[2:3], v[62:63], v[50:51], v[70:71] op_sel_hi:[1,0,1]
	v_pk_fma_f32 v[4:5], v[62:63], v[50:51], v[72:73] op_sel:[0,1,0]
	v_pk_fma_f32 v[6:7], v[62:63], v[52:53], v[74:75] op_sel_hi:[1,0,1]
	v_pk_fma_f32 v[8:9], v[62:63], v[52:53], v[76:77] op_sel:[0,1,0]
	v_pk_fma_f32 v[10:11], v[62:63], v[54:55], v[78:79] op_sel_hi:[1,0,1]
	v_pk_fma_f32 v[12:13], v[62:63], v[54:55], v[80:81] op_sel:[0,1,0]
	v_pk_fma_f32 v[14:15], v[62:63], v[56:57], v[82:83] op_sel_hi:[1,0,1]
	v_pk_fma_f32 v[16:17], v[62:63], v[56:57], v[84:85] op_sel:[0,1,0]
	ds_read_b128 v[50:53], v88 offset:28416
	ds_read_b128 v[54:57], v88 offset:28432
	v_pk_fma_f32 v[86:87], v[58:59], v[60:61], v[66:67] op_sel:[0,1,0]
	v_pk_fma_f32 v[86:87], v[62:63], v[60:61], v[86:87] op_sel_hi:[1,0,1]
	ds_read_b64 v[58:59], v89 offset:44800
	ds_read_b64 v[60:61], v90 offset:51256
	ds_write_b64 v91, v[86:87] offset:2048
	s_waitcnt lgkmcnt(7)
	v_pk_mul_f32 v[62:63], v[2:3], v[18:19] op_sel_hi:[1,0]
	v_pk_mul_f32 v[64:65], v[4:5], v[18:19] op_sel:[0,1]
	v_pk_mul_f32 v[66:67], v[2:3], v[26:27] op_sel_hi:[1,0]
	v_pk_mul_f32 v[68:69], v[4:5], v[26:27] op_sel:[0,1]
	v_pk_fma_f32 v[62:63], v[6:7], v[20:21], v[62:63] op_sel_hi:[1,0,1]
	v_pk_fma_f32 v[66:67], v[6:7], v[28:29], v[66:67] op_sel_hi:[1,0,1]
	v_pk_fma_f32 v[64:65], v[8:9], v[20:21], v[64:65] op_sel:[0,1,0]
	v_pk_fma_f32 v[68:69], v[8:9], v[28:29], v[68:69] op_sel:[0,1,0]
	v_pk_fma_f32 v[62:63], v[10:11], v[22:23], v[62:63] op_sel_hi:[1,0,1]
	v_pk_fma_f32 v[66:67], v[10:11], v[30:31], v[66:67] op_sel_hi:[1,0,1]
	v_pk_fma_f32 v[64:65], v[12:13], v[22:23], v[64:65] op_sel:[0,1,0]
	v_pk_fma_f32 v[68:69], v[12:13], v[30:31], v[68:69] op_sel:[0,1,0]
	v_pk_fma_f32 v[62:63], v[14:15], v[24:25], v[62:63] op_sel_hi:[1,0,1]
	v_pk_fma_f32 v[66:67], v[14:15], v[32:33], v[66:67] op_sel_hi:[1,0,1]
	v_pk_fma_f32 v[64:65], v[16:17], v[24:25], v[64:65] op_sel:[0,1,0]
	v_pk_fma_f32 v[68:69], v[16:17], v[32:33], v[68:69] op_sel:[0,1,0]
	ds_read_b128 v[18:21], v88 offset:19968
	ds_read_b128 v[22:25], v88 offset:19984
	ds_read_b128 v[26:29], v88 offset:36352
	ds_read_b128 v[30:33], v88 offset:36368
	v_pk_add_f32 v[62:63], v[62:63], v[64:65]
	v_pk_add_f32 v[66:67], v[66:67], v[68:69]
	v_pk_mul_f32 v[70:71], v[2:3], v[34:35] op_sel_hi:[1,0]
	v_pk_mul_f32 v[72:73], v[4:5], v[34:35] op_sel:[0,1]
	v_pk_mul_f32 v[74:75], v[6:7], v[36:37] op_sel_hi:[1,0]
	v_pk_mul_f32 v[76:77], v[8:9], v[36:37] op_sel:[0,1]
	v_pk_mul_f32 v[78:79], v[10:11], v[38:39] op_sel_hi:[1,0]
	v_pk_mul_f32 v[80:81], v[12:13], v[38:39] op_sel:[0,1]
	v_pk_mul_f32 v[82:83], v[14:15], v[40:41] op_sel_hi:[1,0]
	v_pk_mul_f32 v[84:85], v[16:17], v[40:41] op_sel:[0,1]
	ds_read_b128 v[34:37], v88 offset:3584
	ds_read_b128 v[38:41], v88 offset:3600
	v_add_f32_dpp v62, v62, v62 quad_perm:[1,0,3,2] row_mask:0xf bank_mask:0xf bound_ctrl:1
	v_add_f32_dpp v63, v63, v63 quad_perm:[1,0,3,2] row_mask:0xf bank_mask:0xf bound_ctrl:1
	v_add_f32_dpp v66, v66, v66 quad_perm:[1,0,3,2] row_mask:0xf bank_mask:0xf bound_ctrl:1
	v_add_f32_dpp v67, v67, v67 quad_perm:[1,0,3,2] row_mask:0xf bank_mask:0xf bound_ctrl:1
	s_waitcnt lgkmcnt(7)
	v_pk_fma_f32 v[70:71], v[58:59], v[42:43], v[70:71] op_sel_hi:[1,0,1]
	v_pk_fma_f32 v[72:73], v[58:59], v[42:43], v[72:73] op_sel:[0,1,0]
	v_pk_fma_f32 v[74:75], v[58:59], v[44:45], v[74:75] op_sel_hi:[1,0,1]
	v_pk_fma_f32 v[76:77], v[58:59], v[44:45], v[76:77] op_sel:[0,1,0]
	v_add_f32_dpp v62, v62, v62 quad_perm:[2,3,0,1] row_mask:0xf bank_mask:0xf bound_ctrl:1
	v_add_f32_dpp v63, v63, v63 quad_perm:[2,3,0,1] row_mask:0xf bank_mask:0xf bound_ctrl:1
	v_add_f32_dpp v66, v66, v66 quad_perm:[2,3,0,1] row_mask:0xf bank_mask:0xf bound_ctrl:1
	v_add_f32_dpp v67, v67, v67 quad_perm:[2,3,0,1] row_mask:0xf bank_mask:0xf bound_ctrl:1
	v_pk_fma_f32 v[78:79], v[58:59], v[46:47], v[78:79] op_sel_hi:[1,0,1]
	v_pk_fma_f32 v[80:81], v[58:59], v[46:47], v[80:81] op_sel:[0,1,0]
	v_pk_fma_f32 v[82:83], v[58:59], v[48:49], v[82:83] op_sel_hi:[1,0,1]
	v_pk_fma_f32 v[84:85], v[58:59], v[48:49], v[84:85] op_sel:[0,1,0]
	ds_read_b128 v[42:45], v88 offset:11776
	ds_read_b128 v[46:49], v88 offset:11792
	v_add_f32_dpp v62, v62, v62 row_half_mirror row_mask:0xf bank_mask:0xf bound_ctrl:1
	v_add_f32_dpp v63, v63, v63 row_half_mirror row_mask:0xf bank_mask:0xf bound_ctrl:1
	v_add_f32_dpp v66, v66, v66 row_half_mirror row_mask:0xf bank_mask:0xf bound_ctrl:1
	v_add_f32_dpp v67, v67, v67 row_half_mirror row_mask:0xf bank_mask:0xf bound_ctrl:1
	v_pk_fma_f32 v[2:3], v[62:63], v[50:51], v[70:71] op_sel_hi:[1,0,1]
	v_pk_fma_f32 v[4:5], v[62:63], v[50:51], v[72:73] op_sel:[0,1,0]
	v_pk_fma_f32 v[6:7], v[62:63], v[52:53], v[74:75] op_sel_hi:[1,0,1]
	v_pk_fma_f32 v[8:9], v[62:63], v[52:53], v[76:77] op_sel:[0,1,0]
	v_pk_fma_f32 v[10:11], v[62:63], v[54:55], v[78:79] op_sel_hi:[1,0,1]
	v_pk_fma_f32 v[12:13], v[62:63], v[54:55], v[80:81] op_sel:[0,1,0]
	v_pk_fma_f32 v[14:15], v[62:63], v[56:57], v[82:83] op_sel_hi:[1,0,1]
	v_pk_fma_f32 v[16:17], v[62:63], v[56:57], v[84:85] op_sel:[0,1,0]
	ds_read_b128 v[50:53], v88 offset:28160
	ds_read_b128 v[54:57], v88 offset:28176
	v_pk_fma_f32 v[86:87], v[58:59], v[60:61], v[66:67] op_sel:[0,1,0]
	v_pk_fma_f32 v[86:87], v[62:63], v[60:61], v[86:87] op_sel_hi:[1,0,1]
	ds_read_b64 v[58:59], v89 offset:44544
	ds_read_b64 v[60:61], v90 offset:51248
	ds_write_b64 v91, v[86:87] offset:1792
	s_waitcnt lgkmcnt(7)
	v_pk_mul_f32 v[62:63], v[2:3], v[18:19] op_sel_hi:[1,0]
	v_pk_mul_f32 v[64:65], v[4:5], v[18:19] op_sel:[0,1]
	v_pk_mul_f32 v[66:67], v[2:3], v[26:27] op_sel_hi:[1,0]
	v_pk_mul_f32 v[68:69], v[4:5], v[26:27] op_sel:[0,1]
	v_pk_fma_f32 v[62:63], v[6:7], v[20:21], v[62:63] op_sel_hi:[1,0,1]
	v_pk_fma_f32 v[66:67], v[6:7], v[28:29], v[66:67] op_sel_hi:[1,0,1]
	v_pk_fma_f32 v[64:65], v[8:9], v[20:21], v[64:65] op_sel:[0,1,0]
	v_pk_fma_f32 v[68:69], v[8:9], v[28:29], v[68:69] op_sel:[0,1,0]
	v_pk_fma_f32 v[62:63], v[10:11], v[22:23], v[62:63] op_sel_hi:[1,0,1]
	v_pk_fma_f32 v[66:67], v[10:11], v[30:31], v[66:67] op_sel_hi:[1,0,1]
	v_pk_fma_f32 v[64:65], v[12:13], v[22:23], v[64:65] op_sel:[0,1,0]
	v_pk_fma_f32 v[68:69], v[12:13], v[30:31], v[68:69] op_sel:[0,1,0]
	v_pk_fma_f32 v[62:63], v[14:15], v[24:25], v[62:63] op_sel_hi:[1,0,1]
	v_pk_fma_f32 v[66:67], v[14:15], v[32:33], v[66:67] op_sel_hi:[1,0,1]
	v_pk_fma_f32 v[64:65], v[16:17], v[24:25], v[64:65] op_sel:[0,1,0]
	v_pk_fma_f32 v[68:69], v[16:17], v[32:33], v[68:69] op_sel:[0,1,0]
	ds_read_b128 v[18:21], v88 offset:19712
	ds_read_b128 v[22:25], v88 offset:19728
	ds_read_b128 v[26:29], v88 offset:36096
	ds_read_b128 v[30:33], v88 offset:36112
	v_pk_add_f32 v[62:63], v[62:63], v[64:65]
	v_pk_add_f32 v[66:67], v[66:67], v[68:69]
	v_pk_mul_f32 v[70:71], v[2:3], v[34:35] op_sel_hi:[1,0]
	v_pk_mul_f32 v[72:73], v[4:5], v[34:35] op_sel:[0,1]
	v_pk_mul_f32 v[74:75], v[6:7], v[36:37] op_sel_hi:[1,0]
	v_pk_mul_f32 v[76:77], v[8:9], v[36:37] op_sel:[0,1]
	v_pk_mul_f32 v[78:79], v[10:11], v[38:39] op_sel_hi:[1,0]
	v_pk_mul_f32 v[80:81], v[12:13], v[38:39] op_sel:[0,1]
	v_pk_mul_f32 v[82:83], v[14:15], v[40:41] op_sel_hi:[1,0]
	v_pk_mul_f32 v[84:85], v[16:17], v[40:41] op_sel:[0,1]
	ds_read_b128 v[34:37], v88 offset:3328
	ds_read_b128 v[38:41], v88 offset:3344
	v_add_f32_dpp v62, v62, v62 quad_perm:[1,0,3,2] row_mask:0xf bank_mask:0xf bound_ctrl:1
	v_add_f32_dpp v63, v63, v63 quad_perm:[1,0,3,2] row_mask:0xf bank_mask:0xf bound_ctrl:1
	v_add_f32_dpp v66, v66, v66 quad_perm:[1,0,3,2] row_mask:0xf bank_mask:0xf bound_ctrl:1
	v_add_f32_dpp v67, v67, v67 quad_perm:[1,0,3,2] row_mask:0xf bank_mask:0xf bound_ctrl:1
	s_waitcnt lgkmcnt(7)
	v_pk_fma_f32 v[70:71], v[58:59], v[42:43], v[70:71] op_sel_hi:[1,0,1]
	v_pk_fma_f32 v[72:73], v[58:59], v[42:43], v[72:73] op_sel:[0,1,0]
	v_pk_fma_f32 v[74:75], v[58:59], v[44:45], v[74:75] op_sel_hi:[1,0,1]
	v_pk_fma_f32 v[76:77], v[58:59], v[44:45], v[76:77] op_sel:[0,1,0]
	v_add_f32_dpp v62, v62, v62 quad_perm:[2,3,0,1] row_mask:0xf bank_mask:0xf bound_ctrl:1
	v_add_f32_dpp v63, v63, v63 quad_perm:[2,3,0,1] row_mask:0xf bank_mask:0xf bound_ctrl:1
	v_add_f32_dpp v66, v66, v66 quad_perm:[2,3,0,1] row_mask:0xf bank_mask:0xf bound_ctrl:1
	v_add_f32_dpp v67, v67, v67 quad_perm:[2,3,0,1] row_mask:0xf bank_mask:0xf bound_ctrl:1
	v_pk_fma_f32 v[78:79], v[58:59], v[46:47], v[78:79] op_sel_hi:[1,0,1]
	v_pk_fma_f32 v[80:81], v[58:59], v[46:47], v[80:81] op_sel:[0,1,0]
	v_pk_fma_f32 v[82:83], v[58:59], v[48:49], v[82:83] op_sel_hi:[1,0,1]
	v_pk_fma_f32 v[84:85], v[58:59], v[48:49], v[84:85] op_sel:[0,1,0]
	ds_read_b128 v[42:45], v88 offset:11520
	ds_read_b128 v[46:49], v88 offset:11536
	v_add_f32_dpp v62, v62, v62 row_half_mirror row_mask:0xf bank_mask:0xf bound_ctrl:1
	v_add_f32_dpp v63, v63, v63 row_half_mirror row_mask:0xf bank_mask:0xf bound_ctrl:1
	v_add_f32_dpp v66, v66, v66 row_half_mirror row_mask:0xf bank_mask:0xf bound_ctrl:1
	v_add_f32_dpp v67, v67, v67 row_half_mirror row_mask:0xf bank_mask:0xf bound_ctrl:1
	v_pk_fma_f32 v[2:3], v[62:63], v[50:51], v[70:71] op_sel_hi:[1,0,1]
	v_pk_fma_f32 v[4:5], v[62:63], v[50:51], v[72:73] op_sel:[0,1,0]
	v_pk_fma_f32 v[6:7], v[62:63], v[52:53], v[74:75] op_sel_hi:[1,0,1]
	v_pk_fma_f32 v[8:9], v[62:63], v[52:53], v[76:77] op_sel:[0,1,0]
	v_pk_fma_f32 v[10:11], v[62:63], v[54:55], v[78:79] op_sel_hi:[1,0,1]
	v_pk_fma_f32 v[12:13], v[62:63], v[54:55], v[80:81] op_sel:[0,1,0]
	v_pk_fma_f32 v[14:15], v[62:63], v[56:57], v[82:83] op_sel_hi:[1,0,1]
	v_pk_fma_f32 v[16:17], v[62:63], v[56:57], v[84:85] op_sel:[0,1,0]
	ds_read_b128 v[50:53], v88 offset:27904
	ds_read_b128 v[54:57], v88 offset:27920
	v_pk_fma_f32 v[86:87], v[58:59], v[60:61], v[66:67] op_sel:[0,1,0]
	v_pk_fma_f32 v[86:87], v[62:63], v[60:61], v[86:87] op_sel_hi:[1,0,1]
	ds_read_b64 v[58:59], v89 offset:44288
	ds_read_b64 v[60:61], v90 offset:51240
	ds_write_b64 v91, v[86:87] offset:1536
	s_waitcnt lgkmcnt(7)
	v_pk_mul_f32 v[62:63], v[2:3], v[18:19] op_sel_hi:[1,0]
	v_pk_mul_f32 v[64:65], v[4:5], v[18:19] op_sel:[0,1]
	v_pk_mul_f32 v[66:67], v[2:3], v[26:27] op_sel_hi:[1,0]
	v_pk_mul_f32 v[68:69], v[4:5], v[26:27] op_sel:[0,1]
	v_pk_fma_f32 v[62:63], v[6:7], v[20:21], v[62:63] op_sel_hi:[1,0,1]
	v_pk_fma_f32 v[66:67], v[6:7], v[28:29], v[66:67] op_sel_hi:[1,0,1]
	v_pk_fma_f32 v[64:65], v[8:9], v[20:21], v[64:65] op_sel:[0,1,0]
	v_pk_fma_f32 v[68:69], v[8:9], v[28:29], v[68:69] op_sel:[0,1,0]
	v_pk_fma_f32 v[62:63], v[10:11], v[22:23], v[62:63] op_sel_hi:[1,0,1]
	v_pk_fma_f32 v[66:67], v[10:11], v[30:31], v[66:67] op_sel_hi:[1,0,1]
	v_pk_fma_f32 v[64:65], v[12:13], v[22:23], v[64:65] op_sel:[0,1,0]
	v_pk_fma_f32 v[68:69], v[12:13], v[30:31], v[68:69] op_sel:[0,1,0]
	v_pk_fma_f32 v[62:63], v[14:15], v[24:25], v[62:63] op_sel_hi:[1,0,1]
	v_pk_fma_f32 v[66:67], v[14:15], v[32:33], v[66:67] op_sel_hi:[1,0,1]
	v_pk_fma_f32 v[64:65], v[16:17], v[24:25], v[64:65] op_sel:[0,1,0]
	v_pk_fma_f32 v[68:69], v[16:17], v[32:33], v[68:69] op_sel:[0,1,0]
	ds_read_b128 v[18:21], v88 offset:19456
	ds_read_b128 v[22:25], v88 offset:19472
	ds_read_b128 v[26:29], v88 offset:35840
	ds_read_b128 v[30:33], v88 offset:35856
	v_pk_add_f32 v[62:63], v[62:63], v[64:65]
	v_pk_add_f32 v[66:67], v[66:67], v[68:69]
	v_pk_mul_f32 v[70:71], v[2:3], v[34:35] op_sel_hi:[1,0]
	v_pk_mul_f32 v[72:73], v[4:5], v[34:35] op_sel:[0,1]
	v_pk_mul_f32 v[74:75], v[6:7], v[36:37] op_sel_hi:[1,0]
	v_pk_mul_f32 v[76:77], v[8:9], v[36:37] op_sel:[0,1]
	v_pk_mul_f32 v[78:79], v[10:11], v[38:39] op_sel_hi:[1,0]
	v_pk_mul_f32 v[80:81], v[12:13], v[38:39] op_sel:[0,1]
	v_pk_mul_f32 v[82:83], v[14:15], v[40:41] op_sel_hi:[1,0]
	v_pk_mul_f32 v[84:85], v[16:17], v[40:41] op_sel:[0,1]
	ds_read_b128 v[34:37], v88 offset:3072
	ds_read_b128 v[38:41], v88 offset:3088
	v_add_f32_dpp v62, v62, v62 quad_perm:[1,0,3,2] row_mask:0xf bank_mask:0xf bound_ctrl:1
	v_add_f32_dpp v63, v63, v63 quad_perm:[1,0,3,2] row_mask:0xf bank_mask:0xf bound_ctrl:1
	v_add_f32_dpp v66, v66, v66 quad_perm:[1,0,3,2] row_mask:0xf bank_mask:0xf bound_ctrl:1
	v_add_f32_dpp v67, v67, v67 quad_perm:[1,0,3,2] row_mask:0xf bank_mask:0xf bound_ctrl:1
	s_waitcnt lgkmcnt(7)
	v_pk_fma_f32 v[70:71], v[58:59], v[42:43], v[70:71] op_sel_hi:[1,0,1]
	v_pk_fma_f32 v[72:73], v[58:59], v[42:43], v[72:73] op_sel:[0,1,0]
	v_pk_fma_f32 v[74:75], v[58:59], v[44:45], v[74:75] op_sel_hi:[1,0,1]
	v_pk_fma_f32 v[76:77], v[58:59], v[44:45], v[76:77] op_sel:[0,1,0]
	v_add_f32_dpp v62, v62, v62 quad_perm:[2,3,0,1] row_mask:0xf bank_mask:0xf bound_ctrl:1
	v_add_f32_dpp v63, v63, v63 quad_perm:[2,3,0,1] row_mask:0xf bank_mask:0xf bound_ctrl:1
	v_add_f32_dpp v66, v66, v66 quad_perm:[2,3,0,1] row_mask:0xf bank_mask:0xf bound_ctrl:1
	v_add_f32_dpp v67, v67, v67 quad_perm:[2,3,0,1] row_mask:0xf bank_mask:0xf bound_ctrl:1
	v_pk_fma_f32 v[78:79], v[58:59], v[46:47], v[78:79] op_sel_hi:[1,0,1]
	v_pk_fma_f32 v[80:81], v[58:59], v[46:47], v[80:81] op_sel:[0,1,0]
	v_pk_fma_f32 v[82:83], v[58:59], v[48:49], v[82:83] op_sel_hi:[1,0,1]
	v_pk_fma_f32 v[84:85], v[58:59], v[48:49], v[84:85] op_sel:[0,1,0]
	ds_read_b128 v[42:45], v88 offset:11264
	ds_read_b128 v[46:49], v88 offset:11280
	v_add_f32_dpp v62, v62, v62 row_half_mirror row_mask:0xf bank_mask:0xf bound_ctrl:1
	v_add_f32_dpp v63, v63, v63 row_half_mirror row_mask:0xf bank_mask:0xf bound_ctrl:1
	v_add_f32_dpp v66, v66, v66 row_half_mirror row_mask:0xf bank_mask:0xf bound_ctrl:1
	v_add_f32_dpp v67, v67, v67 row_half_mirror row_mask:0xf bank_mask:0xf bound_ctrl:1
	v_pk_fma_f32 v[2:3], v[62:63], v[50:51], v[70:71] op_sel_hi:[1,0,1]
	v_pk_fma_f32 v[4:5], v[62:63], v[50:51], v[72:73] op_sel:[0,1,0]
	v_pk_fma_f32 v[6:7], v[62:63], v[52:53], v[74:75] op_sel_hi:[1,0,1]
	v_pk_fma_f32 v[8:9], v[62:63], v[52:53], v[76:77] op_sel:[0,1,0]
	v_pk_fma_f32 v[10:11], v[62:63], v[54:55], v[78:79] op_sel_hi:[1,0,1]
	v_pk_fma_f32 v[12:13], v[62:63], v[54:55], v[80:81] op_sel:[0,1,0]
	v_pk_fma_f32 v[14:15], v[62:63], v[56:57], v[82:83] op_sel_hi:[1,0,1]
	v_pk_fma_f32 v[16:17], v[62:63], v[56:57], v[84:85] op_sel:[0,1,0]
	ds_read_b128 v[50:53], v88 offset:27648
	ds_read_b128 v[54:57], v88 offset:27664
	v_pk_fma_f32 v[86:87], v[58:59], v[60:61], v[66:67] op_sel:[0,1,0]
	v_pk_fma_f32 v[86:87], v[62:63], v[60:61], v[86:87] op_sel_hi:[1,0,1]
	ds_read_b64 v[58:59], v89 offset:44032
	ds_read_b64 v[60:61], v90 offset:51232
	ds_write_b64 v91, v[86:87] offset:1280
	s_waitcnt lgkmcnt(7)
	v_pk_mul_f32 v[62:63], v[2:3], v[18:19] op_sel_hi:[1,0]
	v_pk_mul_f32 v[64:65], v[4:5], v[18:19] op_sel:[0,1]
	v_pk_mul_f32 v[66:67], v[2:3], v[26:27] op_sel_hi:[1,0]
	v_pk_mul_f32 v[68:69], v[4:5], v[26:27] op_sel:[0,1]
	v_pk_fma_f32 v[62:63], v[6:7], v[20:21], v[62:63] op_sel_hi:[1,0,1]
	v_pk_fma_f32 v[66:67], v[6:7], v[28:29], v[66:67] op_sel_hi:[1,0,1]
	v_pk_fma_f32 v[64:65], v[8:9], v[20:21], v[64:65] op_sel:[0,1,0]
	v_pk_fma_f32 v[68:69], v[8:9], v[28:29], v[68:69] op_sel:[0,1,0]
	v_pk_fma_f32 v[62:63], v[10:11], v[22:23], v[62:63] op_sel_hi:[1,0,1]
	v_pk_fma_f32 v[66:67], v[10:11], v[30:31], v[66:67] op_sel_hi:[1,0,1]
	v_pk_fma_f32 v[64:65], v[12:13], v[22:23], v[64:65] op_sel:[0,1,0]
	v_pk_fma_f32 v[68:69], v[12:13], v[30:31], v[68:69] op_sel:[0,1,0]
	v_pk_fma_f32 v[62:63], v[14:15], v[24:25], v[62:63] op_sel_hi:[1,0,1]
	v_pk_fma_f32 v[66:67], v[14:15], v[32:33], v[66:67] op_sel_hi:[1,0,1]
	v_pk_fma_f32 v[64:65], v[16:17], v[24:25], v[64:65] op_sel:[0,1,0]
	v_pk_fma_f32 v[68:69], v[16:17], v[32:33], v[68:69] op_sel:[0,1,0]
	ds_read_b128 v[18:21], v88 offset:19200
	ds_read_b128 v[22:25], v88 offset:19216
	ds_read_b128 v[26:29], v88 offset:35584
	ds_read_b128 v[30:33], v88 offset:35600
	v_pk_add_f32 v[62:63], v[62:63], v[64:65]
	v_pk_add_f32 v[66:67], v[66:67], v[68:69]
	v_pk_mul_f32 v[70:71], v[2:3], v[34:35] op_sel_hi:[1,0]
	v_pk_mul_f32 v[72:73], v[4:5], v[34:35] op_sel:[0,1]
	v_pk_mul_f32 v[74:75], v[6:7], v[36:37] op_sel_hi:[1,0]
	v_pk_mul_f32 v[76:77], v[8:9], v[36:37] op_sel:[0,1]
	v_pk_mul_f32 v[78:79], v[10:11], v[38:39] op_sel_hi:[1,0]
	v_pk_mul_f32 v[80:81], v[12:13], v[38:39] op_sel:[0,1]
	v_pk_mul_f32 v[82:83], v[14:15], v[40:41] op_sel_hi:[1,0]
	v_pk_mul_f32 v[84:85], v[16:17], v[40:41] op_sel:[0,1]
	ds_read_b128 v[34:37], v88 offset:2816
	ds_read_b128 v[38:41], v88 offset:2832
	v_add_f32_dpp v62, v62, v62 quad_perm:[1,0,3,2] row_mask:0xf bank_mask:0xf bound_ctrl:1
	v_add_f32_dpp v63, v63, v63 quad_perm:[1,0,3,2] row_mask:0xf bank_mask:0xf bound_ctrl:1
	v_add_f32_dpp v66, v66, v66 quad_perm:[1,0,3,2] row_mask:0xf bank_mask:0xf bound_ctrl:1
	v_add_f32_dpp v67, v67, v67 quad_perm:[1,0,3,2] row_mask:0xf bank_mask:0xf bound_ctrl:1
	s_waitcnt lgkmcnt(7)
	v_pk_fma_f32 v[70:71], v[58:59], v[42:43], v[70:71] op_sel_hi:[1,0,1]
	v_pk_fma_f32 v[72:73], v[58:59], v[42:43], v[72:73] op_sel:[0,1,0]
	v_pk_fma_f32 v[74:75], v[58:59], v[44:45], v[74:75] op_sel_hi:[1,0,1]
	v_pk_fma_f32 v[76:77], v[58:59], v[44:45], v[76:77] op_sel:[0,1,0]
	v_add_f32_dpp v62, v62, v62 quad_perm:[2,3,0,1] row_mask:0xf bank_mask:0xf bound_ctrl:1
	v_add_f32_dpp v63, v63, v63 quad_perm:[2,3,0,1] row_mask:0xf bank_mask:0xf bound_ctrl:1
	v_add_f32_dpp v66, v66, v66 quad_perm:[2,3,0,1] row_mask:0xf bank_mask:0xf bound_ctrl:1
	v_add_f32_dpp v67, v67, v67 quad_perm:[2,3,0,1] row_mask:0xf bank_mask:0xf bound_ctrl:1
	v_pk_fma_f32 v[78:79], v[58:59], v[46:47], v[78:79] op_sel_hi:[1,0,1]
	v_pk_fma_f32 v[80:81], v[58:59], v[46:47], v[80:81] op_sel:[0,1,0]
	v_pk_fma_f32 v[82:83], v[58:59], v[48:49], v[82:83] op_sel_hi:[1,0,1]
	v_pk_fma_f32 v[84:85], v[58:59], v[48:49], v[84:85] op_sel:[0,1,0]
	ds_read_b128 v[42:45], v88 offset:11008
	ds_read_b128 v[46:49], v88 offset:11024
	v_add_f32_dpp v62, v62, v62 row_half_mirror row_mask:0xf bank_mask:0xf bound_ctrl:1
	v_add_f32_dpp v63, v63, v63 row_half_mirror row_mask:0xf bank_mask:0xf bound_ctrl:1
	v_add_f32_dpp v66, v66, v66 row_half_mirror row_mask:0xf bank_mask:0xf bound_ctrl:1
	v_add_f32_dpp v67, v67, v67 row_half_mirror row_mask:0xf bank_mask:0xf bound_ctrl:1
	v_pk_fma_f32 v[2:3], v[62:63], v[50:51], v[70:71] op_sel_hi:[1,0,1]
	v_pk_fma_f32 v[4:5], v[62:63], v[50:51], v[72:73] op_sel:[0,1,0]
	v_pk_fma_f32 v[6:7], v[62:63], v[52:53], v[74:75] op_sel_hi:[1,0,1]
	v_pk_fma_f32 v[8:9], v[62:63], v[52:53], v[76:77] op_sel:[0,1,0]
	v_pk_fma_f32 v[10:11], v[62:63], v[54:55], v[78:79] op_sel_hi:[1,0,1]
	v_pk_fma_f32 v[12:13], v[62:63], v[54:55], v[80:81] op_sel:[0,1,0]
	v_pk_fma_f32 v[14:15], v[62:63], v[56:57], v[82:83] op_sel_hi:[1,0,1]
	v_pk_fma_f32 v[16:17], v[62:63], v[56:57], v[84:85] op_sel:[0,1,0]
	ds_read_b128 v[50:53], v88 offset:27392
	ds_read_b128 v[54:57], v88 offset:27408
	v_pk_fma_f32 v[86:87], v[58:59], v[60:61], v[66:67] op_sel:[0,1,0]
	v_pk_fma_f32 v[86:87], v[62:63], v[60:61], v[86:87] op_sel_hi:[1,0,1]
	ds_read_b64 v[58:59], v89 offset:43776
	ds_read_b64 v[60:61], v90 offset:51224
	ds_write_b64 v91, v[86:87] offset:1024
	s_waitcnt lgkmcnt(7)
	v_pk_mul_f32 v[62:63], v[2:3], v[18:19] op_sel_hi:[1,0]
	v_pk_mul_f32 v[64:65], v[4:5], v[18:19] op_sel:[0,1]
	v_pk_mul_f32 v[66:67], v[2:3], v[26:27] op_sel_hi:[1,0]
	v_pk_mul_f32 v[68:69], v[4:5], v[26:27] op_sel:[0,1]
	v_pk_fma_f32 v[62:63], v[6:7], v[20:21], v[62:63] op_sel_hi:[1,0,1]
	v_pk_fma_f32 v[66:67], v[6:7], v[28:29], v[66:67] op_sel_hi:[1,0,1]
	v_pk_fma_f32 v[64:65], v[8:9], v[20:21], v[64:65] op_sel:[0,1,0]
	v_pk_fma_f32 v[68:69], v[8:9], v[28:29], v[68:69] op_sel:[0,1,0]
	v_pk_fma_f32 v[62:63], v[10:11], v[22:23], v[62:63] op_sel_hi:[1,0,1]
	v_pk_fma_f32 v[66:67], v[10:11], v[30:31], v[66:67] op_sel_hi:[1,0,1]
	v_pk_fma_f32 v[64:65], v[12:13], v[22:23], v[64:65] op_sel:[0,1,0]
	v_pk_fma_f32 v[68:69], v[12:13], v[30:31], v[68:69] op_sel:[0,1,0]
	v_pk_fma_f32 v[62:63], v[14:15], v[24:25], v[62:63] op_sel_hi:[1,0,1]
	v_pk_fma_f32 v[66:67], v[14:15], v[32:33], v[66:67] op_sel_hi:[1,0,1]
	v_pk_fma_f32 v[64:65], v[16:17], v[24:25], v[64:65] op_sel:[0,1,0]
	v_pk_fma_f32 v[68:69], v[16:17], v[32:33], v[68:69] op_sel:[0,1,0]
	ds_read_b128 v[18:21], v88 offset:18944
	ds_read_b128 v[22:25], v88 offset:18960
	ds_read_b128 v[26:29], v88 offset:35328
	ds_read_b128 v[30:33], v88 offset:35344
	v_pk_add_f32 v[62:63], v[62:63], v[64:65]
	v_pk_add_f32 v[66:67], v[66:67], v[68:69]
	v_pk_mul_f32 v[70:71], v[2:3], v[34:35] op_sel_hi:[1,0]
	v_pk_mul_f32 v[72:73], v[4:5], v[34:35] op_sel:[0,1]
	v_pk_mul_f32 v[74:75], v[6:7], v[36:37] op_sel_hi:[1,0]
	v_pk_mul_f32 v[76:77], v[8:9], v[36:37] op_sel:[0,1]
	v_pk_mul_f32 v[78:79], v[10:11], v[38:39] op_sel_hi:[1,0]
	v_pk_mul_f32 v[80:81], v[12:13], v[38:39] op_sel:[0,1]
	v_pk_mul_f32 v[82:83], v[14:15], v[40:41] op_sel_hi:[1,0]
	v_pk_mul_f32 v[84:85], v[16:17], v[40:41] op_sel:[0,1]
	ds_read_b128 v[34:37], v88 offset:2560
	ds_read_b128 v[38:41], v88 offset:2576
	v_add_f32_dpp v62, v62, v62 quad_perm:[1,0,3,2] row_mask:0xf bank_mask:0xf bound_ctrl:1
	v_add_f32_dpp v63, v63, v63 quad_perm:[1,0,3,2] row_mask:0xf bank_mask:0xf bound_ctrl:1
	v_add_f32_dpp v66, v66, v66 quad_perm:[1,0,3,2] row_mask:0xf bank_mask:0xf bound_ctrl:1
	v_add_f32_dpp v67, v67, v67 quad_perm:[1,0,3,2] row_mask:0xf bank_mask:0xf bound_ctrl:1
	s_waitcnt lgkmcnt(7)
	v_pk_fma_f32 v[70:71], v[58:59], v[42:43], v[70:71] op_sel_hi:[1,0,1]
	v_pk_fma_f32 v[72:73], v[58:59], v[42:43], v[72:73] op_sel:[0,1,0]
	v_pk_fma_f32 v[74:75], v[58:59], v[44:45], v[74:75] op_sel_hi:[1,0,1]
	v_pk_fma_f32 v[76:77], v[58:59], v[44:45], v[76:77] op_sel:[0,1,0]
	v_add_f32_dpp v62, v62, v62 quad_perm:[2,3,0,1] row_mask:0xf bank_mask:0xf bound_ctrl:1
	v_add_f32_dpp v63, v63, v63 quad_perm:[2,3,0,1] row_mask:0xf bank_mask:0xf bound_ctrl:1
	v_add_f32_dpp v66, v66, v66 quad_perm:[2,3,0,1] row_mask:0xf bank_mask:0xf bound_ctrl:1
	v_add_f32_dpp v67, v67, v67 quad_perm:[2,3,0,1] row_mask:0xf bank_mask:0xf bound_ctrl:1
	v_pk_fma_f32 v[78:79], v[58:59], v[46:47], v[78:79] op_sel_hi:[1,0,1]
	v_pk_fma_f32 v[80:81], v[58:59], v[46:47], v[80:81] op_sel:[0,1,0]
	v_pk_fma_f32 v[82:83], v[58:59], v[48:49], v[82:83] op_sel_hi:[1,0,1]
	v_pk_fma_f32 v[84:85], v[58:59], v[48:49], v[84:85] op_sel:[0,1,0]
	ds_read_b128 v[42:45], v88 offset:10752
	ds_read_b128 v[46:49], v88 offset:10768
	v_add_f32_dpp v62, v62, v62 row_half_mirror row_mask:0xf bank_mask:0xf bound_ctrl:1
	v_add_f32_dpp v63, v63, v63 row_half_mirror row_mask:0xf bank_mask:0xf bound_ctrl:1
	v_add_f32_dpp v66, v66, v66 row_half_mirror row_mask:0xf bank_mask:0xf bound_ctrl:1
	v_add_f32_dpp v67, v67, v67 row_half_mirror row_mask:0xf bank_mask:0xf bound_ctrl:1
	v_pk_fma_f32 v[2:3], v[62:63], v[50:51], v[70:71] op_sel_hi:[1,0,1]
	v_pk_fma_f32 v[4:5], v[62:63], v[50:51], v[72:73] op_sel:[0,1,0]
	v_pk_fma_f32 v[6:7], v[62:63], v[52:53], v[74:75] op_sel_hi:[1,0,1]
	v_pk_fma_f32 v[8:9], v[62:63], v[52:53], v[76:77] op_sel:[0,1,0]
	v_pk_fma_f32 v[10:11], v[62:63], v[54:55], v[78:79] op_sel_hi:[1,0,1]
	v_pk_fma_f32 v[12:13], v[62:63], v[54:55], v[80:81] op_sel:[0,1,0]
	v_pk_fma_f32 v[14:15], v[62:63], v[56:57], v[82:83] op_sel_hi:[1,0,1]
	v_pk_fma_f32 v[16:17], v[62:63], v[56:57], v[84:85] op_sel:[0,1,0]
	ds_read_b128 v[50:53], v88 offset:27136
	ds_read_b128 v[54:57], v88 offset:27152
	v_pk_fma_f32 v[86:87], v[58:59], v[60:61], v[66:67] op_sel:[0,1,0]
	v_pk_fma_f32 v[86:87], v[62:63], v[60:61], v[86:87] op_sel_hi:[1,0,1]
	ds_read_b64 v[58:59], v89 offset:43520
	ds_read_b64 v[60:61], v90 offset:51216
	ds_write_b64 v91, v[86:87] offset:768
	s_waitcnt lgkmcnt(7)
	v_pk_mul_f32 v[62:63], v[2:3], v[18:19] op_sel_hi:[1,0]
	v_pk_mul_f32 v[64:65], v[4:5], v[18:19] op_sel:[0,1]
	v_pk_mul_f32 v[66:67], v[2:3], v[26:27] op_sel_hi:[1,0]
	v_pk_mul_f32 v[68:69], v[4:5], v[26:27] op_sel:[0,1]
	v_pk_fma_f32 v[62:63], v[6:7], v[20:21], v[62:63] op_sel_hi:[1,0,1]
	v_pk_fma_f32 v[66:67], v[6:7], v[28:29], v[66:67] op_sel_hi:[1,0,1]
	v_pk_fma_f32 v[64:65], v[8:9], v[20:21], v[64:65] op_sel:[0,1,0]
	v_pk_fma_f32 v[68:69], v[8:9], v[28:29], v[68:69] op_sel:[0,1,0]
	v_pk_fma_f32 v[62:63], v[10:11], v[22:23], v[62:63] op_sel_hi:[1,0,1]
	v_pk_fma_f32 v[66:67], v[10:11], v[30:31], v[66:67] op_sel_hi:[1,0,1]
	v_pk_fma_f32 v[64:65], v[12:13], v[22:23], v[64:65] op_sel:[0,1,0]
	v_pk_fma_f32 v[68:69], v[12:13], v[30:31], v[68:69] op_sel:[0,1,0]
	v_pk_fma_f32 v[62:63], v[14:15], v[24:25], v[62:63] op_sel_hi:[1,0,1]
	v_pk_fma_f32 v[66:67], v[14:15], v[32:33], v[66:67] op_sel_hi:[1,0,1]
	v_pk_fma_f32 v[64:65], v[16:17], v[24:25], v[64:65] op_sel:[0,1,0]
	v_pk_fma_f32 v[68:69], v[16:17], v[32:33], v[68:69] op_sel:[0,1,0]
	ds_read_b128 v[18:21], v88 offset:18688
	ds_read_b128 v[22:25], v88 offset:18704
	ds_read_b128 v[26:29], v88 offset:35072
	ds_read_b128 v[30:33], v88 offset:35088
	v_pk_add_f32 v[62:63], v[62:63], v[64:65]
	v_pk_add_f32 v[66:67], v[66:67], v[68:69]
	v_pk_mul_f32 v[70:71], v[2:3], v[34:35] op_sel_hi:[1,0]
	v_pk_mul_f32 v[72:73], v[4:5], v[34:35] op_sel:[0,1]
	v_pk_mul_f32 v[74:75], v[6:7], v[36:37] op_sel_hi:[1,0]
	v_pk_mul_f32 v[76:77], v[8:9], v[36:37] op_sel:[0,1]
	v_pk_mul_f32 v[78:79], v[10:11], v[38:39] op_sel_hi:[1,0]
	v_pk_mul_f32 v[80:81], v[12:13], v[38:39] op_sel:[0,1]
	v_pk_mul_f32 v[82:83], v[14:15], v[40:41] op_sel_hi:[1,0]
	v_pk_mul_f32 v[84:85], v[16:17], v[40:41] op_sel:[0,1]
	ds_read_b128 v[34:37], v88 offset:2304
	ds_read_b128 v[38:41], v88 offset:2320
	v_add_f32_dpp v62, v62, v62 quad_perm:[1,0,3,2] row_mask:0xf bank_mask:0xf bound_ctrl:1
	v_add_f32_dpp v63, v63, v63 quad_perm:[1,0,3,2] row_mask:0xf bank_mask:0xf bound_ctrl:1
	v_add_f32_dpp v66, v66, v66 quad_perm:[1,0,3,2] row_mask:0xf bank_mask:0xf bound_ctrl:1
	v_add_f32_dpp v67, v67, v67 quad_perm:[1,0,3,2] row_mask:0xf bank_mask:0xf bound_ctrl:1
	s_waitcnt lgkmcnt(7)
	v_pk_fma_f32 v[70:71], v[58:59], v[42:43], v[70:71] op_sel_hi:[1,0,1]
	v_pk_fma_f32 v[72:73], v[58:59], v[42:43], v[72:73] op_sel:[0,1,0]
	v_pk_fma_f32 v[74:75], v[58:59], v[44:45], v[74:75] op_sel_hi:[1,0,1]
	v_pk_fma_f32 v[76:77], v[58:59], v[44:45], v[76:77] op_sel:[0,1,0]
	v_add_f32_dpp v62, v62, v62 quad_perm:[2,3,0,1] row_mask:0xf bank_mask:0xf bound_ctrl:1
	v_add_f32_dpp v63, v63, v63 quad_perm:[2,3,0,1] row_mask:0xf bank_mask:0xf bound_ctrl:1
	v_add_f32_dpp v66, v66, v66 quad_perm:[2,3,0,1] row_mask:0xf bank_mask:0xf bound_ctrl:1
	v_add_f32_dpp v67, v67, v67 quad_perm:[2,3,0,1] row_mask:0xf bank_mask:0xf bound_ctrl:1
	v_pk_fma_f32 v[78:79], v[58:59], v[46:47], v[78:79] op_sel_hi:[1,0,1]
	v_pk_fma_f32 v[80:81], v[58:59], v[46:47], v[80:81] op_sel:[0,1,0]
	v_pk_fma_f32 v[82:83], v[58:59], v[48:49], v[82:83] op_sel_hi:[1,0,1]
	v_pk_fma_f32 v[84:85], v[58:59], v[48:49], v[84:85] op_sel:[0,1,0]
	ds_read_b128 v[42:45], v88 offset:10496
	ds_read_b128 v[46:49], v88 offset:10512
	v_add_f32_dpp v62, v62, v62 row_half_mirror row_mask:0xf bank_mask:0xf bound_ctrl:1
	v_add_f32_dpp v63, v63, v63 row_half_mirror row_mask:0xf bank_mask:0xf bound_ctrl:1
	v_add_f32_dpp v66, v66, v66 row_half_mirror row_mask:0xf bank_mask:0xf bound_ctrl:1
	v_add_f32_dpp v67, v67, v67 row_half_mirror row_mask:0xf bank_mask:0xf bound_ctrl:1
	v_pk_fma_f32 v[2:3], v[62:63], v[50:51], v[70:71] op_sel_hi:[1,0,1]
	v_pk_fma_f32 v[4:5], v[62:63], v[50:51], v[72:73] op_sel:[0,1,0]
	v_pk_fma_f32 v[6:7], v[62:63], v[52:53], v[74:75] op_sel_hi:[1,0,1]
	v_pk_fma_f32 v[8:9], v[62:63], v[52:53], v[76:77] op_sel:[0,1,0]
	v_pk_fma_f32 v[10:11], v[62:63], v[54:55], v[78:79] op_sel_hi:[1,0,1]
	v_pk_fma_f32 v[12:13], v[62:63], v[54:55], v[80:81] op_sel:[0,1,0]
	v_pk_fma_f32 v[14:15], v[62:63], v[56:57], v[82:83] op_sel_hi:[1,0,1]
	v_pk_fma_f32 v[16:17], v[62:63], v[56:57], v[84:85] op_sel:[0,1,0]
	ds_read_b128 v[50:53], v88 offset:26880
	ds_read_b128 v[54:57], v88 offset:26896
	v_pk_fma_f32 v[86:87], v[58:59], v[60:61], v[66:67] op_sel:[0,1,0]
	v_pk_fma_f32 v[86:87], v[62:63], v[60:61], v[86:87] op_sel_hi:[1,0,1]
	ds_read_b64 v[58:59], v89 offset:43264
	ds_read_b64 v[60:61], v90 offset:51208
	ds_write_b64 v91, v[86:87] offset:512
	s_waitcnt lgkmcnt(7)
	v_pk_mul_f32 v[62:63], v[2:3], v[18:19] op_sel_hi:[1,0]
	v_pk_mul_f32 v[64:65], v[4:5], v[18:19] op_sel:[0,1]
	v_pk_mul_f32 v[66:67], v[2:3], v[26:27] op_sel_hi:[1,0]
	v_pk_mul_f32 v[68:69], v[4:5], v[26:27] op_sel:[0,1]
	v_pk_fma_f32 v[62:63], v[6:7], v[20:21], v[62:63] op_sel_hi:[1,0,1]
	v_pk_fma_f32 v[66:67], v[6:7], v[28:29], v[66:67] op_sel_hi:[1,0,1]
	v_pk_fma_f32 v[64:65], v[8:9], v[20:21], v[64:65] op_sel:[0,1,0]
	v_pk_fma_f32 v[68:69], v[8:9], v[28:29], v[68:69] op_sel:[0,1,0]
	v_pk_fma_f32 v[62:63], v[10:11], v[22:23], v[62:63] op_sel_hi:[1,0,1]
	v_pk_fma_f32 v[66:67], v[10:11], v[30:31], v[66:67] op_sel_hi:[1,0,1]
	v_pk_fma_f32 v[64:65], v[12:13], v[22:23], v[64:65] op_sel:[0,1,0]
	v_pk_fma_f32 v[68:69], v[12:13], v[30:31], v[68:69] op_sel:[0,1,0]
	v_pk_fma_f32 v[62:63], v[14:15], v[24:25], v[62:63] op_sel_hi:[1,0,1]
	v_pk_fma_f32 v[66:67], v[14:15], v[32:33], v[66:67] op_sel_hi:[1,0,1]
	v_pk_fma_f32 v[64:65], v[16:17], v[24:25], v[64:65] op_sel:[0,1,0]
	v_pk_fma_f32 v[68:69], v[16:17], v[32:33], v[68:69] op_sel:[0,1,0]
	ds_read_b128 v[18:21], v88 offset:18432
	ds_read_b128 v[22:25], v88 offset:18448
	ds_read_b128 v[26:29], v88 offset:34816
	ds_read_b128 v[30:33], v88 offset:34832
	v_pk_add_f32 v[62:63], v[62:63], v[64:65]
	v_pk_add_f32 v[66:67], v[66:67], v[68:69]
	v_pk_mul_f32 v[70:71], v[2:3], v[34:35] op_sel_hi:[1,0]
	v_pk_mul_f32 v[72:73], v[4:5], v[34:35] op_sel:[0,1]
	v_pk_mul_f32 v[74:75], v[6:7], v[36:37] op_sel_hi:[1,0]
	v_pk_mul_f32 v[76:77], v[8:9], v[36:37] op_sel:[0,1]
	v_pk_mul_f32 v[78:79], v[10:11], v[38:39] op_sel_hi:[1,0]
	v_pk_mul_f32 v[80:81], v[12:13], v[38:39] op_sel:[0,1]
	v_pk_mul_f32 v[82:83], v[14:15], v[40:41] op_sel_hi:[1,0]
	v_pk_mul_f32 v[84:85], v[16:17], v[40:41] op_sel:[0,1]
	ds_read_b128 v[34:37], v88 offset:2048
	ds_read_b128 v[38:41], v88 offset:2064
	v_add_f32_dpp v62, v62, v62 quad_perm:[1,0,3,2] row_mask:0xf bank_mask:0xf bound_ctrl:1
	v_add_f32_dpp v63, v63, v63 quad_perm:[1,0,3,2] row_mask:0xf bank_mask:0xf bound_ctrl:1
	v_add_f32_dpp v66, v66, v66 quad_perm:[1,0,3,2] row_mask:0xf bank_mask:0xf bound_ctrl:1
	v_add_f32_dpp v67, v67, v67 quad_perm:[1,0,3,2] row_mask:0xf bank_mask:0xf bound_ctrl:1
	s_waitcnt lgkmcnt(7)
	v_pk_fma_f32 v[70:71], v[58:59], v[42:43], v[70:71] op_sel_hi:[1,0,1]
	v_pk_fma_f32 v[72:73], v[58:59], v[42:43], v[72:73] op_sel:[0,1,0]
	v_pk_fma_f32 v[74:75], v[58:59], v[44:45], v[74:75] op_sel_hi:[1,0,1]
	v_pk_fma_f32 v[76:77], v[58:59], v[44:45], v[76:77] op_sel:[0,1,0]
	v_add_f32_dpp v62, v62, v62 quad_perm:[2,3,0,1] row_mask:0xf bank_mask:0xf bound_ctrl:1
	v_add_f32_dpp v63, v63, v63 quad_perm:[2,3,0,1] row_mask:0xf bank_mask:0xf bound_ctrl:1
	v_add_f32_dpp v66, v66, v66 quad_perm:[2,3,0,1] row_mask:0xf bank_mask:0xf bound_ctrl:1
	v_add_f32_dpp v67, v67, v67 quad_perm:[2,3,0,1] row_mask:0xf bank_mask:0xf bound_ctrl:1
	v_pk_fma_f32 v[78:79], v[58:59], v[46:47], v[78:79] op_sel_hi:[1,0,1]
	v_pk_fma_f32 v[80:81], v[58:59], v[46:47], v[80:81] op_sel:[0,1,0]
	v_pk_fma_f32 v[82:83], v[58:59], v[48:49], v[82:83] op_sel_hi:[1,0,1]
	v_pk_fma_f32 v[84:85], v[58:59], v[48:49], v[84:85] op_sel:[0,1,0]
	ds_read_b128 v[42:45], v88 offset:10240
	ds_read_b128 v[46:49], v88 offset:10256
	v_add_f32_dpp v62, v62, v62 row_half_mirror row_mask:0xf bank_mask:0xf bound_ctrl:1
	v_add_f32_dpp v63, v63, v63 row_half_mirror row_mask:0xf bank_mask:0xf bound_ctrl:1
	v_add_f32_dpp v66, v66, v66 row_half_mirror row_mask:0xf bank_mask:0xf bound_ctrl:1
	v_add_f32_dpp v67, v67, v67 row_half_mirror row_mask:0xf bank_mask:0xf bound_ctrl:1
	v_pk_fma_f32 v[2:3], v[62:63], v[50:51], v[70:71] op_sel_hi:[1,0,1]
	v_pk_fma_f32 v[4:5], v[62:63], v[50:51], v[72:73] op_sel:[0,1,0]
	v_pk_fma_f32 v[6:7], v[62:63], v[52:53], v[74:75] op_sel_hi:[1,0,1]
	v_pk_fma_f32 v[8:9], v[62:63], v[52:53], v[76:77] op_sel:[0,1,0]
	v_pk_fma_f32 v[10:11], v[62:63], v[54:55], v[78:79] op_sel_hi:[1,0,1]
	v_pk_fma_f32 v[12:13], v[62:63], v[54:55], v[80:81] op_sel:[0,1,0]
	v_pk_fma_f32 v[14:15], v[62:63], v[56:57], v[82:83] op_sel_hi:[1,0,1]
	v_pk_fma_f32 v[16:17], v[62:63], v[56:57], v[84:85] op_sel:[0,1,0]
	ds_read_b128 v[50:53], v88 offset:26624
	ds_read_b128 v[54:57], v88 offset:26640
	v_pk_fma_f32 v[86:87], v[58:59], v[60:61], v[66:67] op_sel:[0,1,0]
	v_pk_fma_f32 v[86:87], v[62:63], v[60:61], v[86:87] op_sel_hi:[1,0,1]
	ds_read_b64 v[58:59], v89 offset:43008
	ds_read_b64 v[60:61], v90 offset:51200
	ds_write_b64 v91, v[86:87] offset:256
	s_waitcnt lgkmcnt(7)
	v_pk_mul_f32 v[62:63], v[2:3], v[18:19] op_sel_hi:[1,0]
	v_pk_mul_f32 v[64:65], v[4:5], v[18:19] op_sel:[0,1]
	v_pk_mul_f32 v[66:67], v[2:3], v[26:27] op_sel_hi:[1,0]
	v_pk_mul_f32 v[68:69], v[4:5], v[26:27] op_sel:[0,1]
	v_pk_fma_f32 v[62:63], v[6:7], v[20:21], v[62:63] op_sel_hi:[1,0,1]
	v_pk_fma_f32 v[66:67], v[6:7], v[28:29], v[66:67] op_sel_hi:[1,0,1]
	v_pk_fma_f32 v[64:65], v[8:9], v[20:21], v[64:65] op_sel:[0,1,0]
	v_pk_fma_f32 v[68:69], v[8:9], v[28:29], v[68:69] op_sel:[0,1,0]
	v_pk_fma_f32 v[62:63], v[10:11], v[22:23], v[62:63] op_sel_hi:[1,0,1]
	v_pk_fma_f32 v[66:67], v[10:11], v[30:31], v[66:67] op_sel_hi:[1,0,1]
	v_pk_fma_f32 v[64:65], v[12:13], v[22:23], v[64:65] op_sel:[0,1,0]
	v_pk_fma_f32 v[68:69], v[12:13], v[30:31], v[68:69] op_sel:[0,1,0]
	v_pk_fma_f32 v[62:63], v[14:15], v[24:25], v[62:63] op_sel_hi:[1,0,1]
	v_pk_fma_f32 v[66:67], v[14:15], v[32:33], v[66:67] op_sel_hi:[1,0,1]
	v_pk_fma_f32 v[64:65], v[16:17], v[24:25], v[64:65] op_sel:[0,1,0]
	v_pk_fma_f32 v[68:69], v[16:17], v[32:33], v[68:69] op_sel:[0,1,0]
	v_add_u32_e32 v88, s48, v88
	ds_read_b128 v[18:21], v88 offset:22272
	ds_read_b128 v[22:25], v88 offset:22288
	ds_read_b128 v[26:29], v88 offset:38656
	ds_read_b128 v[30:33], v88 offset:38672
	v_pk_add_f32 v[62:63], v[62:63], v[64:65]
	v_pk_add_f32 v[66:67], v[66:67], v[68:69]
	v_pk_mul_f32 v[70:71], v[2:3], v[34:35] op_sel_hi:[1,0]
	v_pk_mul_f32 v[72:73], v[4:5], v[34:35] op_sel:[0,1]
	v_pk_mul_f32 v[74:75], v[6:7], v[36:37] op_sel_hi:[1,0]
	v_pk_mul_f32 v[76:77], v[8:9], v[36:37] op_sel:[0,1]
	v_pk_mul_f32 v[78:79], v[10:11], v[38:39] op_sel_hi:[1,0]
	v_pk_mul_f32 v[80:81], v[12:13], v[38:39] op_sel:[0,1]
	v_pk_mul_f32 v[82:83], v[14:15], v[40:41] op_sel_hi:[1,0]
	v_pk_mul_f32 v[84:85], v[16:17], v[40:41] op_sel:[0,1]
	ds_read_b128 v[34:37], v88 offset:5888
	ds_read_b128 v[38:41], v88 offset:5904
	v_add_f32_dpp v62, v62, v62 quad_perm:[1,0,3,2] row_mask:0xf bank_mask:0xf bound_ctrl:1
	v_add_f32_dpp v63, v63, v63 quad_perm:[1,0,3,2] row_mask:0xf bank_mask:0xf bound_ctrl:1
	v_add_f32_dpp v66, v66, v66 quad_perm:[1,0,3,2] row_mask:0xf bank_mask:0xf bound_ctrl:1
	v_add_f32_dpp v67, v67, v67 quad_perm:[1,0,3,2] row_mask:0xf bank_mask:0xf bound_ctrl:1
	s_waitcnt lgkmcnt(7)
	v_pk_fma_f32 v[70:71], v[58:59], v[42:43], v[70:71] op_sel_hi:[1,0,1]
	v_pk_fma_f32 v[72:73], v[58:59], v[42:43], v[72:73] op_sel:[0,1,0]
	v_pk_fma_f32 v[74:75], v[58:59], v[44:45], v[74:75] op_sel_hi:[1,0,1]
	v_pk_fma_f32 v[76:77], v[58:59], v[44:45], v[76:77] op_sel:[0,1,0]
	v_add_f32_dpp v62, v62, v62 quad_perm:[2,3,0,1] row_mask:0xf bank_mask:0xf bound_ctrl:1
	v_add_f32_dpp v63, v63, v63 quad_perm:[2,3,0,1] row_mask:0xf bank_mask:0xf bound_ctrl:1
	v_add_f32_dpp v66, v66, v66 quad_perm:[2,3,0,1] row_mask:0xf bank_mask:0xf bound_ctrl:1
	v_add_f32_dpp v67, v67, v67 quad_perm:[2,3,0,1] row_mask:0xf bank_mask:0xf bound_ctrl:1
	v_pk_fma_f32 v[78:79], v[58:59], v[46:47], v[78:79] op_sel_hi:[1,0,1]
	v_pk_fma_f32 v[80:81], v[58:59], v[46:47], v[80:81] op_sel:[0,1,0]
	v_pk_fma_f32 v[82:83], v[58:59], v[48:49], v[82:83] op_sel_hi:[1,0,1]
	v_pk_fma_f32 v[84:85], v[58:59], v[48:49], v[84:85] op_sel:[0,1,0]
	ds_read_b128 v[42:45], v88 offset:14080
	ds_read_b128 v[46:49], v88 offset:14096
	v_add_f32_dpp v62, v62, v62 row_half_mirror row_mask:0xf bank_mask:0xf bound_ctrl:1
	v_add_f32_dpp v63, v63, v63 row_half_mirror row_mask:0xf bank_mask:0xf bound_ctrl:1
	v_add_f32_dpp v66, v66, v66 row_half_mirror row_mask:0xf bank_mask:0xf bound_ctrl:1
	v_add_f32_dpp v67, v67, v67 row_half_mirror row_mask:0xf bank_mask:0xf bound_ctrl:1
	v_add_u32_e32 v89, s48, v89
	v_pk_fma_f32 v[2:3], v[62:63], v[50:51], v[70:71] op_sel_hi:[1,0,1]
	v_pk_fma_f32 v[4:5], v[62:63], v[50:51], v[72:73] op_sel:[0,1,0]
	v_pk_fma_f32 v[6:7], v[62:63], v[52:53], v[74:75] op_sel_hi:[1,0,1]
	v_pk_fma_f32 v[8:9], v[62:63], v[52:53], v[76:77] op_sel:[0,1,0]
	v_pk_fma_f32 v[10:11], v[62:63], v[54:55], v[78:79] op_sel_hi:[1,0,1]
	v_pk_fma_f32 v[12:13], v[62:63], v[54:55], v[80:81] op_sel:[0,1,0]
	v_pk_fma_f32 v[14:15], v[62:63], v[56:57], v[82:83] op_sel_hi:[1,0,1]
	v_pk_fma_f32 v[16:17], v[62:63], v[56:57], v[84:85] op_sel:[0,1,0]
	ds_read_b128 v[50:53], v88 offset:30464
	ds_read_b128 v[54:57], v88 offset:30480
	v_pk_fma_f32 v[86:87], v[58:59], v[60:61], v[66:67] op_sel:[0,1,0]
	v_pk_fma_f32 v[86:87], v[62:63], v[60:61], v[86:87] op_sel_hi:[1,0,1]
	v_add_u32_e32 v90, s49, v90
	ds_read_b64 v[58:59], v89 offset:46848
	ds_read_b64 v[60:61], v90 offset:51320
	ds_write_b64 v91, v[86:87] offset:0
	v_add_u32_e32 v91, s48, v91
	s_sub_u32 s100, s100, 1
	s_cmp_lg_u32 s100, 0
	s_cbranch_scc1 .Lrec_bwd_loop
	s_branch .Lrec0_ret

.LBB0_480:
	s_andn2_saveexec_b64 s[2:3], s[2:3]
	s_cbranch_execz .LBB0_251
	v_lshl_add_u64 v[6:7], v[62:63], 0, v[72:73]
	v_lshl_add_u64 v[6:7], v[6:7], 0, v[0:1]
	s_and_b64 s[10:11], s[44:45], s[38:39]
	global_store_dwordx4 v[6:7], v[2:5], off
	s_and_saveexec_b64 s[8:9], s[10:11]
	s_cbranch_execz .LBB0_250
	v_lshl_add_u64 v[6:7], v[70:71], 1, s[58:59]
	v_lshl_add_u64 v[6:7], v[6:7], 0, v[0:1]
	global_store_dwordx4 v[6:7], v[2:5], off
	s_branch .LBB0_250
.Ltr_1153:
	s_branch .LBB0_1153

.Ltr_7:
	s_branch .LBB0_7
.LBB0_483:
	v_readlane_b32 s18, v255, 52
	v_readlane_b32 s19, v255, 53

.LBB0_554:
	s_or_b64 exec, exec, s[42:43]
	s_and_b64 vcc, exec, s[38:39]
	v_ashrrev_i32_e32 v153, 31, v152
	s_cbranch_vccnz .LBB0_579
	s_movk_i32 s8, 0x7fff
	v_add_u32_e32 v0, 0xffff8000, v152
	v_cmp_gt_i32_e32 vcc, s84, v152
	v_cmp_lt_i32_e64 s[42:43], s8, v152
	v_lshlrev_b64 v[140:141], 11, v[0:1]
	s_and_saveexec_b64 s[8:9], s[42:43]
	s_xor_b64 s[46:47], exec, s[8:9]
	s_cbranch_execz .Lrp_lat
	s_mov_b64 s[52:53], 0x400000
	v_lshl_add_u64 v[218:219], v[174:175], 0, v[140:141]
	v_lshl_add_u64 v[220:221], v[176:177], 0, v[140:141]
	v_lshl_add_u64 v[222:223], v[178:179], 0, v[140:141]
	v_lshl_add_u64 v[224:225], v[180:181], 0, v[140:141]
	global_load_dwordx2 v[226:227], v[218:219], off offset:-4
	global_load_dwordx2 v[228:229], v[220:221], off offset:-4
	global_load_dwordx2 v[230:231], v[222:223], off offset:-4
	global_load_dwordx2 v[232:233], v[224:225], off offset:-4
	v_lshl_add_u64 v[218:219], v[218:219], 0, s[52:53]
	v_lshl_add_u64 v[220:221], v[220:221], 0, s[52:53]
	v_lshl_add_u64 v[222:223], v[222:223], 0, s[52:53]
	v_lshl_add_u64 v[224:225], v[224:225], 0, s[52:53]
	global_load_dwordx2 v[234:235], v[218:219], off offset:-4
	global_load_dwordx2 v[236:237], v[220:221], off offset:-4
	global_load_dwordx2 v[238:239], v[222:223], off offset:-4
	global_load_dwordx2 v[240:241], v[224:225], off offset:-4
	s_cmp_lg_u32 s63, 3
	s_cbranch_scc1 .Lrp_two
	v_lshl_add_u64 v[218:219], v[218:219], 0, s[52:53]
	v_lshl_add_u64 v[220:221], v[220:221], 0, s[52:53]
	v_lshl_add_u64 v[222:223], v[222:223], 0, s[52:53]
	v_lshl_add_u64 v[224:225], v[224:225], 0, s[52:53]
	global_load_dwordx2 v[242:243], v[218:219], off offset:-4
	global_load_dwordx2 v[244:245], v[220:221], off offset:-4
	global_load_dwordx2 v[246:247], v[222:223], off offset:-4
	global_load_dwordx2 v[248:249], v[224:225], off offset:-4
	s_branch .Lrp_sum
.Lrp_two:
	v_mov_b32_e32 v242, 0
	v_mov_b32_e32 v243, 0
	v_mov_b32_e32 v244, 0
	v_mov_b32_e32 v245, 0
	v_mov_b32_e32 v246, 0
	v_mov_b32_e32 v247, 0
	v_mov_b32_e32 v248, 0
	v_mov_b32_e32 v249, 0
.Lrp_sum:
	s_waitcnt vmcnt(0)
	v_lshlrev_b32_e32 v132, 16, v226
	v_and_b32_e32 v133, 0xffff0000, v226
	v_lshlrev_b32_e32 v134, 16, v227
	v_and_b32_e32 v135, 0xffff0000, v227
	v_lshlrev_b32_e32 v142, 16, v234
	v_and_b32_e32 v143, 0xffff0000, v234
	v_lshlrev_b32_e32 v194, 16, v235
	v_and_b32_e32 v195, 0xffff0000, v235
	v_pk_add_f32 v[134:135], v[134:135], v[194:195]
	v_pk_add_f32 v[132:133], v[132:133], v[142:143]
	v_lshlrev_b32_e32 v142, 16, v242
	v_and_b32_e32 v143, 0xffff0000, v242
	v_lshlrev_b32_e32 v194, 16, v243
	v_and_b32_e32 v195, 0xffff0000, v243
	v_pk_add_f32 v[134:135], v[134:135], v[194:195]
	v_pk_add_f32 v[132:133], v[132:133], v[142:143]
	v_lshlrev_b32_e32 v136, 16, v228
	v_and_b32_e32 v137, 0xffff0000, v228
	v_lshlrev_b32_e32 v138, 16, v229
	v_and_b32_e32 v139, 0xffff0000, v229
	v_lshlrev_b32_e32 v142, 16, v236
	v_and_b32_e32 v143, 0xffff0000, v236
	v_lshlrev_b32_e32 v194, 16, v237
	v_and_b32_e32 v195, 0xffff0000, v237
	v_pk_add_f32 v[138:139], v[138:139], v[194:195]
	v_pk_add_f32 v[136:137], v[136:137], v[142:143]
	v_lshlrev_b32_e32 v142, 16, v244
	v_and_b32_e32 v143, 0xffff0000, v244
	v_lshlrev_b32_e32 v194, 16, v245
	v_and_b32_e32 v195, 0xffff0000, v245
	v_pk_add_f32 v[138:139], v[138:139], v[194:195]
	v_pk_add_f32 v[136:137], v[136:137], v[142:143]
	v_lshlrev_b32_e32 v144, 16, v230
	v_and_b32_e32 v145, 0xffff0000, v230
	v_lshlrev_b32_e32 v146, 16, v231
	v_and_b32_e32 v147, 0xffff0000, v231
	v_lshlrev_b32_e32 v142, 16, v238
	v_and_b32_e32 v143, 0xffff0000, v238
	v_lshlrev_b32_e32 v194, 16, v239
	v_and_b32_e32 v195, 0xffff0000, v239
	v_pk_add_f32 v[146:147], v[146:147], v[194:195]
	v_pk_add_f32 v[144:145], v[144:145], v[142:143]
	v_lshlrev_b32_e32 v142, 16, v246
	v_and_b32_e32 v143, 0xffff0000, v246
	v_lshlrev_b32_e32 v194, 16, v247
	v_and_b32_e32 v195, 0xffff0000, v247
	v_pk_add_f32 v[146:147], v[146:147], v[194:195]
	v_pk_add_f32 v[144:145], v[144:145], v[142:143]
	v_lshlrev_b32_e32 v148, 16, v232
	v_and_b32_e32 v149, 0xffff0000, v232
	v_lshlrev_b32_e32 v150, 16, v233
	v_and_b32_e32 v151, 0xffff0000, v233
	v_lshlrev_b32_e32 v142, 16, v240
	v_and_b32_e32 v143, 0xffff0000, v240
	v_lshlrev_b32_e32 v194, 16, v241
	v_and_b32_e32 v195, 0xffff0000, v241
	v_pk_add_f32 v[150:151], v[150:151], v[194:195]
	v_pk_add_f32 v[148:149], v[148:149], v[142:143]
	v_lshlrev_b32_e32 v142, 16, v248
	v_and_b32_e32 v143, 0xffff0000, v248
	v_lshlrev_b32_e32 v194, 16, v249
	v_and_b32_e32 v195, 0xffff0000, v249
	v_pk_add_f32 v[150:151], v[150:151], v[194:195]
	v_pk_add_f32 v[148:149], v[148:149], v[142:143]
.Lrp_lat:
	s_andn2_saveexec_b64 s[8:9], s[46:47]
	v_lshlrev_b32_e32 v132, 16, v160
	v_and_b32_e32 v133, 0xffff0000, v160
	v_lshlrev_b32_e32 v134, 16, v161
	v_and_b32_e32 v135, 0xffff0000, v161
	v_lshlrev_b32_e32 v136, 16, v158
	v_and_b32_e32 v137, 0xffff0000, v158
	v_lshlrev_b32_e32 v138, 16, v159
	v_and_b32_e32 v139, 0xffff0000, v159
	v_lshlrev_b32_e32 v144, 16, v156
	v_and_b32_e32 v145, 0xffff0000, v156
	v_lshlrev_b32_e32 v146, 16, v157
	v_and_b32_e32 v147, 0xffff0000, v157
	v_lshlrev_b32_e32 v148, 16, v154
	v_and_b32_e32 v149, 0xffff0000, v154
	v_lshlrev_b32_e32 v150, 16, v155
	v_and_b32_e32 v151, 0xffff0000, v155
	s_or_b64 exec, exec, s[8:9]
	v_mul_f32_e32 v3, v133, v133
	v_mul_f32_e32 v140, v137, v137
	v_fmac_f32_e32 v3, v132, v132
	v_fmac_f32_e32 v140, v136, v136
	v_fmac_f32_e32 v3, v134, v134
	v_fmac_f32_e32 v140, v138, v138
	v_fmac_f32_e32 v3, v135, v135
	v_fmac_f32_e32 v140, v139, v139
	v_add_f32_e32 v3, v3, v140
	v_mul_f32_e32 v140, v145, v145
	v_fmac_f32_e32 v140, v144, v144
	v_fmac_f32_e32 v140, v146, v146
	v_fmac_f32_e32 v140, v147, v147
	v_add_f32_e32 v3, v3, v140
	v_cndmask_b32_e32 v140, v0, v152, vcc
	v_mov_b32_e32 v0, s55
	v_mov_b32_e32 v142, s3
	v_cndmask_b32_e32 v141, 0, v153, vcc
	v_cndmask_b32_e32 v143, v0, v142, vcc
	v_mov_b32_e32 v0, s54
	v_mov_b32_e32 v142, s2
	v_cndmask_b32_e32 v142, v0, v142, vcc
	v_lshlrev_b64 v[140:141], 12, v[140:141]
	v_pk_mul_f32 v[194:195], v[148:149], v[148:149]
	v_lshl_add_u64 v[140:141], v[142:143], 0, v[140:141]
	v_pk_mul_f32 v[142:143], v[150:151], v[150:151]
	v_add_f32_e32 v0, v194, v195
	v_add_f32_e32 v0, v142, v0
	v_add_f32_e32 v0, v143, v0
	v_add_f32_e32 v0, v3, v0
	v_mov_b32_e32 v3, v1
	v_lshl_add_u64 v[194:195], v[140:141], 0, v[2:3]
	v_add_f32_dpp v0, v0, v0 quad_perm:[1,0,3,2] row_mask:0xf bank_mask:0xf bound_ctrl:1
	s_waitcnt vmcnt(0)
	v_pk_mul_f32 v[140:141], s[10:11], v[82:83]
	v_pk_mul_f32 v[196:197], s[18:19], v[80:81]
	v_add_f32_dpp v0, v0, v0 quad_perm:[2,3,0,1] row_mask:0xf bank_mask:0xf bound_ctrl:1
	s_nop 1
	v_add_f32_dpp v0, v0, v0 row_half_mirror row_mask:0xf bank_mask:0xf bound_ctrl:1
	s_nop 1
	v_add_f32_dpp v0, v0, v0 row_mirror row_mask:0xf bank_mask:0xf bound_ctrl:1
	s_nop 0
	v_readlane_b32 s42, v0, 16
	v_readlane_b32 s43, v0, 48
	v_readlane_b32 s8, v0, 0
	v_readlane_b32 s9, v0, 32
	v_mov_b32_e32 v142, s42
	v_mov_b32_e32 v143, s43
	v_pk_add_f32 v[142:143], s[8:9], v[142:143]
	s_nop 0
	v_add_f32_e32 v0, v142, v143
	v_fmamk_f32 v0, v0, 0x3a800000, v213
	v_rsq_f32_e32 v0, v0
	s_nop 0
	v_pk_mul_f32 v[134:135], v[134:135], v[0:1] op_sel_hi:[1,0]
	v_pk_mul_f32 v[132:133], v[132:133], v[0:1] op_sel_hi:[1,0]
	v_pk_mul_f32 v[134:135], v[6:7], v[134:135]
	v_pk_mul_f32 v[136:137], v[136:137], v[0:1] op_sel_hi:[1,0]
	v_pk_mul_f32 v[132:133], v[4:5], v[132:133]
	v_pk_fma_f32 v[142:143], v[140:141], v[134:135], v[50:51]
	v_pk_mul_f32 v[134:135], s[18:19], v[76:77]
	v_pk_mul_f32 v[138:139], v[138:139], v[0:1] op_sel_hi:[1,0]
	v_pk_mul_f32 v[136:137], v[12:13], v[136:137]
	v_pk_fma_f32 v[140:141], v[196:197], v[132:133], v[48:49]
	v_pk_mul_f32 v[132:133], s[10:11], v[78:79]
	v_pk_mul_f32 v[138:139], v[14:15], v[138:139]
	v_pk_fma_f32 v[136:137], v[134:135], v[136:137], v[44:45]
	v_pk_mul_f32 v[134:135], v[146:147], v[0:1] op_sel_hi:[1,0]
	v_pk_mul_f32 v[144:145], v[144:145], v[0:1] op_sel_hi:[1,0]
	v_pk_mul_f32 v[148:149], v[148:149], v[0:1] op_sel_hi:[1,0]
	v_pk_fma_f32 v[138:139], v[132:133], v[138:139], v[46:47]
	v_pk_mul_f32 v[132:133], s[10:11], v[74:75]
	v_pk_mul_f32 v[196:197], s[18:19], v[72:73]
	v_pk_mul_f32 v[144:145], v[20:21], v[144:145]
	v_pk_mul_f32 v[134:135], v[22:23], v[134:135]
	v_pk_mul_f32 v[146:147], s[18:19], v[68:69]
	v_pk_mul_f32 v[150:151], v[150:151], v[0:1] op_sel_hi:[1,0]
	v_pk_mul_f32 v[148:149], v[28:29], v[148:149]
	v_pk_fma_f32 v[134:135], v[132:133], v[134:135], v[42:43]
	v_pk_fma_f32 v[132:133], v[196:197], v[144:145], v[40:41]
	v_pk_mul_f32 v[144:145], s[10:11], v[70:71]
	v_pk_mul_f32 v[150:151], v[30:31], v[150:151]
	v_pk_fma_f32 v[148:149], v[146:147], v[148:149], v[36:37]
	v_pk_fma_f32 v[150:151], v[144:145], v[150:151], v[38:39]
	global_store_dwordx4 v[194:195], v[140:143], off nt
	v_mov_b64_e32 v[144:145], v[148:149]
	v_mov_b64_e32 v[146:147], v[150:151]
	global_store_dwordx4 v[194:195], v[136:139], off offset:1024 nt
	global_store_dwordx4 v[194:195], v[132:135], off offset:2048 nt
	global_store_dwordx4 v[194:195], v[148:151], off offset:3072 nt
	s_and_b64 vcc, exec, s[40:41]
	s_cbranch_vccnz .LBB0_577

.LBB0_588:
	s_ashr_i32 s18, s24, 31
	s_lshr_b32 s18, s18, 28
	s_add_i32 s18, s24, s18
	s_ashr_i32 s19, s18, 4
	s_lshl_b32 s18, s19, 6
	s_lshl_b32 s19, s19, 10
	s_sub_i32 s19, s9, s19
	v_add_u32_e32 v2, s19, v4
	v_add_u32_e32 v12, s18, v5
	v_and_b32_e32 v3, 24, v10
	v_and_b32_e32 v2, 0xffffffe3, v2
	v_or3_b32 v2, v2, v6, v3
	v_ashrrev_i32_e32 v13, 31, v12
	v_ashrrev_i32_e32 v3, 31, v2
	v_lshlrev_b64 v[14:15], 12, v[12:13]
	v_or_b32_e32 v16, 1, v12
	v_or_b32_e32 v18, 2, v12
	v_or_b32_e32 v20, 3, v12
	v_or_b32_e32 v22, 4, v12
	v_or_b32_e32 v24, 5, v12
	v_or_b32_e32 v26, 6, v12
	v_or_b32_e32 v12, 7, v12
	v_lshl_add_u64 v[2:3], v[2:3], 2, s[10:11]
	v_ashrrev_i32_e32 v17, 31, v16
	v_ashrrev_i32_e32 v19, 31, v18
	v_ashrrev_i32_e32 v21, 31, v20
	v_ashrrev_i32_e32 v23, 31, v22
	v_ashrrev_i32_e32 v25, 31, v24
	v_ashrrev_i32_e32 v27, 31, v26
	v_ashrrev_i32_e32 v13, 31, v12
	v_lshl_add_u64 v[14:15], v[2:3], 0, v[14:15]
	v_lshlrev_b64 v[16:17], 12, v[16:17]
	v_lshlrev_b64 v[18:19], 12, v[18:19]
	v_lshlrev_b64 v[20:21], 12, v[20:21]
	v_lshlrev_b64 v[22:23], 12, v[22:23]
	v_lshlrev_b64 v[24:25], 12, v[24:25]
	v_lshlrev_b64 v[26:27], 12, v[26:27]
	v_lshlrev_b64 v[12:13], 12, v[12:13]
	v_lshl_add_u64 v[16:17], v[2:3], 0, v[16:17]
	v_lshl_add_u64 v[18:19], v[2:3], 0, v[18:19]
	v_lshl_add_u64 v[20:21], v[2:3], 0, v[20:21]
	v_lshl_add_u64 v[22:23], v[2:3], 0, v[22:23]
	v_lshl_add_u64 v[24:25], v[2:3], 0, v[24:25]
	v_lshl_add_u64 v[26:27], v[2:3], 0, v[26:27]
	v_lshl_add_u64 v[2:3], v[2:3], 0, v[12:13]
	global_load_dword v28, v[14:15], off
	global_load_dword v29, v[16:17], off
	global_load_dword v30, v[18:19], off
	global_load_dword v31, v[20:21], off
	global_load_dword v32, v[22:23], off
	global_load_dword v33, v[24:25], off
	global_load_dword v34, v[26:27], off
	global_load_dword v35, v[2:3], off
	s_add_i32 s24, s24, s1
	s_add_i32 s9, s9, s25
	v_add_u32_e32 v10, s8, v10
	s_waitcnt vmcnt(0)
	v_cvt_pk_bf16_f32 v12, v28, v29
	v_cvt_pk_bf16_f32 v13, v30, v31
	v_cvt_pk_bf16_f32 v14, v32, v33
	v_cvt_pk_bf16_f32 v15, v34, v35
	ds_write_b128 v7, v[12:15]
	s_waitcnt lgkmcnt(0)
	s_barrier
	ds_read_b128 v[12:15], v9
	v_add_u32_e32 v11, s19, v8
	v_mov_b64_e32 v[2:3], s[16:17]
	v_mad_i64_i32 v[2:3], s[26:27], v11, s21, v[2:3]
	s_ashr_i32 s19, s18, 31
	v_lshl_add_u64 v[2:3], s[18:19], 1, v[2:3]
	v_lshl_add_u64 v[2:3], v[2:3], 0, v[0:1]
	s_cmpk_lt_i32 s24, 0x2c0
	s_waitcnt lgkmcnt(0)
	global_store_dwordx4 v[2:3], v[12:15], off
	s_barrier
	s_cbranch_scc1 .LBB0_588

.LBB0_596:
	s_ashr_i32 s16, s15, 31
	s_lshr_b32 s16, s16, 28
	s_add_i32 s16, s15, s16
	s_ashr_i32 s17, s16, 4
	s_lshl_b32 s16, s17, 6
	s_lshl_b32 s17, s17, 10
	s_sub_i32 s17, s9, s17
	v_add_u32_e32 v2, s17, v4
	v_add_u32_e32 v12, s16, v5
	v_and_b32_e32 v3, 24, v10
	v_and_b32_e32 v2, 0xffffffe3, v2
	v_or3_b32 v2, v2, v6, v3
	v_ashrrev_i32_e32 v13, 31, v12
	v_ashrrev_i32_e32 v3, 31, v2
	v_lshlrev_b64 v[14:15], 12, v[12:13]
	v_or_b32_e32 v16, 1, v12
	v_or_b32_e32 v18, 2, v12
	v_or_b32_e32 v20, 3, v12
	v_or_b32_e32 v22, 4, v12
	v_or_b32_e32 v24, 5, v12
	v_or_b32_e32 v26, 6, v12
	v_or_b32_e32 v12, 7, v12
	v_lshl_add_u64 v[2:3], v[2:3], 2, s[2:3]
	v_ashrrev_i32_e32 v17, 31, v16
	v_ashrrev_i32_e32 v19, 31, v18
	v_ashrrev_i32_e32 v21, 31, v20
	v_ashrrev_i32_e32 v23, 31, v22
	v_ashrrev_i32_e32 v25, 31, v24
	v_ashrrev_i32_e32 v27, 31, v26
	v_ashrrev_i32_e32 v13, 31, v12
	v_lshl_add_u64 v[14:15], v[2:3], 0, v[14:15]
	v_lshlrev_b64 v[16:17], 12, v[16:17]
	v_lshlrev_b64 v[18:19], 12, v[18:19]
	v_lshlrev_b64 v[20:21], 12, v[20:21]
	v_lshlrev_b64 v[22:23], 12, v[22:23]
	v_lshlrev_b64 v[24:25], 12, v[24:25]
	v_lshlrev_b64 v[26:27], 12, v[26:27]
	v_lshlrev_b64 v[12:13], 12, v[12:13]
	v_lshl_add_u64 v[16:17], v[2:3], 0, v[16:17]
	v_lshl_add_u64 v[18:19], v[2:3], 0, v[18:19]
	v_lshl_add_u64 v[20:21], v[2:3], 0, v[20:21]
	v_lshl_add_u64 v[22:23], v[2:3], 0, v[22:23]
	v_lshl_add_u64 v[24:25], v[2:3], 0, v[24:25]
	v_lshl_add_u64 v[26:27], v[2:3], 0, v[26:27]
	v_lshl_add_u64 v[2:3], v[2:3], 0, v[12:13]
	global_load_dword v28, v[14:15], off
	global_load_dword v29, v[16:17], off
	global_load_dword v30, v[18:19], off
	global_load_dword v31, v[20:21], off
	global_load_dword v32, v[22:23], off
	global_load_dword v33, v[24:25], off
	global_load_dword v34, v[26:27], off
	global_load_dword v35, v[2:3], off
	s_add_i32 s15, s15, s1
	s_add_i32 s9, s9, s24
	v_add_u32_e32 v10, s8, v10
	s_waitcnt vmcnt(0)
	v_cvt_pk_bf16_f32 v12, v28, v29
	v_cvt_pk_bf16_f32 v13, v30, v31
	v_cvt_pk_bf16_f32 v14, v32, v33
	v_cvt_pk_bf16_f32 v15, v34, v35
	ds_write_b128 v7, v[12:15]
	s_waitcnt lgkmcnt(0)
	s_barrier
	ds_read_b128 v[12:15], v9
	v_add_u32_e32 v11, s17, v8
	v_mov_b64_e32 v[2:3], s[10:11]
	v_mad_i64_i32 v[2:3], s[18:19], v11, s21, v[2:3]
	s_ashr_i32 s17, s16, 31
	v_lshl_add_u64 v[2:3], s[16:17], 1, v[2:3]
	v_lshl_add_u64 v[2:3], v[2:3], 0, v[0:1]
	s_cmpk_lt_i32 s15, 0x2c0
	s_waitcnt lgkmcnt(0)
	global_store_dwordx4 v[2:3], v[12:15], off
	s_barrier
	s_cbranch_scc1 .LBB0_596
